# v55 + one correctly-rounded sqrt/reciprocal sequence per 4-row group in rw_post
# speedup vs baseline: 1.0118x; 1.0000x over previous
; #define POST_LD(Y_, V_, G_, R_, C_, t) do { _Pragma("unroll") for (int q = 0; q < 8; ++q) { const size_t o_ = (size_t)((t) + q) * DH; Y_[q] = yp[o_]; V_[q] = vp[o_]; G_[q] = gp[o_]; R_[q] = rp[((t) + q) * 32]; C_[q] = cp[o_]; } } while (0)
; __device__ __forceinline__ void rw_post(Frame& F) {
;     ...
;         const float* yp = Y + (size_t)rb0 * DH + col; const float* vp = VS + (size_t)rb0 * DH + col; const bf16* gp = G + (size_t)rb0 * DH + col; const float* rp = RK + (size_t)rb0 * 32 + h;
;         const float* cp = k > 0 ? C + (size_t)(rb0 - SEGLEN) * DH + col : yp;
;         float y[8], vv[8], rk[8], cc[8]; bf16 gg[8];
;     ...
;         POST_LD(y, vv, gg, rk, cc, 0);
;     ...
;             for (int q = 0; q < 8; ++q) { const int row = rb0 + t0 + q;
;                 const float mean = wsum(y[q]) * (1.f / 64.f); const float dv = y[q] - mean; const float var = wsum(dv * dv) * (1.f / 64.f);
.Lpo_s1done:
	s_barrier
	global_load_dwordx4 v[120:123], v11, s[6:7]
	global_load_dwordx4 v[124:127], v11, s[6:7] offset:1024
	global_load_dwordx4 v[128:131], v11, s[8:9]
	global_load_dwordx4 v[132:135], v11, s[8:9] offset:1024
	global_load_dwordx4 v[136:139], v11, s[10:11]
	global_load_dword v159, v158, s[12:13]
	s_add_u32 s6, s6, 0x10000
	s_addc_u32 s7, s7, 0
	s_add_u32 s8, s8, 0x10000
	s_addc_u32 s9, s9, 0
	s_add_u32 s10, s10, 0x8000
	s_addc_u32 s11, s11, 0
	s_add_u32 s12, s12, 0x400
	s_addc_u32 s13, s13, 0
	s_waitcnt vmcnt(0)
	s_waitcnt vmcnt(8)
	ds_write_b128 v12, v[120:123] offset:0
	ds_write_b128 v12, v[124:127] offset:1024
	ds_write_b128 v12, v[128:131] offset:16384
	ds_write_b128 v12, v[132:135] offset:17408
	ds_write_b128 v14, v[136:139]
	v_readlane_b32 s69, v159, 0
	v_readlane_b32 s70, v159, 1
	v_readlane_b32 s71, v159, 2
	v_readlane_b32 s72, v159, 3
	v_readlane_b32 s73, v159, 4
	v_readlane_b32 s26, v159, 5
	v_readlane_b32 s27, v159, 6
	v_readlane_b32 s32, v159, 7
	global_load_dwordx4 v[120:123], v11, s[6:7]
	global_load_dwordx4 v[124:127], v11, s[6:7] offset:1024
	global_load_dwordx4 v[128:131], v11, s[8:9]
	global_load_dwordx4 v[132:135], v11, s[8:9] offset:1024
	global_load_dwordx4 v[136:139], v11, s[10:11]
	global_load_dword v159, v158, s[12:13]
	s_add_u32 s6, s6, 0x10000
	s_addc_u32 s7, s7, 0
	s_add_u32 s8, s8, 0x10000
	s_addc_u32 s9, s9, 0
	s_add_u32 s10, s10, 0x8000
	s_addc_u32 s11, s11, 0
	s_add_u32 s12, s12, 0x400
	s_addc_u32 s13, s13, 0
	s_waitcnt lgkmcnt(0)
	s_barrier
	ds_read_b32 v80, v154 offset:0
	ds_read_b32 v81, v154 offset:16384
	ds_read_u16 v83, v156 offset:0
	ds_read_b32 v85, v154 offset:2048
	ds_read_b32 v86, v154 offset:18432
	ds_read_u16 v88, v156 offset:1024
	ds_read_b32 v90, v154 offset:4096
	ds_read_b32 v91, v154 offset:20480
	ds_read_u16 v93, v156 offset:2048
	ds_read_b32 v95, v154 offset:6144
	ds_read_b32 v96, v154 offset:22528
	ds_read_u16 v98, v156 offset:3072
	ds_read_b32 v100, v154 offset:8192
	ds_read_b32 v101, v154 offset:24576
	ds_read_u16 v103, v156 offset:4096
	ds_read_b32 v105, v154 offset:10240
	ds_read_b32 v106, v154 offset:26624
	ds_read_u16 v108, v156 offset:5120
	ds_read_b32 v110, v154 offset:12288
	ds_read_b32 v111, v154 offset:28672
	ds_read_u16 v113, v156 offset:6144
	ds_read_b32 v115, v154 offset:14336
	ds_read_b32 v116, v154 offset:30720
	ds_read_u16 v118, v156 offset:7168
	s_waitcnt lgkmcnt(0)
	v_add_f32_e32 v80, v80, v16
	v_add_f32_e32 v85, v85, v17
	v_add_f32_e32 v90, v90, v18
	v_add_f32_e32 v95, v95, v19
	v_add_f32_dpp v168, v80, v80 quad_perm:[1,0,3,2] row_mask:0xf bank_mask:0xf bound_ctrl:1
	v_add_f32_dpp v174, v85, v85 quad_perm:[1,0,3,2] row_mask:0xf bank_mask:0xf bound_ctrl:1
	v_add_f32_dpp v241, v90, v90 quad_perm:[1,0,3,2] row_mask:0xf bank_mask:0xf bound_ctrl:1
	v_add_f32_dpp v247, v95, v95 quad_perm:[1,0,3,2] row_mask:0xf bank_mask:0xf bound_ctrl:1
	v_add_f32_dpp v168, v168, v168 quad_perm:[2,3,0,1] row_mask:0xf bank_mask:0xf bound_ctrl:1
	v_add_f32_dpp v174, v174, v174 quad_perm:[2,3,0,1] row_mask:0xf bank_mask:0xf bound_ctrl:1
	v_add_f32_dpp v241, v241, v241 quad_perm:[2,3,0,1] row_mask:0xf bank_mask:0xf bound_ctrl:1
	v_add_f32_dpp v247, v247, v247 quad_perm:[2,3,0,1] row_mask:0xf bank_mask:0xf bound_ctrl:1
	v_add_f32_dpp v168, v168, v168 row_half_mirror row_mask:0xf bank_mask:0xf bound_ctrl:1
	v_add_f32_dpp v174, v174, v174 row_half_mirror row_mask:0xf bank_mask:0xf bound_ctrl:1
	v_add_f32_dpp v241, v241, v241 row_half_mirror row_mask:0xf bank_mask:0xf bound_ctrl:1
	v_add_f32_dpp v247, v247, v247 row_half_mirror row_mask:0xf bank_mask:0xf bound_ctrl:1
	v_add_f32_dpp v168, v168, v168 row_mirror row_mask:0xf bank_mask:0xf bound_ctrl:1
	v_add_f32_dpp v174, v174, v174 row_mirror row_mask:0xf bank_mask:0xf bound_ctrl:1
	v_add_f32_dpp v241, v241, v241 row_mirror row_mask:0xf bank_mask:0xf bound_ctrl:1
	v_add_f32_dpp v247, v247, v247 row_mirror row_mask:0xf bank_mask:0xf bound_ctrl:1
	v_readlane_b32 s36, v168, 16
	v_readlane_b32 s40, v174, 16
	v_readlane_b32 s44, v241, 16
	v_readlane_b32 s48, v247, 16
	v_readlane_b32 s37, v168, 48
	v_readlane_b32 s41, v174, 48
	v_readlane_b32 s45, v241, 48
	v_readlane_b32 s49, v247, 48
	v_readlane_b32 s38, v168, 0
	v_readlane_b32 s42, v174, 0
	v_readlane_b32 s46, v241, 0
	v_readlane_b32 s50, v247, 0
	v_readlane_b32 s39, v168, 32
	v_readlane_b32 s43, v174, 32
	v_readlane_b32 s47, v241, 32
	v_readlane_b32 s51, v247, 32
	v_mov_b32_e32 v168, s36
	v_mov_b32_e32 v174, s40
	v_mov_b32_e32 v241, s44
	v_mov_b32_e32 v247, s48
	v_mov_b32_e32 v169, s37
	v_mov_b32_e32 v175, s41
	v_mov_b32_e32 v242, s45
	v_mov_b32_e32 v248, s49
	v_add_f32_e32 v168, s38, v168
	v_add_f32_e32 v174, s42, v174
	v_add_f32_e32 v241, s46, v241
	v_add_f32_e32 v247, s50, v247
	v_add_f32_e32 v169, s39, v169
	v_add_f32_e32 v175, s43, v175
	v_add_f32_e32 v242, s47, v242
	v_add_f32_e32 v248, s51, v248
	v_add_f32_e32 v168, v168, v169
	v_add_f32_e32 v174, v174, v175
	v_add_f32_e32 v241, v241, v242
	v_add_f32_e32 v247, v247, v248
	v_fmamk_f32 v80, v168, 0xbc800000, v80
	v_fmamk_f32 v85, v174, 0xbc800000, v85
	v_fmamk_f32 v90, v241, 0xbc800000, v90
	v_fmamk_f32 v95, v247, 0xbc800000, v95
	v_mul_f32_e32 v168, v80, v80
	v_mul_f32_e32 v174, v85, v85
	v_mul_f32_e32 v241, v90, v90
	v_mul_f32_e32 v247, v95, v95
	v_mov_b32_dpp v168, v168 quad_perm:[1,0,3,2] row_mask:0xf bank_mask:0xf bound_ctrl:1
	v_mov_b32_dpp v174, v174 quad_perm:[1,0,3,2] row_mask:0xf bank_mask:0xf bound_ctrl:1
	v_mov_b32_dpp v241, v241 quad_perm:[1,0,3,2] row_mask:0xf bank_mask:0xf bound_ctrl:1
	v_mov_b32_dpp v247, v247 quad_perm:[1,0,3,2] row_mask:0xf bank_mask:0xf bound_ctrl:1
	v_fmac_f32_e32 v168, v80, v80
; __device__ __forceinline__ float bf2f(bf16 x) { return __uint_as_float(((unsigned)x) << 16); }
; __device__ __forceinline__ unsigned f2bf(float f) { return cvt_pk_bf16(f, 0.f) & 0xffffu; }
; __device__ __forceinline__ float dpp_xor1(float x) { return __builtin_bit_cast(float, __builtin_amdgcn_update_dpp(0, __builtin_bit_cast(int, x), 0xB1, 0xF, 0xF, true)); }
; __device__ __forceinline__ float dpp_xor2(float x) { return __builtin_bit_cast(float, __builtin_amdgcn_update_dpp(0, __builtin_bit_cast(int, x), 0x4E, 0xF, 0xF, true)); }
; __device__ __forceinline__ float dpp_hmir(float x) { return __builtin_bit_cast(float, __builtin_amdgcn_update_dpp(0, __builtin_bit_cast(int, x), 0x141, 0xF, 0xF, true)); }
; __device__ __forceinline__ float dpp_mir(float x)  { return __builtin_bit_cast(float, __builtin_amdgcn_update_dpp(0, __builtin_bit_cast(int, x), 0x140, 0xF, 0xF, true)); }
; __device__ __forceinline__ float red16(float x) { x += dpp_xor1(x); x += dpp_xor2(x); x += dpp_hmir(x); x += dpp_mir(x); return x; }
; __device__ __forceinline__ float wsum(float x) {
;     x = red16(x); const int xi = __builtin_bit_cast(int, x);
;     const float r0 = __builtin_bit_cast(float, __builtin_amdgcn_readlane(xi, 0)), r1 = __builtin_bit_cast(float, __builtin_amdgcn_readlane(xi, 16));
;     const float r2 = __builtin_bit_cast(float, __builtin_amdgcn_readlane(xi, 32)), r3 = __builtin_bit_cast(float, __builtin_amdgcn_readlane(xi, 48));
;     return (r0 + r1) + (r2 + r3);
; __device__ __forceinline__ void rw_post(Frame& F) {
;     ...
;                 const float mean = wsum(y[q]) * (1.f / 64.f); const float dv = y[q] - mean; const float var = wsum(dv * dv) * (1.f / 64.f);
;                 const float yn = dv * (1.f / sqrtf(var + 64e-5f)) * g_ + b_;
;                 OB[(size_t)row * DH + col] = (bf16)f2bf((yn + rk[q] * vv[q]) * bf2f(gg[q])); }
	v_fmac_f32_e32 v174, v85, v85
	v_fmac_f32_e32 v241, v90, v90
	v_fmac_f32_e32 v247, v95, v95
	v_add_f32_dpp v168, v168, v168 quad_perm:[2,3,0,1] row_mask:0xf bank_mask:0xf bound_ctrl:1
	v_add_f32_dpp v174, v174, v174 quad_perm:[2,3,0,1] row_mask:0xf bank_mask:0xf bound_ctrl:1
	v_add_f32_dpp v241, v241, v241 quad_perm:[2,3,0,1] row_mask:0xf bank_mask:0xf bound_ctrl:1
	v_add_f32_dpp v247, v247, v247 quad_perm:[2,3,0,1] row_mask:0xf bank_mask:0xf bound_ctrl:1
	v_add_f32_dpp v168, v168, v168 row_half_mirror row_mask:0xf bank_mask:0xf bound_ctrl:1
	v_add_f32_dpp v174, v174, v174 row_half_mirror row_mask:0xf bank_mask:0xf bound_ctrl:1
	v_add_f32_dpp v241, v241, v241 row_half_mirror row_mask:0xf bank_mask:0xf bound_ctrl:1
	v_add_f32_dpp v247, v247, v247 row_half_mirror row_mask:0xf bank_mask:0xf bound_ctrl:1
	v_add_f32_dpp v168, v168, v168 row_mirror row_mask:0xf bank_mask:0xf bound_ctrl:1
	v_add_f32_dpp v174, v174, v174 row_mirror row_mask:0xf bank_mask:0xf bound_ctrl:1
	v_add_f32_dpp v241, v241, v241 row_mirror row_mask:0xf bank_mask:0xf bound_ctrl:1
	v_add_f32_dpp v247, v247, v247 row_mirror row_mask:0xf bank_mask:0xf bound_ctrl:1
	v_readlane_b32 s36, v168, 16
	v_readlane_b32 s40, v174, 16
	v_readlane_b32 s44, v241, 16
	v_readlane_b32 s48, v247, 16
	v_readlane_b32 s37, v168, 48
	v_readlane_b32 s41, v174, 48
	v_readlane_b32 s45, v241, 48
	v_readlane_b32 s49, v247, 48
	v_readlane_b32 s38, v168, 0
	v_readlane_b32 s42, v174, 0
	v_readlane_b32 s46, v241, 0
	v_readlane_b32 s50, v247, 0
	v_readlane_b32 s39, v168, 32
	v_readlane_b32 s43, v174, 32
	v_readlane_b32 s47, v241, 32
	v_readlane_b32 s51, v247, 32
	v_mov_b32_e32 v168, s36
	v_mov_b32_e32 v174, s40
	v_mov_b32_e32 v241, s44
	v_mov_b32_e32 v247, s48
	v_mov_b32_e32 v169, s37
	v_mov_b32_e32 v175, s41
	v_mov_b32_e32 v242, s45
	v_mov_b32_e32 v248, s49
	v_add_f32_e32 v168, s38, v168
	v_add_f32_e32 v174, s42, v174
	v_add_f32_e32 v241, s46, v241
	v_add_f32_e32 v247, s50, v247
	v_add_f32_e32 v169, s39, v169
	v_add_f32_e32 v175, s43, v175
	v_add_f32_e32 v242, s47, v242
	v_add_f32_e32 v248, s51, v248
	v_add_f32_e32 v168, v168, v169
	v_add_f32_e32 v174, v174, v175
	v_add_f32_e32 v241, v241, v242
	v_add_f32_e32 v247, v247, v248
	v_fmamk_f32 v168, v168, 0x3c800000, v9
	v_fmamk_f32 v174, v174, 0x3c800000, v9
	v_fmamk_f32 v241, v241, 0x3c800000, v9
	v_fmamk_f32 v247, v247, 0x3c800000, v9
	v_readfirstlane_b32 s40, v174
	v_readfirstlane_b32 s44, v241
	v_readfirstlane_b32 s48, v247
	v_writelane_b32 v168, s40, 1
	v_writelane_b32 v168, s44, 2
	v_writelane_b32 v168, s48, 3
	v_mul_f32_e32 v169, 0x4f800000, v168
	v_cmp_gt_f32_e64 s[52:53], s68, v168
	v_mov_b32_e32 v170, v168
	s_nop 1
	v_cndmask_b32_e64 v168, v170, v169, s[52:53]
	v_sqrt_f32_e32 v169, v168
	s_nop 0
	v_add_u32_e32 v170, -1, v169
	v_fma_f32 v171, -v170, v169, v168
	v_cmp_ge_f32_e64 s[60:61], 0, v171
	v_add_u32_e32 v171, 1, v169
	s_nop 1
	v_cndmask_b32_e64 v170, v169, v170, s[60:61]
	v_fma_f32 v169, -v171, v169, v168
	v_cmp_lt_f32_e64 s[60:61], 0, v169
	s_nop 1
	v_cndmask_b32_e64 v169, v170, v171, s[60:61]
	v_mul_f32_e32 v170, 0x37800000, v169
	v_cndmask_b32_e64 v169, v169, v170, s[52:53]
	v_cmp_class_f32_e64 s[60:61], v168, v8
	s_nop 1
	v_cndmask_b32_e64 v168, v169, v168, s[60:61]
	v_div_scale_f32 v169, s[60:61], v168, v168, 1.0
	v_rcp_f32_e32 v170, v169
	s_nop 0
	v_fma_f32 v171, -v169, v170, 1.0
	v_fmac_f32_e32 v170, v171, v170
	v_div_scale_f32 v171, vcc, 1.0, v168, 1.0
	v_mul_f32_e32 v172, v171, v170
	v_fma_f32 v173, -v169, v172, v171
	v_fmac_f32_e32 v172, v173, v170
	v_fma_f32 v169, -v169, v172, v171
	v_div_fmas_f32 v169, v169, v170, v172
	v_div_fixup_f32 v168, v169, v168, 1.0
	s_nop 0
	v_readlane_b32 s37, v168, 0
	v_readlane_b32 s41, v168, 1
	v_readlane_b32 s45, v168, 2
	v_readlane_b32 s49, v168, 3
	v_mul_f32_e32 v80, s37, v80
	v_mul_f32_e32 v85, s41, v85
	v_mul_f32_e32 v90, s45, v90
	v_mul_f32_e32 v95, s49, v95
	v_lshlrev_b32_e32 v83, 16, v83
	v_lshlrev_b32_e32 v88, 16, v88
	v_lshlrev_b32_e32 v93, 16, v93
	v_lshlrev_b32_e32 v98, 16, v98
	v_fma_f32 v80, v6, v80, v7
	v_fma_f32 v85, v6, v85, v7
	v_fma_f32 v90, v6, v90, v7
	v_fma_f32 v95, v6, v95, v7
	v_fmac_f32_e32 v80, s69, v81
	v_fmac_f32_e32 v85, s70, v86
	v_fmac_f32_e32 v90, s71, v91
	v_fmac_f32_e32 v95, s72, v96
	v_mul_f32_e32 v80, v80, v83
	v_mul_f32_e32 v85, v85, v88
	v_mul_f32_e32 v90, v90, v93
	v_mul_f32_e32 v95, v95, v98
	v_cvt_pk_bf16_f32 v169, v80, v80
	v_cvt_pk_bf16_f32 v175, v85, v85
	v_cvt_pk_bf16_f32 v242, v90, v90
	v_cvt_pk_bf16_f32 v248, v95, v95
	global_store_short v2, v169, s[28:29]
	s_add_u32 s28, s28, 0x1000
	s_addc_u32 s29, s29, 0
	global_store_short v2, v175, s[28:29]
	s_add_u32 s28, s28, 0x1000
	s_addc_u32 s29, s29, 0
	global_store_short v2, v242, s[28:29]
	s_add_u32 s28, s28, 0x1000
	s_addc_u32 s29, s29, 0
	global_store_short v2, v248, s[28:29]
	s_add_u32 s28, s28, 0x1000
	s_addc_u32 s29, s29, 0
	v_add_f32_e32 v100, v100, v32
	v_add_f32_e32 v105, v105, v33
	v_add_f32_e32 v110, v110, v34
	v_add_f32_e32 v115, v115, v35
	v_add_f32_dpp v168, v100, v100 quad_perm:[1,0,3,2] row_mask:0xf bank_mask:0xf bound_ctrl:1
	v_add_f32_dpp v174, v105, v105 quad_perm:[1,0,3,2] row_mask:0xf bank_mask:0xf bound_ctrl:1
	v_add_f32_dpp v241, v110, v110 quad_perm:[1,0,3,2] row_mask:0xf bank_mask:0xf bound_ctrl:1
	v_add_f32_dpp v247, v115, v115 quad_perm:[1,0,3,2] row_mask:0xf bank_mask:0xf bound_ctrl:1
	v_add_f32_dpp v168, v168, v168 quad_perm:[2,3,0,1] row_mask:0xf bank_mask:0xf bound_ctrl:1
	v_add_f32_dpp v174, v174, v174 quad_perm:[2,3,0,1] row_mask:0xf bank_mask:0xf bound_ctrl:1
	v_add_f32_dpp v241, v241, v241 quad_perm:[2,3,0,1] row_mask:0xf bank_mask:0xf bound_ctrl:1
; __device__ __forceinline__ float dpp_xor1(float x) { return __builtin_bit_cast(float, __builtin_amdgcn_update_dpp(0, __builtin_bit_cast(int, x), 0xB1, 0xF, 0xF, true)); }
; __device__ __forceinline__ float dpp_xor2(float x) { return __builtin_bit_cast(float, __builtin_amdgcn_update_dpp(0, __builtin_bit_cast(int, x), 0x4E, 0xF, 0xF, true)); }
; __device__ __forceinline__ float dpp_hmir(float x) { return __builtin_bit_cast(float, __builtin_amdgcn_update_dpp(0, __builtin_bit_cast(int, x), 0x141, 0xF, 0xF, true)); }
; __device__ __forceinline__ float dpp_mir(float x)  { return __builtin_bit_cast(float, __builtin_amdgcn_update_dpp(0, __builtin_bit_cast(int, x), 0x140, 0xF, 0xF, true)); }
; __device__ __forceinline__ float red16(float x) { x += dpp_xor1(x); x += dpp_xor2(x); x += dpp_hmir(x); x += dpp_mir(x); return x; }
; __device__ __forceinline__ float wsum(float x) {
;     x = red16(x); const int xi = __builtin_bit_cast(int, x);
;     const float r0 = __builtin_bit_cast(float, __builtin_amdgcn_readlane(xi, 0)), r1 = __builtin_bit_cast(float, __builtin_amdgcn_readlane(xi, 16));
;     const float r2 = __builtin_bit_cast(float, __builtin_amdgcn_readlane(xi, 32)), r3 = __builtin_bit_cast(float, __builtin_amdgcn_readlane(xi, 48));
;     return (r0 + r1) + (r2 + r3);
; __device__ __forceinline__ void rw_post(Frame& F) {
;     ...
;             for (int q = 0; q < 8; ++q) { const int row = rb0 + t0 + q;
;                 const float mean = wsum(y[q]) * (1.f / 64.f); const float dv = y[q] - mean; const float var = wsum(dv * dv) * (1.f / 64.f);
;                 const float yn = dv * (1.f / sqrtf(var + 64e-5f)) * g_ + b_;
	v_add_f32_dpp v247, v247, v247 quad_perm:[2,3,0,1] row_mask:0xf bank_mask:0xf bound_ctrl:1
	v_add_f32_dpp v168, v168, v168 row_half_mirror row_mask:0xf bank_mask:0xf bound_ctrl:1
	v_add_f32_dpp v174, v174, v174 row_half_mirror row_mask:0xf bank_mask:0xf bound_ctrl:1
	v_add_f32_dpp v241, v241, v241 row_half_mirror row_mask:0xf bank_mask:0xf bound_ctrl:1
	v_add_f32_dpp v247, v247, v247 row_half_mirror row_mask:0xf bank_mask:0xf bound_ctrl:1
	v_add_f32_dpp v168, v168, v168 row_mirror row_mask:0xf bank_mask:0xf bound_ctrl:1
	v_add_f32_dpp v174, v174, v174 row_mirror row_mask:0xf bank_mask:0xf bound_ctrl:1
	v_add_f32_dpp v241, v241, v241 row_mirror row_mask:0xf bank_mask:0xf bound_ctrl:1
	v_add_f32_dpp v247, v247, v247 row_mirror row_mask:0xf bank_mask:0xf bound_ctrl:1
	v_readlane_b32 s36, v168, 16
	v_readlane_b32 s40, v174, 16
	v_readlane_b32 s44, v241, 16
	v_readlane_b32 s48, v247, 16
	v_readlane_b32 s37, v168, 48
	v_readlane_b32 s41, v174, 48
	v_readlane_b32 s45, v241, 48
	v_readlane_b32 s49, v247, 48
	v_readlane_b32 s38, v168, 0
	v_readlane_b32 s42, v174, 0
	v_readlane_b32 s46, v241, 0
	v_readlane_b32 s50, v247, 0
	v_readlane_b32 s39, v168, 32
	v_readlane_b32 s43, v174, 32
	v_readlane_b32 s47, v241, 32
	v_readlane_b32 s51, v247, 32
	v_mov_b32_e32 v168, s36
	v_mov_b32_e32 v174, s40
	v_mov_b32_e32 v241, s44
	v_mov_b32_e32 v247, s48
	v_mov_b32_e32 v169, s37
	v_mov_b32_e32 v175, s41
	v_mov_b32_e32 v242, s45
	v_mov_b32_e32 v248, s49
	v_add_f32_e32 v168, s38, v168
	v_add_f32_e32 v174, s42, v174
	v_add_f32_e32 v241, s46, v241
	v_add_f32_e32 v247, s50, v247
	v_add_f32_e32 v169, s39, v169
	v_add_f32_e32 v175, s43, v175
	v_add_f32_e32 v242, s47, v242
	v_add_f32_e32 v248, s51, v248
	v_add_f32_e32 v168, v168, v169
	v_add_f32_e32 v174, v174, v175
	v_add_f32_e32 v241, v241, v242
	v_add_f32_e32 v247, v247, v248
	v_fmamk_f32 v100, v168, 0xbc800000, v100
	v_fmamk_f32 v105, v174, 0xbc800000, v105
	v_fmamk_f32 v110, v241, 0xbc800000, v110
	v_fmamk_f32 v115, v247, 0xbc800000, v115
	v_mul_f32_e32 v168, v100, v100
	v_mul_f32_e32 v174, v105, v105
	v_mul_f32_e32 v241, v110, v110
	v_mul_f32_e32 v247, v115, v115
	v_mov_b32_dpp v168, v168 quad_perm:[1,0,3,2] row_mask:0xf bank_mask:0xf bound_ctrl:1
	v_mov_b32_dpp v174, v174 quad_perm:[1,0,3,2] row_mask:0xf bank_mask:0xf bound_ctrl:1
	v_mov_b32_dpp v241, v241 quad_perm:[1,0,3,2] row_mask:0xf bank_mask:0xf bound_ctrl:1
	v_mov_b32_dpp v247, v247 quad_perm:[1,0,3,2] row_mask:0xf bank_mask:0xf bound_ctrl:1
	v_fmac_f32_e32 v168, v100, v100
	v_fmac_f32_e32 v174, v105, v105
	v_fmac_f32_e32 v241, v110, v110
	v_fmac_f32_e32 v247, v115, v115
	v_add_f32_dpp v168, v168, v168 quad_perm:[2,3,0,1] row_mask:0xf bank_mask:0xf bound_ctrl:1
	v_add_f32_dpp v174, v174, v174 quad_perm:[2,3,0,1] row_mask:0xf bank_mask:0xf bound_ctrl:1
	v_add_f32_dpp v241, v241, v241 quad_perm:[2,3,0,1] row_mask:0xf bank_mask:0xf bound_ctrl:1
	v_add_f32_dpp v247, v247, v247 quad_perm:[2,3,0,1] row_mask:0xf bank_mask:0xf bound_ctrl:1
	v_add_f32_dpp v168, v168, v168 row_half_mirror row_mask:0xf bank_mask:0xf bound_ctrl:1
	v_add_f32_dpp v174, v174, v174 row_half_mirror row_mask:0xf bank_mask:0xf bound_ctrl:1
	v_add_f32_dpp v241, v241, v241 row_half_mirror row_mask:0xf bank_mask:0xf bound_ctrl:1
	v_add_f32_dpp v247, v247, v247 row_half_mirror row_mask:0xf bank_mask:0xf bound_ctrl:1
	v_add_f32_dpp v168, v168, v168 row_mirror row_mask:0xf bank_mask:0xf bound_ctrl:1
	v_add_f32_dpp v174, v174, v174 row_mirror row_mask:0xf bank_mask:0xf bound_ctrl:1
	v_add_f32_dpp v241, v241, v241 row_mirror row_mask:0xf bank_mask:0xf bound_ctrl:1
	v_add_f32_dpp v247, v247, v247 row_mirror row_mask:0xf bank_mask:0xf bound_ctrl:1
	v_readlane_b32 s36, v168, 16
	v_readlane_b32 s40, v174, 16
	v_readlane_b32 s44, v241, 16
	v_readlane_b32 s48, v247, 16
	v_readlane_b32 s37, v168, 48
	v_readlane_b32 s41, v174, 48
	v_readlane_b32 s45, v241, 48
	v_readlane_b32 s49, v247, 48
	v_readlane_b32 s38, v168, 0
	v_readlane_b32 s42, v174, 0
	v_readlane_b32 s46, v241, 0
	v_readlane_b32 s50, v247, 0
	v_readlane_b32 s39, v168, 32
	v_readlane_b32 s43, v174, 32
	v_readlane_b32 s47, v241, 32
	v_readlane_b32 s51, v247, 32
	v_mov_b32_e32 v168, s36
	v_mov_b32_e32 v174, s40
	v_mov_b32_e32 v241, s44
	v_mov_b32_e32 v247, s48
	v_mov_b32_e32 v169, s37
	v_mov_b32_e32 v175, s41
	v_mov_b32_e32 v242, s45
	v_mov_b32_e32 v248, s49
	v_add_f32_e32 v168, s38, v168
	v_add_f32_e32 v174, s42, v174
	v_add_f32_e32 v241, s46, v241
	v_add_f32_e32 v247, s50, v247
	v_add_f32_e32 v169, s39, v169
	v_add_f32_e32 v175, s43, v175
	v_add_f32_e32 v242, s47, v242
	v_add_f32_e32 v248, s51, v248
	v_add_f32_e32 v168, v168, v169
	v_add_f32_e32 v174, v174, v175
	v_add_f32_e32 v241, v241, v242
	v_add_f32_e32 v247, v247, v248
	v_fmamk_f32 v168, v168, 0x3c800000, v9
	v_fmamk_f32 v174, v174, 0x3c800000, v9
	v_fmamk_f32 v241, v241, 0x3c800000, v9
	v_fmamk_f32 v247, v247, 0x3c800000, v9
	v_readfirstlane_b32 s40, v174
	v_readfirstlane_b32 s44, v241
	v_readfirstlane_b32 s48, v247
	v_writelane_b32 v168, s40, 1
	v_writelane_b32 v168, s44, 2
	v_writelane_b32 v168, s48, 3
	v_mul_f32_e32 v169, 0x4f800000, v168
	v_cmp_gt_f32_e64 s[52:53], s68, v168
	v_mov_b32_e32 v170, v168
	s_nop 1
	v_cndmask_b32_e64 v168, v170, v169, s[52:53]
	v_sqrt_f32_e32 v169, v168
	s_nop 0
	v_add_u32_e32 v170, -1, v169
	v_fma_f32 v171, -v170, v169, v168
	v_cmp_ge_f32_e64 s[60:61], 0, v171
	v_add_u32_e32 v171, 1, v169
	s_nop 1
	v_cndmask_b32_e64 v170, v169, v170, s[60:61]
	v_fma_f32 v169, -v171, v169, v168
	v_cmp_lt_f32_e64 s[60:61], 0, v169
	s_nop 1
	v_cndmask_b32_e64 v169, v170, v171, s[60:61]
	v_mul_f32_e32 v170, 0x37800000, v169
	v_cndmask_b32_e64 v169, v169, v170, s[52:53]
; __device__ __forceinline__ float bf2f(bf16 x) { return __uint_as_float(((unsigned)x) << 16); }
; __device__ __forceinline__ unsigned f2bf(float f) { return cvt_pk_bf16(f, 0.f) & 0xffffu; }
; #define POST_LD(Y_, V_, G_, R_, C_, t) do { _Pragma("unroll") for (int q = 0; q < 8; ++q) { const size_t o_ = (size_t)((t) + q) * DH; Y_[q] = yp[o_]; V_[q] = vp[o_]; G_[q] = gp[o_]; R_[q] = rp[((t) + q) * 32]; C_[q] = cp[o_]; } } while (0)
; __device__ __forceinline__ void rw_post(Frame& F) {
;     ...
;         POST_LD(y, vv, gg, rk, cc, 0);
;         for (int t0 = 0; t0 < 64; t0 += 8) {
;             float ny[8], nv[8], nr[8], nc[8]; bf16 ng[8];
;             const int tn = t0 + 8 < 64 ? t0 + 8 : t0;
;             POST_LD(ny, nv, ng, nr, nc, tn);
;     ...
;             for (int q = 0; q < 8; ++q) { const int row = rb0 + t0 + q;
;                 const float mean = wsum(y[q]) * (1.f / 64.f); const float dv = y[q] - mean; const float var = wsum(dv * dv) * (1.f / 64.f);
;                 const float yn = dv * (1.f / sqrtf(var + 64e-5f)) * g_ + b_;
;                 OB[(size_t)row * DH + col] = (bf16)f2bf((yn + rk[q] * vv[q]) * bf2f(gg[q])); }
	v_cmp_class_f32_e64 s[60:61], v168, v8
	s_nop 1
	v_cndmask_b32_e64 v168, v169, v168, s[60:61]
	v_div_scale_f32 v169, s[60:61], v168, v168, 1.0
	v_rcp_f32_e32 v170, v169
	s_nop 0
	v_fma_f32 v171, -v169, v170, 1.0
	v_fmac_f32_e32 v170, v171, v170
	v_div_scale_f32 v171, vcc, 1.0, v168, 1.0
	v_mul_f32_e32 v172, v171, v170
	v_fma_f32 v173, -v169, v172, v171
	v_fmac_f32_e32 v172, v173, v170
	v_fma_f32 v169, -v169, v172, v171
	v_div_fmas_f32 v169, v169, v170, v172
	v_div_fixup_f32 v168, v169, v168, 1.0
	s_nop 0
	v_readlane_b32 s37, v168, 0
	v_readlane_b32 s41, v168, 1
	v_readlane_b32 s45, v168, 2
	v_readlane_b32 s49, v168, 3
	v_mul_f32_e32 v100, s37, v100
	v_mul_f32_e32 v105, s41, v105
	v_mul_f32_e32 v110, s45, v110
	v_mul_f32_e32 v115, s49, v115
	v_lshlrev_b32_e32 v103, 16, v103
	v_lshlrev_b32_e32 v108, 16, v108
	v_lshlrev_b32_e32 v113, 16, v113
	v_lshlrev_b32_e32 v118, 16, v118
	v_fma_f32 v100, v6, v100, v7
	v_fma_f32 v105, v6, v105, v7
	v_fma_f32 v110, v6, v110, v7
	v_fma_f32 v115, v6, v115, v7
	v_fmac_f32_e32 v100, s73, v101
	v_fmac_f32_e32 v105, s26, v106
	v_fmac_f32_e32 v110, s27, v111
	v_fmac_f32_e32 v115, s32, v116
	v_mul_f32_e32 v100, v100, v103
	v_mul_f32_e32 v105, v105, v108
	v_mul_f32_e32 v110, v110, v113
	v_mul_f32_e32 v115, v115, v118
	v_cvt_pk_bf16_f32 v169, v100, v100
	v_cvt_pk_bf16_f32 v175, v105, v105
	v_cvt_pk_bf16_f32 v242, v110, v110
	v_cvt_pk_bf16_f32 v248, v115, v115
	global_store_short v2, v169, s[28:29]
	s_add_u32 s28, s28, 0x1000
	s_addc_u32 s29, s29, 0
	global_store_short v2, v175, s[28:29]
	s_add_u32 s28, s28, 0x1000
	s_addc_u32 s29, s29, 0
	global_store_short v2, v242, s[28:29]
	s_add_u32 s28, s28, 0x1000
	s_addc_u32 s29, s29, 0
	global_store_short v2, v248, s[28:29]
	s_add_u32 s28, s28, 0x1000
	s_addc_u32 s29, s29, 0
	s_waitcnt vmcnt(8)
	ds_write_b128 v13, v[120:123] offset:0
	ds_write_b128 v13, v[124:127] offset:1024
	ds_write_b128 v13, v[128:131] offset:16384
	ds_write_b128 v13, v[132:135] offset:17408
	ds_write_b128 v15, v[136:139]
	v_readlane_b32 s69, v159, 0
	v_readlane_b32 s70, v159, 1
	v_readlane_b32 s71, v159, 2
	v_readlane_b32 s72, v159, 3
	v_readlane_b32 s73, v159, 4
	v_readlane_b32 s26, v159, 5
	v_readlane_b32 s27, v159, 6
	v_readlane_b32 s32, v159, 7
	global_load_dwordx4 v[120:123], v11, s[6:7]
	global_load_dwordx4 v[124:127], v11, s[6:7] offset:1024
	global_load_dwordx4 v[128:131], v11, s[8:9]
	global_load_dwordx4 v[132:135], v11, s[8:9] offset:1024
	global_load_dwordx4 v[136:139], v11, s[10:11]
	global_load_dword v159, v158, s[12:13]
	s_add_u32 s6, s6, 0x10000
	s_addc_u32 s7, s7, 0
	s_add_u32 s8, s8, 0x10000
	s_addc_u32 s9, s9, 0
	s_add_u32 s10, s10, 0x8000
	s_addc_u32 s11, s11, 0
	s_add_u32 s12, s12, 0x400
	s_addc_u32 s13, s13, 0
	s_waitcnt lgkmcnt(0)
	s_barrier
	ds_read_b32 v80, v155 offset:0
	ds_read_b32 v81, v155 offset:16384
	ds_read_u16 v83, v157 offset:0
	ds_read_b32 v85, v155 offset:2048
	ds_read_b32 v86, v155 offset:18432
	ds_read_u16 v88, v157 offset:1024
	ds_read_b32 v90, v155 offset:4096
	ds_read_b32 v91, v155 offset:20480
	ds_read_u16 v93, v157 offset:2048
	ds_read_b32 v95, v155 offset:6144
	ds_read_b32 v96, v155 offset:22528
	ds_read_u16 v98, v157 offset:3072
	ds_read_b32 v100, v155 offset:8192
	ds_read_b32 v101, v155 offset:24576
	ds_read_u16 v103, v157 offset:4096
	ds_read_b32 v105, v155 offset:10240
	ds_read_b32 v106, v155 offset:26624
	ds_read_u16 v108, v157 offset:5120
	ds_read_b32 v110, v155 offset:12288
	ds_read_b32 v111, v155 offset:28672
	ds_read_u16 v113, v157 offset:6144
	ds_read_b32 v115, v155 offset:14336
	ds_read_b32 v116, v155 offset:30720
	ds_read_u16 v118, v157 offset:7168
	s_waitcnt lgkmcnt(0)
	v_add_f32_e32 v80, v80, v20
	v_add_f32_e32 v85, v85, v21
	v_add_f32_e32 v90, v90, v22
	v_add_f32_e32 v95, v95, v23
	v_add_f32_dpp v168, v80, v80 quad_perm:[1,0,3,2] row_mask:0xf bank_mask:0xf bound_ctrl:1
	v_add_f32_dpp v174, v85, v85 quad_perm:[1,0,3,2] row_mask:0xf bank_mask:0xf bound_ctrl:1
	v_add_f32_dpp v241, v90, v90 quad_perm:[1,0,3,2] row_mask:0xf bank_mask:0xf bound_ctrl:1
	v_add_f32_dpp v247, v95, v95 quad_perm:[1,0,3,2] row_mask:0xf bank_mask:0xf bound_ctrl:1
	v_add_f32_dpp v168, v168, v168 quad_perm:[2,3,0,1] row_mask:0xf bank_mask:0xf bound_ctrl:1
	v_add_f32_dpp v174, v174, v174 quad_perm:[2,3,0,1] row_mask:0xf bank_mask:0xf bound_ctrl:1
	v_add_f32_dpp v241, v241, v241 quad_perm:[2,3,0,1] row_mask:0xf bank_mask:0xf bound_ctrl:1
	v_add_f32_dpp v247, v247, v247 quad_perm:[2,3,0,1] row_mask:0xf bank_mask:0xf bound_ctrl:1
	v_add_f32_dpp v168, v168, v168 row_half_mirror row_mask:0xf bank_mask:0xf bound_ctrl:1
	v_add_f32_dpp v174, v174, v174 row_half_mirror row_mask:0xf bank_mask:0xf bound_ctrl:1
	v_add_f32_dpp v241, v241, v241 row_half_mirror row_mask:0xf bank_mask:0xf bound_ctrl:1
	v_add_f32_dpp v247, v247, v247 row_half_mirror row_mask:0xf bank_mask:0xf bound_ctrl:1
	v_add_f32_dpp v168, v168, v168 row_mirror row_mask:0xf bank_mask:0xf bound_ctrl:1
	v_add_f32_dpp v174, v174, v174 row_mirror row_mask:0xf bank_mask:0xf bound_ctrl:1
	v_add_f32_dpp v241, v241, v241 row_mirror row_mask:0xf bank_mask:0xf bound_ctrl:1
	v_add_f32_dpp v247, v247, v247 row_mirror row_mask:0xf bank_mask:0xf bound_ctrl:1
	v_readlane_b32 s36, v168, 16
	v_readlane_b32 s40, v174, 16
	v_readlane_b32 s44, v241, 16
	v_readlane_b32 s48, v247, 16
	v_readlane_b32 s37, v168, 48
	v_readlane_b32 s41, v174, 48
	v_readlane_b32 s45, v241, 48
	v_readlane_b32 s49, v247, 48
	v_readlane_b32 s38, v168, 0
	v_readlane_b32 s42, v174, 0
	v_readlane_b32 s46, v241, 0
	v_readlane_b32 s50, v247, 0
	v_readlane_b32 s39, v168, 32
	v_readlane_b32 s43, v174, 32
	v_readlane_b32 s47, v241, 32
	v_readlane_b32 s51, v247, 32
; __device__ __forceinline__ float bf2f(bf16 x) { return __uint_as_float(((unsigned)x) << 16); }
; __device__ __forceinline__ unsigned f2bf(float f) { return cvt_pk_bf16(f, 0.f) & 0xffffu; }
; __device__ __forceinline__ void rw_post(Frame& F) {
;     ...
;             for (int q = 0; q < 8; ++q) { const int row = rb0 + t0 + q;
;                 const float mean = wsum(y[q]) * (1.f / 64.f); const float dv = y[q] - mean; const float var = wsum(dv * dv) * (1.f / 64.f);
;                 const float yn = dv * (1.f / sqrtf(var + 64e-5f)) * g_ + b_;
;                 OB[(size_t)row * DH + col] = (bf16)f2bf((yn + rk[q] * vv[q]) * bf2f(gg[q])); }
	v_mov_b32_e32 v168, s36
	v_mov_b32_e32 v174, s40
	v_mov_b32_e32 v241, s44
	v_mov_b32_e32 v247, s48
	v_mov_b32_e32 v169, s37
	v_mov_b32_e32 v175, s41
	v_mov_b32_e32 v242, s45
	v_mov_b32_e32 v248, s49
	v_add_f32_e32 v168, s38, v168
	v_add_f32_e32 v174, s42, v174
	v_add_f32_e32 v241, s46, v241
	v_add_f32_e32 v247, s50, v247
	v_add_f32_e32 v169, s39, v169
	v_add_f32_e32 v175, s43, v175
	v_add_f32_e32 v242, s47, v242
	v_add_f32_e32 v248, s51, v248
	v_add_f32_e32 v168, v168, v169
	v_add_f32_e32 v174, v174, v175
	v_add_f32_e32 v241, v241, v242
	v_add_f32_e32 v247, v247, v248
	v_fmamk_f32 v80, v168, 0xbc800000, v80
	v_fmamk_f32 v85, v174, 0xbc800000, v85
	v_fmamk_f32 v90, v241, 0xbc800000, v90
	v_fmamk_f32 v95, v247, 0xbc800000, v95
	v_mul_f32_e32 v168, v80, v80
	v_mul_f32_e32 v174, v85, v85
	v_mul_f32_e32 v241, v90, v90
	v_mul_f32_e32 v247, v95, v95
	v_mov_b32_dpp v168, v168 quad_perm:[1,0,3,2] row_mask:0xf bank_mask:0xf bound_ctrl:1
	v_mov_b32_dpp v174, v174 quad_perm:[1,0,3,2] row_mask:0xf bank_mask:0xf bound_ctrl:1
	v_mov_b32_dpp v241, v241 quad_perm:[1,0,3,2] row_mask:0xf bank_mask:0xf bound_ctrl:1
	v_mov_b32_dpp v247, v247 quad_perm:[1,0,3,2] row_mask:0xf bank_mask:0xf bound_ctrl:1
	v_fmac_f32_e32 v168, v80, v80
	v_fmac_f32_e32 v174, v85, v85
	v_fmac_f32_e32 v241, v90, v90
	v_fmac_f32_e32 v247, v95, v95
	v_add_f32_dpp v168, v168, v168 quad_perm:[2,3,0,1] row_mask:0xf bank_mask:0xf bound_ctrl:1
	v_add_f32_dpp v174, v174, v174 quad_perm:[2,3,0,1] row_mask:0xf bank_mask:0xf bound_ctrl:1
	v_add_f32_dpp v241, v241, v241 quad_perm:[2,3,0,1] row_mask:0xf bank_mask:0xf bound_ctrl:1
	v_add_f32_dpp v247, v247, v247 quad_perm:[2,3,0,1] row_mask:0xf bank_mask:0xf bound_ctrl:1
	v_add_f32_dpp v168, v168, v168 row_half_mirror row_mask:0xf bank_mask:0xf bound_ctrl:1
	v_add_f32_dpp v174, v174, v174 row_half_mirror row_mask:0xf bank_mask:0xf bound_ctrl:1
	v_add_f32_dpp v241, v241, v241 row_half_mirror row_mask:0xf bank_mask:0xf bound_ctrl:1
	v_add_f32_dpp v247, v247, v247 row_half_mirror row_mask:0xf bank_mask:0xf bound_ctrl:1
	v_add_f32_dpp v168, v168, v168 row_mirror row_mask:0xf bank_mask:0xf bound_ctrl:1
	v_add_f32_dpp v174, v174, v174 row_mirror row_mask:0xf bank_mask:0xf bound_ctrl:1
	v_add_f32_dpp v241, v241, v241 row_mirror row_mask:0xf bank_mask:0xf bound_ctrl:1
	v_add_f32_dpp v247, v247, v247 row_mirror row_mask:0xf bank_mask:0xf bound_ctrl:1
	v_readlane_b32 s36, v168, 16
	v_readlane_b32 s40, v174, 16
	v_readlane_b32 s44, v241, 16
	v_readlane_b32 s48, v247, 16
	v_readlane_b32 s37, v168, 48
	v_readlane_b32 s41, v174, 48
	v_readlane_b32 s45, v241, 48
	v_readlane_b32 s49, v247, 48
	v_readlane_b32 s38, v168, 0
	v_readlane_b32 s42, v174, 0
	v_readlane_b32 s46, v241, 0
	v_readlane_b32 s50, v247, 0
	v_readlane_b32 s39, v168, 32
	v_readlane_b32 s43, v174, 32
	v_readlane_b32 s47, v241, 32
	v_readlane_b32 s51, v247, 32
	v_mov_b32_e32 v168, s36
	v_mov_b32_e32 v174, s40
	v_mov_b32_e32 v241, s44
	v_mov_b32_e32 v247, s48
	v_mov_b32_e32 v169, s37
	v_mov_b32_e32 v175, s41
	v_mov_b32_e32 v242, s45
	v_mov_b32_e32 v248, s49
	v_add_f32_e32 v168, s38, v168
	v_add_f32_e32 v174, s42, v174
	v_add_f32_e32 v241, s46, v241
	v_add_f32_e32 v247, s50, v247
	v_add_f32_e32 v169, s39, v169
	v_add_f32_e32 v175, s43, v175
	v_add_f32_e32 v242, s47, v242
	v_add_f32_e32 v248, s51, v248
	v_add_f32_e32 v168, v168, v169
	v_add_f32_e32 v174, v174, v175
	v_add_f32_e32 v241, v241, v242
	v_add_f32_e32 v247, v247, v248
	v_fmamk_f32 v168, v168, 0x3c800000, v9
	v_fmamk_f32 v174, v174, 0x3c800000, v9
	v_fmamk_f32 v241, v241, 0x3c800000, v9
	v_fmamk_f32 v247, v247, 0x3c800000, v9
	v_readfirstlane_b32 s40, v174
	v_readfirstlane_b32 s44, v241
	v_readfirstlane_b32 s48, v247
	v_writelane_b32 v168, s40, 1
	v_writelane_b32 v168, s44, 2
	v_writelane_b32 v168, s48, 3
	v_mul_f32_e32 v169, 0x4f800000, v168
	v_cmp_gt_f32_e64 s[52:53], s68, v168
	v_mov_b32_e32 v170, v168
	s_nop 1
	v_cndmask_b32_e64 v168, v170, v169, s[52:53]
	v_sqrt_f32_e32 v169, v168
	s_nop 0
	v_add_u32_e32 v170, -1, v169
	v_fma_f32 v171, -v170, v169, v168
	v_cmp_ge_f32_e64 s[60:61], 0, v171
	v_add_u32_e32 v171, 1, v169
	s_nop 1
	v_cndmask_b32_e64 v170, v169, v170, s[60:61]
	v_fma_f32 v169, -v171, v169, v168
	v_cmp_lt_f32_e64 s[60:61], 0, v169
	s_nop 1
	v_cndmask_b32_e64 v169, v170, v171, s[60:61]
	v_mul_f32_e32 v170, 0x37800000, v169
	v_cndmask_b32_e64 v169, v169, v170, s[52:53]
	v_cmp_class_f32_e64 s[60:61], v168, v8
	s_nop 1
	v_cndmask_b32_e64 v168, v169, v168, s[60:61]
	v_div_scale_f32 v169, s[60:61], v168, v168, 1.0
	v_rcp_f32_e32 v170, v169
	s_nop 0
	v_fma_f32 v171, -v169, v170, 1.0
	v_fmac_f32_e32 v170, v171, v170
	v_div_scale_f32 v171, vcc, 1.0, v168, 1.0
	v_mul_f32_e32 v172, v171, v170
	v_fma_f32 v173, -v169, v172, v171
	v_fmac_f32_e32 v172, v173, v170
	v_fma_f32 v169, -v169, v172, v171
	v_div_fmas_f32 v169, v169, v170, v172
	v_div_fixup_f32 v168, v169, v168, 1.0
	s_nop 0
	v_readlane_b32 s37, v168, 0
	v_readlane_b32 s41, v168, 1
	v_readlane_b32 s45, v168, 2
	v_readlane_b32 s49, v168, 3
	v_mul_f32_e32 v80, s37, v80
	v_mul_f32_e32 v85, s41, v85
	v_mul_f32_e32 v90, s45, v90
	v_mul_f32_e32 v95, s49, v95
	v_lshlrev_b32_e32 v83, 16, v83
	v_lshlrev_b32_e32 v88, 16, v88
	v_lshlrev_b32_e32 v93, 16, v93
	v_lshlrev_b32_e32 v98, 16, v98
	v_fma_f32 v80, v6, v80, v7
	v_fma_f32 v85, v6, v85, v7
	v_fma_f32 v90, v6, v90, v7
	v_fma_f32 v95, v6, v95, v7
	v_fmac_f32_e32 v80, s69, v81
	v_fmac_f32_e32 v85, s70, v86
	v_fmac_f32_e32 v90, s71, v91
	v_fmac_f32_e32 v95, s72, v96
	v_mul_f32_e32 v80, v80, v83
	v_mul_f32_e32 v85, v85, v88
	v_mul_f32_e32 v90, v90, v93
	v_mul_f32_e32 v95, v95, v98
	v_cvt_pk_bf16_f32 v169, v80, v80
	v_cvt_pk_bf16_f32 v175, v85, v85
; __device__ __forceinline__ float bf2f(bf16 x) { return __uint_as_float(((unsigned)x) << 16); }
; __device__ __forceinline__ unsigned f2bf(float f) { return cvt_pk_bf16(f, 0.f) & 0xffffu; }
; __device__ __forceinline__ void rw_post(Frame& F) {
;     ...
;             for (int q = 0; q < 8; ++q) { const int row = rb0 + t0 + q;
;                 const float mean = wsum(y[q]) * (1.f / 64.f); const float dv = y[q] - mean; const float var = wsum(dv * dv) * (1.f / 64.f);
;                 const float yn = dv * (1.f / sqrtf(var + 64e-5f)) * g_ + b_;
;                 OB[(size_t)row * DH + col] = (bf16)f2bf((yn + rk[q] * vv[q]) * bf2f(gg[q])); }
	v_cvt_pk_bf16_f32 v242, v90, v90
	v_cvt_pk_bf16_f32 v248, v95, v95
	global_store_short v2, v169, s[28:29]
	s_add_u32 s28, s28, 0x1000
	s_addc_u32 s29, s29, 0
	global_store_short v2, v175, s[28:29]
	s_add_u32 s28, s28, 0x1000
	s_addc_u32 s29, s29, 0
	global_store_short v2, v242, s[28:29]
	s_add_u32 s28, s28, 0x1000
	s_addc_u32 s29, s29, 0
	global_store_short v2, v248, s[28:29]
	s_add_u32 s28, s28, 0x1000
	s_addc_u32 s29, s29, 0
	v_add_f32_e32 v100, v100, v36
	v_add_f32_e32 v105, v105, v37
	v_add_f32_e32 v110, v110, v38
	v_add_f32_e32 v115, v115, v39
	v_add_f32_dpp v168, v100, v100 quad_perm:[1,0,3,2] row_mask:0xf bank_mask:0xf bound_ctrl:1
	v_add_f32_dpp v174, v105, v105 quad_perm:[1,0,3,2] row_mask:0xf bank_mask:0xf bound_ctrl:1
	v_add_f32_dpp v241, v110, v110 quad_perm:[1,0,3,2] row_mask:0xf bank_mask:0xf bound_ctrl:1
	v_add_f32_dpp v247, v115, v115 quad_perm:[1,0,3,2] row_mask:0xf bank_mask:0xf bound_ctrl:1
	v_add_f32_dpp v168, v168, v168 quad_perm:[2,3,0,1] row_mask:0xf bank_mask:0xf bound_ctrl:1
	v_add_f32_dpp v174, v174, v174 quad_perm:[2,3,0,1] row_mask:0xf bank_mask:0xf bound_ctrl:1
	v_add_f32_dpp v241, v241, v241 quad_perm:[2,3,0,1] row_mask:0xf bank_mask:0xf bound_ctrl:1
	v_add_f32_dpp v247, v247, v247 quad_perm:[2,3,0,1] row_mask:0xf bank_mask:0xf bound_ctrl:1
	v_add_f32_dpp v168, v168, v168 row_half_mirror row_mask:0xf bank_mask:0xf bound_ctrl:1
	v_add_f32_dpp v174, v174, v174 row_half_mirror row_mask:0xf bank_mask:0xf bound_ctrl:1
	v_add_f32_dpp v241, v241, v241 row_half_mirror row_mask:0xf bank_mask:0xf bound_ctrl:1
	v_add_f32_dpp v247, v247, v247 row_half_mirror row_mask:0xf bank_mask:0xf bound_ctrl:1
	v_add_f32_dpp v168, v168, v168 row_mirror row_mask:0xf bank_mask:0xf bound_ctrl:1
	v_add_f32_dpp v174, v174, v174 row_mirror row_mask:0xf bank_mask:0xf bound_ctrl:1
	v_add_f32_dpp v241, v241, v241 row_mirror row_mask:0xf bank_mask:0xf bound_ctrl:1
	v_add_f32_dpp v247, v247, v247 row_mirror row_mask:0xf bank_mask:0xf bound_ctrl:1
	v_readlane_b32 s36, v168, 16
	v_readlane_b32 s40, v174, 16
	v_readlane_b32 s44, v241, 16
	v_readlane_b32 s48, v247, 16
	v_readlane_b32 s37, v168, 48
	v_readlane_b32 s41, v174, 48
	v_readlane_b32 s45, v241, 48
	v_readlane_b32 s49, v247, 48
	v_readlane_b32 s38, v168, 0
	v_readlane_b32 s42, v174, 0
	v_readlane_b32 s46, v241, 0
	v_readlane_b32 s50, v247, 0
	v_readlane_b32 s39, v168, 32
	v_readlane_b32 s43, v174, 32
	v_readlane_b32 s47, v241, 32
	v_readlane_b32 s51, v247, 32
	v_mov_b32_e32 v168, s36
	v_mov_b32_e32 v174, s40
	v_mov_b32_e32 v241, s44
	v_mov_b32_e32 v247, s48
	v_mov_b32_e32 v169, s37
	v_mov_b32_e32 v175, s41
	v_mov_b32_e32 v242, s45
	v_mov_b32_e32 v248, s49
	v_add_f32_e32 v168, s38, v168
	v_add_f32_e32 v174, s42, v174
	v_add_f32_e32 v241, s46, v241
	v_add_f32_e32 v247, s50, v247
	v_add_f32_e32 v169, s39, v169
	v_add_f32_e32 v175, s43, v175
	v_add_f32_e32 v242, s47, v242
	v_add_f32_e32 v248, s51, v248
	v_add_f32_e32 v168, v168, v169
	v_add_f32_e32 v174, v174, v175
	v_add_f32_e32 v241, v241, v242
	v_add_f32_e32 v247, v247, v248
	v_fmamk_f32 v100, v168, 0xbc800000, v100
	v_fmamk_f32 v105, v174, 0xbc800000, v105
	v_fmamk_f32 v110, v241, 0xbc800000, v110
	v_fmamk_f32 v115, v247, 0xbc800000, v115
	v_mul_f32_e32 v168, v100, v100
	v_mul_f32_e32 v174, v105, v105
	v_mul_f32_e32 v241, v110, v110
	v_mul_f32_e32 v247, v115, v115
	v_mov_b32_dpp v168, v168 quad_perm:[1,0,3,2] row_mask:0xf bank_mask:0xf bound_ctrl:1
	v_mov_b32_dpp v174, v174 quad_perm:[1,0,3,2] row_mask:0xf bank_mask:0xf bound_ctrl:1
	v_mov_b32_dpp v241, v241 quad_perm:[1,0,3,2] row_mask:0xf bank_mask:0xf bound_ctrl:1
	v_mov_b32_dpp v247, v247 quad_perm:[1,0,3,2] row_mask:0xf bank_mask:0xf bound_ctrl:1
	v_fmac_f32_e32 v168, v100, v100
	v_fmac_f32_e32 v174, v105, v105
	v_fmac_f32_e32 v241, v110, v110
	v_fmac_f32_e32 v247, v115, v115
	v_add_f32_dpp v168, v168, v168 quad_perm:[2,3,0,1] row_mask:0xf bank_mask:0xf bound_ctrl:1
	v_add_f32_dpp v174, v174, v174 quad_perm:[2,3,0,1] row_mask:0xf bank_mask:0xf bound_ctrl:1
	v_add_f32_dpp v241, v241, v241 quad_perm:[2,3,0,1] row_mask:0xf bank_mask:0xf bound_ctrl:1
	v_add_f32_dpp v247, v247, v247 quad_perm:[2,3,0,1] row_mask:0xf bank_mask:0xf bound_ctrl:1
	v_add_f32_dpp v168, v168, v168 row_half_mirror row_mask:0xf bank_mask:0xf bound_ctrl:1
	v_add_f32_dpp v174, v174, v174 row_half_mirror row_mask:0xf bank_mask:0xf bound_ctrl:1
	v_add_f32_dpp v241, v241, v241 row_half_mirror row_mask:0xf bank_mask:0xf bound_ctrl:1
	v_add_f32_dpp v247, v247, v247 row_half_mirror row_mask:0xf bank_mask:0xf bound_ctrl:1
	v_add_f32_dpp v168, v168, v168 row_mirror row_mask:0xf bank_mask:0xf bound_ctrl:1
	v_add_f32_dpp v174, v174, v174 row_mirror row_mask:0xf bank_mask:0xf bound_ctrl:1
	v_add_f32_dpp v241, v241, v241 row_mirror row_mask:0xf bank_mask:0xf bound_ctrl:1
	v_add_f32_dpp v247, v247, v247 row_mirror row_mask:0xf bank_mask:0xf bound_ctrl:1
	v_readlane_b32 s36, v168, 16
	v_readlane_b32 s40, v174, 16
	v_readlane_b32 s44, v241, 16
	v_readlane_b32 s48, v247, 16
	v_readlane_b32 s37, v168, 48
	v_readlane_b32 s41, v174, 48
	v_readlane_b32 s45, v241, 48
	v_readlane_b32 s49, v247, 48
	v_readlane_b32 s38, v168, 0
	v_readlane_b32 s42, v174, 0
	v_readlane_b32 s46, v241, 0
	v_readlane_b32 s50, v247, 0
	v_readlane_b32 s39, v168, 32
	v_readlane_b32 s43, v174, 32
	v_readlane_b32 s47, v241, 32
	v_readlane_b32 s51, v247, 32
	v_mov_b32_e32 v168, s36
	v_mov_b32_e32 v174, s40
	v_mov_b32_e32 v241, s44
	v_mov_b32_e32 v247, s48
	v_mov_b32_e32 v169, s37
	v_mov_b32_e32 v175, s41
	v_mov_b32_e32 v242, s45
	v_mov_b32_e32 v248, s49
	v_add_f32_e32 v168, s38, v168
	v_add_f32_e32 v174, s42, v174
	v_add_f32_e32 v241, s46, v241
	v_add_f32_e32 v247, s50, v247
; __device__ __forceinline__ float bf2f(bf16 x) { return __uint_as_float(((unsigned)x) << 16); }
; __device__ __forceinline__ unsigned f2bf(float f) { return cvt_pk_bf16(f, 0.f) & 0xffffu; }
; #define POST_LD(Y_, V_, G_, R_, C_, t) do { _Pragma("unroll") for (int q = 0; q < 8; ++q) { const size_t o_ = (size_t)((t) + q) * DH; Y_[q] = yp[o_]; V_[q] = vp[o_]; G_[q] = gp[o_]; R_[q] = rp[((t) + q) * 32]; C_[q] = cp[o_]; } } while (0)
; __device__ __forceinline__ void rw_post(Frame& F) {
;     ...
;         POST_LD(y, vv, gg, rk, cc, 0);
;         for (int t0 = 0; t0 < 64; t0 += 8) {
;             float ny[8], nv[8], nr[8], nc[8]; bf16 ng[8];
;             const int tn = t0 + 8 < 64 ? t0 + 8 : t0;
;             POST_LD(ny, nv, ng, nr, nc, tn);
;     ...
;             for (int q = 0; q < 8; ++q) { const int row = rb0 + t0 + q;
;                 const float mean = wsum(y[q]) * (1.f / 64.f); const float dv = y[q] - mean; const float var = wsum(dv * dv) * (1.f / 64.f);
;                 const float yn = dv * (1.f / sqrtf(var + 64e-5f)) * g_ + b_;
;                 OB[(size_t)row * DH + col] = (bf16)f2bf((yn + rk[q] * vv[q]) * bf2f(gg[q])); }
	v_add_f32_e32 v169, s39, v169
	v_add_f32_e32 v175, s43, v175
	v_add_f32_e32 v242, s47, v242
	v_add_f32_e32 v248, s51, v248
	v_add_f32_e32 v168, v168, v169
	v_add_f32_e32 v174, v174, v175
	v_add_f32_e32 v241, v241, v242
	v_add_f32_e32 v247, v247, v248
	v_fmamk_f32 v168, v168, 0x3c800000, v9
	v_fmamk_f32 v174, v174, 0x3c800000, v9
	v_fmamk_f32 v241, v241, 0x3c800000, v9
	v_fmamk_f32 v247, v247, 0x3c800000, v9
	v_readfirstlane_b32 s40, v174
	v_readfirstlane_b32 s44, v241
	v_readfirstlane_b32 s48, v247
	v_writelane_b32 v168, s40, 1
	v_writelane_b32 v168, s44, 2
	v_writelane_b32 v168, s48, 3
	v_mul_f32_e32 v169, 0x4f800000, v168
	v_cmp_gt_f32_e64 s[52:53], s68, v168
	v_mov_b32_e32 v170, v168
	s_nop 1
	v_cndmask_b32_e64 v168, v170, v169, s[52:53]
	v_sqrt_f32_e32 v169, v168
	s_nop 0
	v_add_u32_e32 v170, -1, v169
	v_fma_f32 v171, -v170, v169, v168
	v_cmp_ge_f32_e64 s[60:61], 0, v171
	v_add_u32_e32 v171, 1, v169
	s_nop 1
	v_cndmask_b32_e64 v170, v169, v170, s[60:61]
	v_fma_f32 v169, -v171, v169, v168
	v_cmp_lt_f32_e64 s[60:61], 0, v169
	s_nop 1
	v_cndmask_b32_e64 v169, v170, v171, s[60:61]
	v_mul_f32_e32 v170, 0x37800000, v169
	v_cndmask_b32_e64 v169, v169, v170, s[52:53]
	v_cmp_class_f32_e64 s[60:61], v168, v8
	s_nop 1
	v_cndmask_b32_e64 v168, v169, v168, s[60:61]
	v_div_scale_f32 v169, s[60:61], v168, v168, 1.0
	v_rcp_f32_e32 v170, v169
	s_nop 0
	v_fma_f32 v171, -v169, v170, 1.0
	v_fmac_f32_e32 v170, v171, v170
	v_div_scale_f32 v171, vcc, 1.0, v168, 1.0
	v_mul_f32_e32 v172, v171, v170
	v_fma_f32 v173, -v169, v172, v171
	v_fmac_f32_e32 v172, v173, v170
	v_fma_f32 v169, -v169, v172, v171
	v_div_fmas_f32 v169, v169, v170, v172
	v_div_fixup_f32 v168, v169, v168, 1.0
	s_nop 0
	v_readlane_b32 s37, v168, 0
	v_readlane_b32 s41, v168, 1
	v_readlane_b32 s45, v168, 2
	v_readlane_b32 s49, v168, 3
	v_mul_f32_e32 v100, s37, v100
	v_mul_f32_e32 v105, s41, v105
	v_mul_f32_e32 v110, s45, v110
	v_mul_f32_e32 v115, s49, v115
	v_lshlrev_b32_e32 v103, 16, v103
	v_lshlrev_b32_e32 v108, 16, v108
	v_lshlrev_b32_e32 v113, 16, v113
	v_lshlrev_b32_e32 v118, 16, v118
	v_fma_f32 v100, v6, v100, v7
	v_fma_f32 v105, v6, v105, v7
	v_fma_f32 v110, v6, v110, v7
	v_fma_f32 v115, v6, v115, v7
	v_fmac_f32_e32 v100, s73, v101
	v_fmac_f32_e32 v105, s26, v106
	v_fmac_f32_e32 v110, s27, v111
	v_fmac_f32_e32 v115, s32, v116
	v_mul_f32_e32 v100, v100, v103
	v_mul_f32_e32 v105, v105, v108
	v_mul_f32_e32 v110, v110, v113
	v_mul_f32_e32 v115, v115, v118
	v_cvt_pk_bf16_f32 v169, v100, v100
	v_cvt_pk_bf16_f32 v175, v105, v105
	v_cvt_pk_bf16_f32 v242, v110, v110
	v_cvt_pk_bf16_f32 v248, v115, v115
	global_store_short v2, v169, s[28:29]
	s_add_u32 s28, s28, 0x1000
	s_addc_u32 s29, s29, 0
	global_store_short v2, v175, s[28:29]
	s_add_u32 s28, s28, 0x1000
	s_addc_u32 s29, s29, 0
	global_store_short v2, v242, s[28:29]
	s_add_u32 s28, s28, 0x1000
	s_addc_u32 s29, s29, 0
	global_store_short v2, v248, s[28:29]
	s_add_u32 s28, s28, 0x1000
	s_addc_u32 s29, s29, 0
	s_waitcnt vmcnt(8)
	ds_write_b128 v12, v[120:123] offset:0
	ds_write_b128 v12, v[124:127] offset:1024
	ds_write_b128 v12, v[128:131] offset:16384
	ds_write_b128 v12, v[132:135] offset:17408
	ds_write_b128 v14, v[136:139]
	v_readlane_b32 s69, v159, 0
	v_readlane_b32 s70, v159, 1
	v_readlane_b32 s71, v159, 2
	v_readlane_b32 s72, v159, 3
	v_readlane_b32 s73, v159, 4
	v_readlane_b32 s26, v159, 5
	v_readlane_b32 s27, v159, 6
	v_readlane_b32 s32, v159, 7
	global_load_dwordx4 v[120:123], v11, s[6:7]
	global_load_dwordx4 v[124:127], v11, s[6:7] offset:1024
	global_load_dwordx4 v[128:131], v11, s[8:9]
	global_load_dwordx4 v[132:135], v11, s[8:9] offset:1024
	global_load_dwordx4 v[136:139], v11, s[10:11]
	global_load_dword v159, v158, s[12:13]
	s_add_u32 s6, s6, 0x10000
	s_addc_u32 s7, s7, 0
	s_add_u32 s8, s8, 0x10000
	s_addc_u32 s9, s9, 0
	s_add_u32 s10, s10, 0x8000
	s_addc_u32 s11, s11, 0
	s_add_u32 s12, s12, 0x400
	s_addc_u32 s13, s13, 0
	s_waitcnt lgkmcnt(0)
	s_barrier
	ds_read_b32 v80, v154 offset:0
	ds_read_b32 v81, v154 offset:16384
	ds_read_u16 v83, v156 offset:0
	ds_read_b32 v85, v154 offset:2048
	ds_read_b32 v86, v154 offset:18432
	ds_read_u16 v88, v156 offset:1024
	ds_read_b32 v90, v154 offset:4096
	ds_read_b32 v91, v154 offset:20480
	ds_read_u16 v93, v156 offset:2048
	ds_read_b32 v95, v154 offset:6144
	ds_read_b32 v96, v154 offset:22528
	ds_read_u16 v98, v156 offset:3072
	ds_read_b32 v100, v154 offset:8192
	ds_read_b32 v101, v154 offset:24576
	ds_read_u16 v103, v156 offset:4096
	ds_read_b32 v105, v154 offset:10240
	ds_read_b32 v106, v154 offset:26624
	ds_read_u16 v108, v156 offset:5120
	ds_read_b32 v110, v154 offset:12288
	ds_read_b32 v111, v154 offset:28672
	ds_read_u16 v113, v156 offset:6144
	ds_read_b32 v115, v154 offset:14336
	ds_read_b32 v116, v154 offset:30720
	ds_read_u16 v118, v156 offset:7168
	s_waitcnt lgkmcnt(0)
; __device__ __forceinline__ void rw_post(Frame& F) {
;     ...
;                         y[4 * hf + q] += (a[0] + a[1]) + (a[2] + a[3]); }
;                     asm volatile("s_waitcnt lgkmcnt(0)" ::: "memory"); }
;             }
; #pragma unroll
;             for (int q = 0; q < 8; ++q) { const int row = rb0 + t0 + q;
;                 const float mean = wsum(y[q]) * (1.f / 64.f); const float dv = y[q] - mean; const float var = wsum(dv * dv) * (1.f / 64.f);
;                 const float yn = dv * (1.f / sqrtf(var + 64e-5f)) * g_ + b_;
	v_add_f32_e32 v80, v80, v24
	v_add_f32_e32 v85, v85, v25
	v_add_f32_e32 v90, v90, v26
	v_add_f32_e32 v95, v95, v27
	v_add_f32_dpp v168, v80, v80 quad_perm:[1,0,3,2] row_mask:0xf bank_mask:0xf bound_ctrl:1
	v_add_f32_dpp v174, v85, v85 quad_perm:[1,0,3,2] row_mask:0xf bank_mask:0xf bound_ctrl:1
	v_add_f32_dpp v241, v90, v90 quad_perm:[1,0,3,2] row_mask:0xf bank_mask:0xf bound_ctrl:1
	v_add_f32_dpp v247, v95, v95 quad_perm:[1,0,3,2] row_mask:0xf bank_mask:0xf bound_ctrl:1
	v_add_f32_dpp v168, v168, v168 quad_perm:[2,3,0,1] row_mask:0xf bank_mask:0xf bound_ctrl:1
	v_add_f32_dpp v174, v174, v174 quad_perm:[2,3,0,1] row_mask:0xf bank_mask:0xf bound_ctrl:1
	v_add_f32_dpp v241, v241, v241 quad_perm:[2,3,0,1] row_mask:0xf bank_mask:0xf bound_ctrl:1
	v_add_f32_dpp v247, v247, v247 quad_perm:[2,3,0,1] row_mask:0xf bank_mask:0xf bound_ctrl:1
	v_add_f32_dpp v168, v168, v168 row_half_mirror row_mask:0xf bank_mask:0xf bound_ctrl:1
	v_add_f32_dpp v174, v174, v174 row_half_mirror row_mask:0xf bank_mask:0xf bound_ctrl:1
	v_add_f32_dpp v241, v241, v241 row_half_mirror row_mask:0xf bank_mask:0xf bound_ctrl:1
	v_add_f32_dpp v247, v247, v247 row_half_mirror row_mask:0xf bank_mask:0xf bound_ctrl:1
	v_add_f32_dpp v168, v168, v168 row_mirror row_mask:0xf bank_mask:0xf bound_ctrl:1
	v_add_f32_dpp v174, v174, v174 row_mirror row_mask:0xf bank_mask:0xf bound_ctrl:1
	v_add_f32_dpp v241, v241, v241 row_mirror row_mask:0xf bank_mask:0xf bound_ctrl:1
	v_add_f32_dpp v247, v247, v247 row_mirror row_mask:0xf bank_mask:0xf bound_ctrl:1
	v_readlane_b32 s36, v168, 16
	v_readlane_b32 s40, v174, 16
	v_readlane_b32 s44, v241, 16
	v_readlane_b32 s48, v247, 16
	v_readlane_b32 s37, v168, 48
	v_readlane_b32 s41, v174, 48
	v_readlane_b32 s45, v241, 48
	v_readlane_b32 s49, v247, 48
	v_readlane_b32 s38, v168, 0
	v_readlane_b32 s42, v174, 0
	v_readlane_b32 s46, v241, 0
	v_readlane_b32 s50, v247, 0
	v_readlane_b32 s39, v168, 32
	v_readlane_b32 s43, v174, 32
	v_readlane_b32 s47, v241, 32
	v_readlane_b32 s51, v247, 32
	v_mov_b32_e32 v168, s36
	v_mov_b32_e32 v174, s40
	v_mov_b32_e32 v241, s44
	v_mov_b32_e32 v247, s48
	v_mov_b32_e32 v169, s37
	v_mov_b32_e32 v175, s41
	v_mov_b32_e32 v242, s45
	v_mov_b32_e32 v248, s49
	v_add_f32_e32 v168, s38, v168
	v_add_f32_e32 v174, s42, v174
	v_add_f32_e32 v241, s46, v241
	v_add_f32_e32 v247, s50, v247
	v_add_f32_e32 v169, s39, v169
	v_add_f32_e32 v175, s43, v175
	v_add_f32_e32 v242, s47, v242
	v_add_f32_e32 v248, s51, v248
	v_add_f32_e32 v168, v168, v169
	v_add_f32_e32 v174, v174, v175
	v_add_f32_e32 v241, v241, v242
	v_add_f32_e32 v247, v247, v248
	v_fmamk_f32 v80, v168, 0xbc800000, v80
	v_fmamk_f32 v85, v174, 0xbc800000, v85
	v_fmamk_f32 v90, v241, 0xbc800000, v90
	v_fmamk_f32 v95, v247, 0xbc800000, v95
	v_mul_f32_e32 v168, v80, v80
	v_mul_f32_e32 v174, v85, v85
	v_mul_f32_e32 v241, v90, v90
	v_mul_f32_e32 v247, v95, v95
	v_mov_b32_dpp v168, v168 quad_perm:[1,0,3,2] row_mask:0xf bank_mask:0xf bound_ctrl:1
	v_mov_b32_dpp v174, v174 quad_perm:[1,0,3,2] row_mask:0xf bank_mask:0xf bound_ctrl:1
	v_mov_b32_dpp v241, v241 quad_perm:[1,0,3,2] row_mask:0xf bank_mask:0xf bound_ctrl:1
	v_mov_b32_dpp v247, v247 quad_perm:[1,0,3,2] row_mask:0xf bank_mask:0xf bound_ctrl:1
	v_fmac_f32_e32 v168, v80, v80
	v_fmac_f32_e32 v174, v85, v85
	v_fmac_f32_e32 v241, v90, v90
	v_fmac_f32_e32 v247, v95, v95
	v_add_f32_dpp v168, v168, v168 quad_perm:[2,3,0,1] row_mask:0xf bank_mask:0xf bound_ctrl:1
	v_add_f32_dpp v174, v174, v174 quad_perm:[2,3,0,1] row_mask:0xf bank_mask:0xf bound_ctrl:1
	v_add_f32_dpp v241, v241, v241 quad_perm:[2,3,0,1] row_mask:0xf bank_mask:0xf bound_ctrl:1
	v_add_f32_dpp v247, v247, v247 quad_perm:[2,3,0,1] row_mask:0xf bank_mask:0xf bound_ctrl:1
	v_add_f32_dpp v168, v168, v168 row_half_mirror row_mask:0xf bank_mask:0xf bound_ctrl:1
	v_add_f32_dpp v174, v174, v174 row_half_mirror row_mask:0xf bank_mask:0xf bound_ctrl:1
	v_add_f32_dpp v241, v241, v241 row_half_mirror row_mask:0xf bank_mask:0xf bound_ctrl:1
	v_add_f32_dpp v247, v247, v247 row_half_mirror row_mask:0xf bank_mask:0xf bound_ctrl:1
	v_add_f32_dpp v168, v168, v168 row_mirror row_mask:0xf bank_mask:0xf bound_ctrl:1
	v_add_f32_dpp v174, v174, v174 row_mirror row_mask:0xf bank_mask:0xf bound_ctrl:1
	v_add_f32_dpp v241, v241, v241 row_mirror row_mask:0xf bank_mask:0xf bound_ctrl:1
	v_add_f32_dpp v247, v247, v247 row_mirror row_mask:0xf bank_mask:0xf bound_ctrl:1
	v_readlane_b32 s36, v168, 16
	v_readlane_b32 s40, v174, 16
	v_readlane_b32 s44, v241, 16
	v_readlane_b32 s48, v247, 16
	v_readlane_b32 s37, v168, 48
	v_readlane_b32 s41, v174, 48
	v_readlane_b32 s45, v241, 48
	v_readlane_b32 s49, v247, 48
	v_readlane_b32 s38, v168, 0
	v_readlane_b32 s42, v174, 0
	v_readlane_b32 s46, v241, 0
	v_readlane_b32 s50, v247, 0
	v_readlane_b32 s39, v168, 32
	v_readlane_b32 s43, v174, 32
	v_readlane_b32 s47, v241, 32
	v_readlane_b32 s51, v247, 32
	v_mov_b32_e32 v168, s36
	v_mov_b32_e32 v174, s40
	v_mov_b32_e32 v241, s44
	v_mov_b32_e32 v247, s48
	v_mov_b32_e32 v169, s37
	v_mov_b32_e32 v175, s41
	v_mov_b32_e32 v242, s45
	v_mov_b32_e32 v248, s49
	v_add_f32_e32 v168, s38, v168
	v_add_f32_e32 v174, s42, v174
	v_add_f32_e32 v241, s46, v241
	v_add_f32_e32 v247, s50, v247
	v_add_f32_e32 v169, s39, v169
	v_add_f32_e32 v175, s43, v175
	v_add_f32_e32 v242, s47, v242
	v_add_f32_e32 v248, s51, v248
	v_add_f32_e32 v168, v168, v169
	v_add_f32_e32 v174, v174, v175
	v_add_f32_e32 v241, v241, v242
	v_add_f32_e32 v247, v247, v248
	v_fmamk_f32 v168, v168, 0x3c800000, v9
	v_fmamk_f32 v174, v174, 0x3c800000, v9
	v_fmamk_f32 v241, v241, 0x3c800000, v9
	v_fmamk_f32 v247, v247, 0x3c800000, v9
	v_readfirstlane_b32 s40, v174
	v_readfirstlane_b32 s44, v241
; __device__ __forceinline__ float bf2f(bf16 x) { return __uint_as_float(((unsigned)x) << 16); }
; __device__ __forceinline__ unsigned f2bf(float f) { return cvt_pk_bf16(f, 0.f) & 0xffffu; }
; __device__ __forceinline__ void rw_post(Frame& F) {
;     ...
;             for (int q = 0; q < 8; ++q) { const int row = rb0 + t0 + q;
;                 const float mean = wsum(y[q]) * (1.f / 64.f); const float dv = y[q] - mean; const float var = wsum(dv * dv) * (1.f / 64.f);
;                 const float yn = dv * (1.f / sqrtf(var + 64e-5f)) * g_ + b_;
;                 OB[(size_t)row * DH + col] = (bf16)f2bf((yn + rk[q] * vv[q]) * bf2f(gg[q])); }
	v_readfirstlane_b32 s48, v247
	v_writelane_b32 v168, s40, 1
	v_writelane_b32 v168, s44, 2
	v_writelane_b32 v168, s48, 3
	v_mul_f32_e32 v169, 0x4f800000, v168
	v_cmp_gt_f32_e64 s[52:53], s68, v168
	v_mov_b32_e32 v170, v168
	s_nop 1
	v_cndmask_b32_e64 v168, v170, v169, s[52:53]
	v_sqrt_f32_e32 v169, v168
	s_nop 0
	v_add_u32_e32 v170, -1, v169
	v_fma_f32 v171, -v170, v169, v168
	v_cmp_ge_f32_e64 s[60:61], 0, v171
	v_add_u32_e32 v171, 1, v169
	s_nop 1
	v_cndmask_b32_e64 v170, v169, v170, s[60:61]
	v_fma_f32 v169, -v171, v169, v168
	v_cmp_lt_f32_e64 s[60:61], 0, v169
	s_nop 1
	v_cndmask_b32_e64 v169, v170, v171, s[60:61]
	v_mul_f32_e32 v170, 0x37800000, v169
	v_cndmask_b32_e64 v169, v169, v170, s[52:53]
	v_cmp_class_f32_e64 s[60:61], v168, v8
	s_nop 1
	v_cndmask_b32_e64 v168, v169, v168, s[60:61]
	v_div_scale_f32 v169, s[60:61], v168, v168, 1.0
	v_rcp_f32_e32 v170, v169
	s_nop 0
	v_fma_f32 v171, -v169, v170, 1.0
	v_fmac_f32_e32 v170, v171, v170
	v_div_scale_f32 v171, vcc, 1.0, v168, 1.0
	v_mul_f32_e32 v172, v171, v170
	v_fma_f32 v173, -v169, v172, v171
	v_fmac_f32_e32 v172, v173, v170
	v_fma_f32 v169, -v169, v172, v171
	v_div_fmas_f32 v169, v169, v170, v172
	v_div_fixup_f32 v168, v169, v168, 1.0
	s_nop 0
	v_readlane_b32 s37, v168, 0
	v_readlane_b32 s41, v168, 1
	v_readlane_b32 s45, v168, 2
	v_readlane_b32 s49, v168, 3
	v_mul_f32_e32 v80, s37, v80
	v_mul_f32_e32 v85, s41, v85
	v_mul_f32_e32 v90, s45, v90
	v_mul_f32_e32 v95, s49, v95
	v_lshlrev_b32_e32 v83, 16, v83
	v_lshlrev_b32_e32 v88, 16, v88
	v_lshlrev_b32_e32 v93, 16, v93
	v_lshlrev_b32_e32 v98, 16, v98
	v_fma_f32 v80, v6, v80, v7
	v_fma_f32 v85, v6, v85, v7
	v_fma_f32 v90, v6, v90, v7
	v_fma_f32 v95, v6, v95, v7
	v_fmac_f32_e32 v80, s69, v81
	v_fmac_f32_e32 v85, s70, v86
	v_fmac_f32_e32 v90, s71, v91
	v_fmac_f32_e32 v95, s72, v96
	v_mul_f32_e32 v80, v80, v83
	v_mul_f32_e32 v85, v85, v88
	v_mul_f32_e32 v90, v90, v93
	v_mul_f32_e32 v95, v95, v98
	v_cvt_pk_bf16_f32 v169, v80, v80
	v_cvt_pk_bf16_f32 v175, v85, v85
	v_cvt_pk_bf16_f32 v242, v90, v90
	v_cvt_pk_bf16_f32 v248, v95, v95
	global_store_short v2, v169, s[28:29]
	s_add_u32 s28, s28, 0x1000
	s_addc_u32 s29, s29, 0
	global_store_short v2, v175, s[28:29]
	s_add_u32 s28, s28, 0x1000
	s_addc_u32 s29, s29, 0
	global_store_short v2, v242, s[28:29]
	s_add_u32 s28, s28, 0x1000
	s_addc_u32 s29, s29, 0
	global_store_short v2, v248, s[28:29]
	s_add_u32 s28, s28, 0x1000
	s_addc_u32 s29, s29, 0
	v_add_f32_e32 v100, v100, v40
	v_add_f32_e32 v105, v105, v41
	v_add_f32_e32 v110, v110, v42
	v_add_f32_e32 v115, v115, v43
	v_add_f32_dpp v168, v100, v100 quad_perm:[1,0,3,2] row_mask:0xf bank_mask:0xf bound_ctrl:1
	v_add_f32_dpp v174, v105, v105 quad_perm:[1,0,3,2] row_mask:0xf bank_mask:0xf bound_ctrl:1
	v_add_f32_dpp v241, v110, v110 quad_perm:[1,0,3,2] row_mask:0xf bank_mask:0xf bound_ctrl:1
	v_add_f32_dpp v247, v115, v115 quad_perm:[1,0,3,2] row_mask:0xf bank_mask:0xf bound_ctrl:1
	v_add_f32_dpp v168, v168, v168 quad_perm:[2,3,0,1] row_mask:0xf bank_mask:0xf bound_ctrl:1
	v_add_f32_dpp v174, v174, v174 quad_perm:[2,3,0,1] row_mask:0xf bank_mask:0xf bound_ctrl:1
	v_add_f32_dpp v241, v241, v241 quad_perm:[2,3,0,1] row_mask:0xf bank_mask:0xf bound_ctrl:1
	v_add_f32_dpp v247, v247, v247 quad_perm:[2,3,0,1] row_mask:0xf bank_mask:0xf bound_ctrl:1
	v_add_f32_dpp v168, v168, v168 row_half_mirror row_mask:0xf bank_mask:0xf bound_ctrl:1
	v_add_f32_dpp v174, v174, v174 row_half_mirror row_mask:0xf bank_mask:0xf bound_ctrl:1
	v_add_f32_dpp v241, v241, v241 row_half_mirror row_mask:0xf bank_mask:0xf bound_ctrl:1
	v_add_f32_dpp v247, v247, v247 row_half_mirror row_mask:0xf bank_mask:0xf bound_ctrl:1
	v_add_f32_dpp v168, v168, v168 row_mirror row_mask:0xf bank_mask:0xf bound_ctrl:1
	v_add_f32_dpp v174, v174, v174 row_mirror row_mask:0xf bank_mask:0xf bound_ctrl:1
	v_add_f32_dpp v241, v241, v241 row_mirror row_mask:0xf bank_mask:0xf bound_ctrl:1
	v_add_f32_dpp v247, v247, v247 row_mirror row_mask:0xf bank_mask:0xf bound_ctrl:1
	v_readlane_b32 s36, v168, 16
	v_readlane_b32 s40, v174, 16
	v_readlane_b32 s44, v241, 16
	v_readlane_b32 s48, v247, 16
	v_readlane_b32 s37, v168, 48
	v_readlane_b32 s41, v174, 48
	v_readlane_b32 s45, v241, 48
	v_readlane_b32 s49, v247, 48
	v_readlane_b32 s38, v168, 0
	v_readlane_b32 s42, v174, 0
	v_readlane_b32 s46, v241, 0
	v_readlane_b32 s50, v247, 0
	v_readlane_b32 s39, v168, 32
	v_readlane_b32 s43, v174, 32
	v_readlane_b32 s47, v241, 32
	v_readlane_b32 s51, v247, 32
	v_mov_b32_e32 v168, s36
	v_mov_b32_e32 v174, s40
	v_mov_b32_e32 v241, s44
	v_mov_b32_e32 v247, s48
	v_mov_b32_e32 v169, s37
	v_mov_b32_e32 v175, s41
	v_mov_b32_e32 v242, s45
	v_mov_b32_e32 v248, s49
	v_add_f32_e32 v168, s38, v168
	v_add_f32_e32 v174, s42, v174
	v_add_f32_e32 v241, s46, v241
	v_add_f32_e32 v247, s50, v247
	v_add_f32_e32 v169, s39, v169
	v_add_f32_e32 v175, s43, v175
	v_add_f32_e32 v242, s47, v242
	v_add_f32_e32 v248, s51, v248
	v_add_f32_e32 v168, v168, v169
	v_add_f32_e32 v174, v174, v175
	v_add_f32_e32 v241, v241, v242
	v_add_f32_e32 v247, v247, v248
	v_fmamk_f32 v100, v168, 0xbc800000, v100
	v_fmamk_f32 v105, v174, 0xbc800000, v105
	v_fmamk_f32 v110, v241, 0xbc800000, v110
	v_fmamk_f32 v115, v247, 0xbc800000, v115
	v_mul_f32_e32 v168, v100, v100
	v_mul_f32_e32 v174, v105, v105
	v_mul_f32_e32 v241, v110, v110
	v_mul_f32_e32 v247, v115, v115
	v_mov_b32_dpp v168, v168 quad_perm:[1,0,3,2] row_mask:0xf bank_mask:0xf bound_ctrl:1
	v_mov_b32_dpp v174, v174 quad_perm:[1,0,3,2] row_mask:0xf bank_mask:0xf bound_ctrl:1
	v_mov_b32_dpp v241, v241 quad_perm:[1,0,3,2] row_mask:0xf bank_mask:0xf bound_ctrl:1
	v_mov_b32_dpp v247, v247 quad_perm:[1,0,3,2] row_mask:0xf bank_mask:0xf bound_ctrl:1
; __device__ __forceinline__ float bf2f(bf16 x) { return __uint_as_float(((unsigned)x) << 16); }
; __device__ __forceinline__ unsigned f2bf(float f) { return cvt_pk_bf16(f, 0.f) & 0xffffu; }
; #define POST_LD(Y_, V_, G_, R_, C_, t) do { _Pragma("unroll") for (int q = 0; q < 8; ++q) { const size_t o_ = (size_t)((t) + q) * DH; Y_[q] = yp[o_]; V_[q] = vp[o_]; G_[q] = gp[o_]; R_[q] = rp[((t) + q) * 32]; C_[q] = cp[o_]; } } while (0)
; __device__ __forceinline__ void rw_post(Frame& F) {
;     ...
;         POST_LD(y, vv, gg, rk, cc, 0);
;         for (int t0 = 0; t0 < 64; t0 += 8) {
;             float ny[8], nv[8], nr[8], nc[8]; bf16 ng[8];
;             const int tn = t0 + 8 < 64 ? t0 + 8 : t0;
;             POST_LD(ny, nv, ng, nr, nc, tn);
;     ...
;             for (int q = 0; q < 8; ++q) { const int row = rb0 + t0 + q;
;                 const float mean = wsum(y[q]) * (1.f / 64.f); const float dv = y[q] - mean; const float var = wsum(dv * dv) * (1.f / 64.f);
;                 const float yn = dv * (1.f / sqrtf(var + 64e-5f)) * g_ + b_;
;                 OB[(size_t)row * DH + col] = (bf16)f2bf((yn + rk[q] * vv[q]) * bf2f(gg[q])); }
	v_fmac_f32_e32 v168, v100, v100
	v_fmac_f32_e32 v174, v105, v105
	v_fmac_f32_e32 v241, v110, v110
	v_fmac_f32_e32 v247, v115, v115
	v_add_f32_dpp v168, v168, v168 quad_perm:[2,3,0,1] row_mask:0xf bank_mask:0xf bound_ctrl:1
	v_add_f32_dpp v174, v174, v174 quad_perm:[2,3,0,1] row_mask:0xf bank_mask:0xf bound_ctrl:1
	v_add_f32_dpp v241, v241, v241 quad_perm:[2,3,0,1] row_mask:0xf bank_mask:0xf bound_ctrl:1
	v_add_f32_dpp v247, v247, v247 quad_perm:[2,3,0,1] row_mask:0xf bank_mask:0xf bound_ctrl:1
	v_add_f32_dpp v168, v168, v168 row_half_mirror row_mask:0xf bank_mask:0xf bound_ctrl:1
	v_add_f32_dpp v174, v174, v174 row_half_mirror row_mask:0xf bank_mask:0xf bound_ctrl:1
	v_add_f32_dpp v241, v241, v241 row_half_mirror row_mask:0xf bank_mask:0xf bound_ctrl:1
	v_add_f32_dpp v247, v247, v247 row_half_mirror row_mask:0xf bank_mask:0xf bound_ctrl:1
	v_add_f32_dpp v168, v168, v168 row_mirror row_mask:0xf bank_mask:0xf bound_ctrl:1
	v_add_f32_dpp v174, v174, v174 row_mirror row_mask:0xf bank_mask:0xf bound_ctrl:1
	v_add_f32_dpp v241, v241, v241 row_mirror row_mask:0xf bank_mask:0xf bound_ctrl:1
	v_add_f32_dpp v247, v247, v247 row_mirror row_mask:0xf bank_mask:0xf bound_ctrl:1
	v_readlane_b32 s36, v168, 16
	v_readlane_b32 s40, v174, 16
	v_readlane_b32 s44, v241, 16
	v_readlane_b32 s48, v247, 16
	v_readlane_b32 s37, v168, 48
	v_readlane_b32 s41, v174, 48
	v_readlane_b32 s45, v241, 48
	v_readlane_b32 s49, v247, 48
	v_readlane_b32 s38, v168, 0
	v_readlane_b32 s42, v174, 0
	v_readlane_b32 s46, v241, 0
	v_readlane_b32 s50, v247, 0
	v_readlane_b32 s39, v168, 32
	v_readlane_b32 s43, v174, 32
	v_readlane_b32 s47, v241, 32
	v_readlane_b32 s51, v247, 32
	v_mov_b32_e32 v168, s36
	v_mov_b32_e32 v174, s40
	v_mov_b32_e32 v241, s44
	v_mov_b32_e32 v247, s48
	v_mov_b32_e32 v169, s37
	v_mov_b32_e32 v175, s41
	v_mov_b32_e32 v242, s45
	v_mov_b32_e32 v248, s49
	v_add_f32_e32 v168, s38, v168
	v_add_f32_e32 v174, s42, v174
	v_add_f32_e32 v241, s46, v241
	v_add_f32_e32 v247, s50, v247
	v_add_f32_e32 v169, s39, v169
	v_add_f32_e32 v175, s43, v175
	v_add_f32_e32 v242, s47, v242
	v_add_f32_e32 v248, s51, v248
	v_add_f32_e32 v168, v168, v169
	v_add_f32_e32 v174, v174, v175
	v_add_f32_e32 v241, v241, v242
	v_add_f32_e32 v247, v247, v248
	v_fmamk_f32 v168, v168, 0x3c800000, v9
	v_fmamk_f32 v174, v174, 0x3c800000, v9
	v_fmamk_f32 v241, v241, 0x3c800000, v9
	v_fmamk_f32 v247, v247, 0x3c800000, v9
	v_readfirstlane_b32 s40, v174
	v_readfirstlane_b32 s44, v241
	v_readfirstlane_b32 s48, v247
	v_writelane_b32 v168, s40, 1
	v_writelane_b32 v168, s44, 2
	v_writelane_b32 v168, s48, 3
	v_mul_f32_e32 v169, 0x4f800000, v168
	v_cmp_gt_f32_e64 s[52:53], s68, v168
	v_mov_b32_e32 v170, v168
	s_nop 1
	v_cndmask_b32_e64 v168, v170, v169, s[52:53]
	v_sqrt_f32_e32 v169, v168
	s_nop 0
	v_add_u32_e32 v170, -1, v169
	v_fma_f32 v171, -v170, v169, v168
	v_cmp_ge_f32_e64 s[60:61], 0, v171
	v_add_u32_e32 v171, 1, v169
	s_nop 1
	v_cndmask_b32_e64 v170, v169, v170, s[60:61]
	v_fma_f32 v169, -v171, v169, v168
	v_cmp_lt_f32_e64 s[60:61], 0, v169
	s_nop 1
	v_cndmask_b32_e64 v169, v170, v171, s[60:61]
	v_mul_f32_e32 v170, 0x37800000, v169
	v_cndmask_b32_e64 v169, v169, v170, s[52:53]
	v_cmp_class_f32_e64 s[60:61], v168, v8
	s_nop 1
	v_cndmask_b32_e64 v168, v169, v168, s[60:61]
	v_div_scale_f32 v169, s[60:61], v168, v168, 1.0
	v_rcp_f32_e32 v170, v169
	s_nop 0
	v_fma_f32 v171, -v169, v170, 1.0
	v_fmac_f32_e32 v170, v171, v170
	v_div_scale_f32 v171, vcc, 1.0, v168, 1.0
	v_mul_f32_e32 v172, v171, v170
	v_fma_f32 v173, -v169, v172, v171
	v_fmac_f32_e32 v172, v173, v170
	v_fma_f32 v169, -v169, v172, v171
	v_div_fmas_f32 v169, v169, v170, v172
	v_div_fixup_f32 v168, v169, v168, 1.0
	s_nop 0
	v_readlane_b32 s37, v168, 0
	v_readlane_b32 s41, v168, 1
	v_readlane_b32 s45, v168, 2
	v_readlane_b32 s49, v168, 3
	v_mul_f32_e32 v100, s37, v100
	v_mul_f32_e32 v105, s41, v105
	v_mul_f32_e32 v110, s45, v110
	v_mul_f32_e32 v115, s49, v115
	v_lshlrev_b32_e32 v103, 16, v103
	v_lshlrev_b32_e32 v108, 16, v108
	v_lshlrev_b32_e32 v113, 16, v113
	v_lshlrev_b32_e32 v118, 16, v118
	v_fma_f32 v100, v6, v100, v7
	v_fma_f32 v105, v6, v105, v7
	v_fma_f32 v110, v6, v110, v7
	v_fma_f32 v115, v6, v115, v7
	v_fmac_f32_e32 v100, s73, v101
	v_fmac_f32_e32 v105, s26, v106
	v_fmac_f32_e32 v110, s27, v111
	v_fmac_f32_e32 v115, s32, v116
	v_mul_f32_e32 v100, v100, v103
	v_mul_f32_e32 v105, v105, v108
	v_mul_f32_e32 v110, v110, v113
	v_mul_f32_e32 v115, v115, v118
	v_cvt_pk_bf16_f32 v169, v100, v100
	v_cvt_pk_bf16_f32 v175, v105, v105
	v_cvt_pk_bf16_f32 v242, v110, v110
	v_cvt_pk_bf16_f32 v248, v115, v115
	global_store_short v2, v169, s[28:29]
	s_add_u32 s28, s28, 0x1000
	s_addc_u32 s29, s29, 0
	global_store_short v2, v175, s[28:29]
	s_add_u32 s28, s28, 0x1000
	s_addc_u32 s29, s29, 0
	global_store_short v2, v242, s[28:29]
	s_add_u32 s28, s28, 0x1000
	s_addc_u32 s29, s29, 0
	global_store_short v2, v248, s[28:29]
	s_add_u32 s28, s28, 0x1000
	s_addc_u32 s29, s29, 0
	s_waitcnt vmcnt(8)
	ds_write_b128 v13, v[120:123] offset:0
	ds_write_b128 v13, v[124:127] offset:1024
	ds_write_b128 v13, v[128:131] offset:16384
	ds_write_b128 v13, v[132:135] offset:17408
	ds_write_b128 v15, v[136:139]
	v_readlane_b32 s69, v159, 0
	v_readlane_b32 s70, v159, 1
	v_readlane_b32 s71, v159, 2
	v_readlane_b32 s72, v159, 3
	v_readlane_b32 s73, v159, 4
	v_readlane_b32 s26, v159, 5
	v_readlane_b32 s27, v159, 6
	v_readlane_b32 s32, v159, 7
	global_load_dwordx4 v[120:123], v11, s[6:7]
	global_load_dwordx4 v[124:127], v11, s[6:7] offset:1024
	global_load_dwordx4 v[128:131], v11, s[8:9]
	global_load_dwordx4 v[132:135], v11, s[8:9] offset:1024
	global_load_dwordx4 v[136:139], v11, s[10:11]
	global_load_dword v159, v158, s[12:13]
	s_add_u32 s6, s6, 0x10000
	s_addc_u32 s7, s7, 0
	s_add_u32 s8, s8, 0x10000
	s_addc_u32 s9, s9, 0
	s_add_u32 s10, s10, 0x8000
	s_addc_u32 s11, s11, 0
	s_add_u32 s12, s12, 0x400
	s_addc_u32 s13, s13, 0
	s_waitcnt lgkmcnt(0)
	s_barrier
; __device__ __forceinline__ void rw_post(Frame& F) {
;     ...
;                         y[4 * hf + q] += (a[0] + a[1]) + (a[2] + a[3]); }
;                     asm volatile("s_waitcnt lgkmcnt(0)" ::: "memory"); }
;             }
; #pragma unroll
;             for (int q = 0; q < 8; ++q) { const int row = rb0 + t0 + q;
;                 const float mean = wsum(y[q]) * (1.f / 64.f); const float dv = y[q] - mean; const float var = wsum(dv * dv) * (1.f / 64.f);
	ds_read_b32 v80, v155 offset:0
	ds_read_b32 v81, v155 offset:16384
	ds_read_u16 v83, v157 offset:0
	ds_read_b32 v85, v155 offset:2048
	ds_read_b32 v86, v155 offset:18432
	ds_read_u16 v88, v157 offset:1024
	ds_read_b32 v90, v155 offset:4096
	ds_read_b32 v91, v155 offset:20480
	ds_read_u16 v93, v157 offset:2048
	ds_read_b32 v95, v155 offset:6144
	ds_read_b32 v96, v155 offset:22528
	ds_read_u16 v98, v157 offset:3072
	ds_read_b32 v100, v155 offset:8192
	ds_read_b32 v101, v155 offset:24576
	ds_read_u16 v103, v157 offset:4096
	ds_read_b32 v105, v155 offset:10240
	ds_read_b32 v106, v155 offset:26624
	ds_read_u16 v108, v157 offset:5120
	ds_read_b32 v110, v155 offset:12288
	ds_read_b32 v111, v155 offset:28672
	ds_read_u16 v113, v157 offset:6144
	ds_read_b32 v115, v155 offset:14336
	ds_read_b32 v116, v155 offset:30720
	ds_read_u16 v118, v157 offset:7168
	s_waitcnt lgkmcnt(0)
	v_add_f32_e32 v80, v80, v28
	v_add_f32_e32 v85, v85, v29
	v_add_f32_e32 v90, v90, v30
	v_add_f32_e32 v95, v95, v31
	v_add_f32_dpp v168, v80, v80 quad_perm:[1,0,3,2] row_mask:0xf bank_mask:0xf bound_ctrl:1
	v_add_f32_dpp v174, v85, v85 quad_perm:[1,0,3,2] row_mask:0xf bank_mask:0xf bound_ctrl:1
	v_add_f32_dpp v241, v90, v90 quad_perm:[1,0,3,2] row_mask:0xf bank_mask:0xf bound_ctrl:1
	v_add_f32_dpp v247, v95, v95 quad_perm:[1,0,3,2] row_mask:0xf bank_mask:0xf bound_ctrl:1
	v_add_f32_dpp v168, v168, v168 quad_perm:[2,3,0,1] row_mask:0xf bank_mask:0xf bound_ctrl:1
	v_add_f32_dpp v174, v174, v174 quad_perm:[2,3,0,1] row_mask:0xf bank_mask:0xf bound_ctrl:1
	v_add_f32_dpp v241, v241, v241 quad_perm:[2,3,0,1] row_mask:0xf bank_mask:0xf bound_ctrl:1
	v_add_f32_dpp v247, v247, v247 quad_perm:[2,3,0,1] row_mask:0xf bank_mask:0xf bound_ctrl:1
	v_add_f32_dpp v168, v168, v168 row_half_mirror row_mask:0xf bank_mask:0xf bound_ctrl:1
	v_add_f32_dpp v174, v174, v174 row_half_mirror row_mask:0xf bank_mask:0xf bound_ctrl:1
	v_add_f32_dpp v241, v241, v241 row_half_mirror row_mask:0xf bank_mask:0xf bound_ctrl:1
	v_add_f32_dpp v247, v247, v247 row_half_mirror row_mask:0xf bank_mask:0xf bound_ctrl:1
	v_add_f32_dpp v168, v168, v168 row_mirror row_mask:0xf bank_mask:0xf bound_ctrl:1
	v_add_f32_dpp v174, v174, v174 row_mirror row_mask:0xf bank_mask:0xf bound_ctrl:1
	v_add_f32_dpp v241, v241, v241 row_mirror row_mask:0xf bank_mask:0xf bound_ctrl:1
	v_add_f32_dpp v247, v247, v247 row_mirror row_mask:0xf bank_mask:0xf bound_ctrl:1
	v_readlane_b32 s36, v168, 16
	v_readlane_b32 s40, v174, 16
	v_readlane_b32 s44, v241, 16
	v_readlane_b32 s48, v247, 16
	v_readlane_b32 s37, v168, 48
	v_readlane_b32 s41, v174, 48
	v_readlane_b32 s45, v241, 48
	v_readlane_b32 s49, v247, 48
	v_readlane_b32 s38, v168, 0
	v_readlane_b32 s42, v174, 0
	v_readlane_b32 s46, v241, 0
	v_readlane_b32 s50, v247, 0
	v_readlane_b32 s39, v168, 32
	v_readlane_b32 s43, v174, 32
	v_readlane_b32 s47, v241, 32
	v_readlane_b32 s51, v247, 32
	v_mov_b32_e32 v168, s36
	v_mov_b32_e32 v174, s40
	v_mov_b32_e32 v241, s44
	v_mov_b32_e32 v247, s48
	v_mov_b32_e32 v169, s37
	v_mov_b32_e32 v175, s41
	v_mov_b32_e32 v242, s45
	v_mov_b32_e32 v248, s49
	v_add_f32_e32 v168, s38, v168
	v_add_f32_e32 v174, s42, v174
	v_add_f32_e32 v241, s46, v241
	v_add_f32_e32 v247, s50, v247
	v_add_f32_e32 v169, s39, v169
	v_add_f32_e32 v175, s43, v175
	v_add_f32_e32 v242, s47, v242
	v_add_f32_e32 v248, s51, v248
	v_add_f32_e32 v168, v168, v169
	v_add_f32_e32 v174, v174, v175
	v_add_f32_e32 v241, v241, v242
	v_add_f32_e32 v247, v247, v248
	v_fmamk_f32 v80, v168, 0xbc800000, v80
	v_fmamk_f32 v85, v174, 0xbc800000, v85
	v_fmamk_f32 v90, v241, 0xbc800000, v90
	v_fmamk_f32 v95, v247, 0xbc800000, v95
	v_mul_f32_e32 v168, v80, v80
	v_mul_f32_e32 v174, v85, v85
	v_mul_f32_e32 v241, v90, v90
	v_mul_f32_e32 v247, v95, v95
	v_mov_b32_dpp v168, v168 quad_perm:[1,0,3,2] row_mask:0xf bank_mask:0xf bound_ctrl:1
	v_mov_b32_dpp v174, v174 quad_perm:[1,0,3,2] row_mask:0xf bank_mask:0xf bound_ctrl:1
	v_mov_b32_dpp v241, v241 quad_perm:[1,0,3,2] row_mask:0xf bank_mask:0xf bound_ctrl:1
	v_mov_b32_dpp v247, v247 quad_perm:[1,0,3,2] row_mask:0xf bank_mask:0xf bound_ctrl:1
	v_fmac_f32_e32 v168, v80, v80
	v_fmac_f32_e32 v174, v85, v85
	v_fmac_f32_e32 v241, v90, v90
	v_fmac_f32_e32 v247, v95, v95
	v_add_f32_dpp v168, v168, v168 quad_perm:[2,3,0,1] row_mask:0xf bank_mask:0xf bound_ctrl:1
	v_add_f32_dpp v174, v174, v174 quad_perm:[2,3,0,1] row_mask:0xf bank_mask:0xf bound_ctrl:1
	v_add_f32_dpp v241, v241, v241 quad_perm:[2,3,0,1] row_mask:0xf bank_mask:0xf bound_ctrl:1
	v_add_f32_dpp v247, v247, v247 quad_perm:[2,3,0,1] row_mask:0xf bank_mask:0xf bound_ctrl:1
	v_add_f32_dpp v168, v168, v168 row_half_mirror row_mask:0xf bank_mask:0xf bound_ctrl:1
	v_add_f32_dpp v174, v174, v174 row_half_mirror row_mask:0xf bank_mask:0xf bound_ctrl:1
	v_add_f32_dpp v241, v241, v241 row_half_mirror row_mask:0xf bank_mask:0xf bound_ctrl:1
	v_add_f32_dpp v247, v247, v247 row_half_mirror row_mask:0xf bank_mask:0xf bound_ctrl:1
	v_add_f32_dpp v168, v168, v168 row_mirror row_mask:0xf bank_mask:0xf bound_ctrl:1
	v_add_f32_dpp v174, v174, v174 row_mirror row_mask:0xf bank_mask:0xf bound_ctrl:1
	v_add_f32_dpp v241, v241, v241 row_mirror row_mask:0xf bank_mask:0xf bound_ctrl:1
	v_add_f32_dpp v247, v247, v247 row_mirror row_mask:0xf bank_mask:0xf bound_ctrl:1
	v_readlane_b32 s36, v168, 16
	v_readlane_b32 s40, v174, 16
	v_readlane_b32 s44, v241, 16
	v_readlane_b32 s48, v247, 16
	v_readlane_b32 s37, v168, 48
	v_readlane_b32 s41, v174, 48
	v_readlane_b32 s45, v241, 48
	v_readlane_b32 s49, v247, 48
	v_readlane_b32 s38, v168, 0
	v_readlane_b32 s42, v174, 0
	v_readlane_b32 s46, v241, 0
	v_readlane_b32 s50, v247, 0
	v_readlane_b32 s39, v168, 32
; __device__ __forceinline__ float bf2f(bf16 x) { return __uint_as_float(((unsigned)x) << 16); }
; __device__ __forceinline__ unsigned f2bf(float f) { return cvt_pk_bf16(f, 0.f) & 0xffffu; }
; __device__ __forceinline__ void rw_post(Frame& F) {
;     ...
;             for (int q = 0; q < 8; ++q) { const int row = rb0 + t0 + q;
;                 const float mean = wsum(y[q]) * (1.f / 64.f); const float dv = y[q] - mean; const float var = wsum(dv * dv) * (1.f / 64.f);
;                 const float yn = dv * (1.f / sqrtf(var + 64e-5f)) * g_ + b_;
;                 OB[(size_t)row * DH + col] = (bf16)f2bf((yn + rk[q] * vv[q]) * bf2f(gg[q])); }
	v_readlane_b32 s43, v174, 32
	v_readlane_b32 s47, v241, 32
	v_readlane_b32 s51, v247, 32
	v_mov_b32_e32 v168, s36
	v_mov_b32_e32 v174, s40
	v_mov_b32_e32 v241, s44
	v_mov_b32_e32 v247, s48
	v_mov_b32_e32 v169, s37
	v_mov_b32_e32 v175, s41
	v_mov_b32_e32 v242, s45
	v_mov_b32_e32 v248, s49
	v_add_f32_e32 v168, s38, v168
	v_add_f32_e32 v174, s42, v174
	v_add_f32_e32 v241, s46, v241
	v_add_f32_e32 v247, s50, v247
	v_add_f32_e32 v169, s39, v169
	v_add_f32_e32 v175, s43, v175
	v_add_f32_e32 v242, s47, v242
	v_add_f32_e32 v248, s51, v248
	v_add_f32_e32 v168, v168, v169
	v_add_f32_e32 v174, v174, v175
	v_add_f32_e32 v241, v241, v242
	v_add_f32_e32 v247, v247, v248
	v_fmamk_f32 v168, v168, 0x3c800000, v9
	v_fmamk_f32 v174, v174, 0x3c800000, v9
	v_fmamk_f32 v241, v241, 0x3c800000, v9
	v_fmamk_f32 v247, v247, 0x3c800000, v9
	v_readfirstlane_b32 s40, v174
	v_readfirstlane_b32 s44, v241
	v_readfirstlane_b32 s48, v247
	v_writelane_b32 v168, s40, 1
	v_writelane_b32 v168, s44, 2
	v_writelane_b32 v168, s48, 3
	v_mul_f32_e32 v169, 0x4f800000, v168
	v_cmp_gt_f32_e64 s[52:53], s68, v168
	v_mov_b32_e32 v170, v168
	s_nop 1
	v_cndmask_b32_e64 v168, v170, v169, s[52:53]
	v_sqrt_f32_e32 v169, v168
	s_nop 0
	v_add_u32_e32 v170, -1, v169
	v_fma_f32 v171, -v170, v169, v168
	v_cmp_ge_f32_e64 s[60:61], 0, v171
	v_add_u32_e32 v171, 1, v169
	s_nop 1
	v_cndmask_b32_e64 v170, v169, v170, s[60:61]
	v_fma_f32 v169, -v171, v169, v168
	v_cmp_lt_f32_e64 s[60:61], 0, v169
	s_nop 1
	v_cndmask_b32_e64 v169, v170, v171, s[60:61]
	v_mul_f32_e32 v170, 0x37800000, v169
	v_cndmask_b32_e64 v169, v169, v170, s[52:53]
	v_cmp_class_f32_e64 s[60:61], v168, v8
	s_nop 1
	v_cndmask_b32_e64 v168, v169, v168, s[60:61]
	v_div_scale_f32 v169, s[60:61], v168, v168, 1.0
	v_rcp_f32_e32 v170, v169
	s_nop 0
	v_fma_f32 v171, -v169, v170, 1.0
	v_fmac_f32_e32 v170, v171, v170
	v_div_scale_f32 v171, vcc, 1.0, v168, 1.0
	v_mul_f32_e32 v172, v171, v170
	v_fma_f32 v173, -v169, v172, v171
	v_fmac_f32_e32 v172, v173, v170
	v_fma_f32 v169, -v169, v172, v171
	v_div_fmas_f32 v169, v169, v170, v172
	v_div_fixup_f32 v168, v169, v168, 1.0
	s_nop 0
	v_readlane_b32 s37, v168, 0
	v_readlane_b32 s41, v168, 1
	v_readlane_b32 s45, v168, 2
	v_readlane_b32 s49, v168, 3
	v_mul_f32_e32 v80, s37, v80
	v_mul_f32_e32 v85, s41, v85
	v_mul_f32_e32 v90, s45, v90
	v_mul_f32_e32 v95, s49, v95
	v_lshlrev_b32_e32 v83, 16, v83
	v_lshlrev_b32_e32 v88, 16, v88
	v_lshlrev_b32_e32 v93, 16, v93
	v_lshlrev_b32_e32 v98, 16, v98
	v_fma_f32 v80, v6, v80, v7
	v_fma_f32 v85, v6, v85, v7
	v_fma_f32 v90, v6, v90, v7
	v_fma_f32 v95, v6, v95, v7
	v_fmac_f32_e32 v80, s69, v81
	v_fmac_f32_e32 v85, s70, v86
	v_fmac_f32_e32 v90, s71, v91
	v_fmac_f32_e32 v95, s72, v96
	v_mul_f32_e32 v80, v80, v83
	v_mul_f32_e32 v85, v85, v88
	v_mul_f32_e32 v90, v90, v93
	v_mul_f32_e32 v95, v95, v98
	v_cvt_pk_bf16_f32 v169, v80, v80
	v_cvt_pk_bf16_f32 v175, v85, v85
	v_cvt_pk_bf16_f32 v242, v90, v90
	v_cvt_pk_bf16_f32 v248, v95, v95
	global_store_short v2, v169, s[28:29]
	s_add_u32 s28, s28, 0x1000
	s_addc_u32 s29, s29, 0
	global_store_short v2, v175, s[28:29]
	s_add_u32 s28, s28, 0x1000
	s_addc_u32 s29, s29, 0
	global_store_short v2, v242, s[28:29]
	s_add_u32 s28, s28, 0x1000
	s_addc_u32 s29, s29, 0
	global_store_short v2, v248, s[28:29]
	s_add_u32 s28, s28, 0x1000
	s_addc_u32 s29, s29, 0
	v_add_f32_e32 v100, v100, v44
	v_add_f32_e32 v105, v105, v45
	v_add_f32_e32 v110, v110, v46
	v_add_f32_e32 v115, v115, v47
	v_add_f32_dpp v168, v100, v100 quad_perm:[1,0,3,2] row_mask:0xf bank_mask:0xf bound_ctrl:1
	v_add_f32_dpp v174, v105, v105 quad_perm:[1,0,3,2] row_mask:0xf bank_mask:0xf bound_ctrl:1
	v_add_f32_dpp v241, v110, v110 quad_perm:[1,0,3,2] row_mask:0xf bank_mask:0xf bound_ctrl:1
	v_add_f32_dpp v247, v115, v115 quad_perm:[1,0,3,2] row_mask:0xf bank_mask:0xf bound_ctrl:1
	v_add_f32_dpp v168, v168, v168 quad_perm:[2,3,0,1] row_mask:0xf bank_mask:0xf bound_ctrl:1
	v_add_f32_dpp v174, v174, v174 quad_perm:[2,3,0,1] row_mask:0xf bank_mask:0xf bound_ctrl:1
	v_add_f32_dpp v241, v241, v241 quad_perm:[2,3,0,1] row_mask:0xf bank_mask:0xf bound_ctrl:1
	v_add_f32_dpp v247, v247, v247 quad_perm:[2,3,0,1] row_mask:0xf bank_mask:0xf bound_ctrl:1
	v_add_f32_dpp v168, v168, v168 row_half_mirror row_mask:0xf bank_mask:0xf bound_ctrl:1
	v_add_f32_dpp v174, v174, v174 row_half_mirror row_mask:0xf bank_mask:0xf bound_ctrl:1
	v_add_f32_dpp v241, v241, v241 row_half_mirror row_mask:0xf bank_mask:0xf bound_ctrl:1
	v_add_f32_dpp v247, v247, v247 row_half_mirror row_mask:0xf bank_mask:0xf bound_ctrl:1
	v_add_f32_dpp v168, v168, v168 row_mirror row_mask:0xf bank_mask:0xf bound_ctrl:1
	v_add_f32_dpp v174, v174, v174 row_mirror row_mask:0xf bank_mask:0xf bound_ctrl:1
	v_add_f32_dpp v241, v241, v241 row_mirror row_mask:0xf bank_mask:0xf bound_ctrl:1
	v_add_f32_dpp v247, v247, v247 row_mirror row_mask:0xf bank_mask:0xf bound_ctrl:1
	v_readlane_b32 s36, v168, 16
	v_readlane_b32 s40, v174, 16
	v_readlane_b32 s44, v241, 16
	v_readlane_b32 s48, v247, 16
	v_readlane_b32 s37, v168, 48
	v_readlane_b32 s41, v174, 48
	v_readlane_b32 s45, v241, 48
	v_readlane_b32 s49, v247, 48
	v_readlane_b32 s38, v168, 0
	v_readlane_b32 s42, v174, 0
	v_readlane_b32 s46, v241, 0
	v_readlane_b32 s50, v247, 0
	v_readlane_b32 s39, v168, 32
	v_readlane_b32 s43, v174, 32
	v_readlane_b32 s47, v241, 32
	v_readlane_b32 s51, v247, 32
	v_mov_b32_e32 v168, s36
	v_mov_b32_e32 v174, s40
	v_mov_b32_e32 v241, s44
	v_mov_b32_e32 v247, s48
	v_mov_b32_e32 v169, s37
	v_mov_b32_e32 v175, s41
	v_mov_b32_e32 v242, s45
	v_mov_b32_e32 v248, s49
	v_add_f32_e32 v168, s38, v168
	v_add_f32_e32 v174, s42, v174
	v_add_f32_e32 v241, s46, v241
; __device__ __forceinline__ float bf2f(bf16 x) { return __uint_as_float(((unsigned)x) << 16); }
; __device__ __forceinline__ unsigned f2bf(float f) { return cvt_pk_bf16(f, 0.f) & 0xffffu; }
; #define POST_LD(Y_, V_, G_, R_, C_, t) do { _Pragma("unroll") for (int q = 0; q < 8; ++q) { const size_t o_ = (size_t)((t) + q) * DH; Y_[q] = yp[o_]; V_[q] = vp[o_]; G_[q] = gp[o_]; R_[q] = rp[((t) + q) * 32]; C_[q] = cp[o_]; } } while (0)
; __device__ __forceinline__ void rw_post(Frame& F) {
;     ...
;         POST_LD(y, vv, gg, rk, cc, 0);
;         for (int t0 = 0; t0 < 64; t0 += 8) {
;             float ny[8], nv[8], nr[8], nc[8]; bf16 ng[8];
;             const int tn = t0 + 8 < 64 ? t0 + 8 : t0;
;             POST_LD(ny, nv, ng, nr, nc, tn);
;     ...
;             for (int q = 0; q < 8; ++q) { const int row = rb0 + t0 + q;
;                 const float mean = wsum(y[q]) * (1.f / 64.f); const float dv = y[q] - mean; const float var = wsum(dv * dv) * (1.f / 64.f);
;                 const float yn = dv * (1.f / sqrtf(var + 64e-5f)) * g_ + b_;
;                 OB[(size_t)row * DH + col] = (bf16)f2bf((yn + rk[q] * vv[q]) * bf2f(gg[q])); }
	v_add_f32_e32 v247, s50, v247
	v_add_f32_e32 v169, s39, v169
	v_add_f32_e32 v175, s43, v175
	v_add_f32_e32 v242, s47, v242
	v_add_f32_e32 v248, s51, v248
	v_add_f32_e32 v168, v168, v169
	v_add_f32_e32 v174, v174, v175
	v_add_f32_e32 v241, v241, v242
	v_add_f32_e32 v247, v247, v248
	v_fmamk_f32 v100, v168, 0xbc800000, v100
	v_fmamk_f32 v105, v174, 0xbc800000, v105
	v_fmamk_f32 v110, v241, 0xbc800000, v110
	v_fmamk_f32 v115, v247, 0xbc800000, v115
	v_mul_f32_e32 v168, v100, v100
	v_mul_f32_e32 v174, v105, v105
	v_mul_f32_e32 v241, v110, v110
	v_mul_f32_e32 v247, v115, v115
	v_mov_b32_dpp v168, v168 quad_perm:[1,0,3,2] row_mask:0xf bank_mask:0xf bound_ctrl:1
	v_mov_b32_dpp v174, v174 quad_perm:[1,0,3,2] row_mask:0xf bank_mask:0xf bound_ctrl:1
	v_mov_b32_dpp v241, v241 quad_perm:[1,0,3,2] row_mask:0xf bank_mask:0xf bound_ctrl:1
	v_mov_b32_dpp v247, v247 quad_perm:[1,0,3,2] row_mask:0xf bank_mask:0xf bound_ctrl:1
	v_fmac_f32_e32 v168, v100, v100
	v_fmac_f32_e32 v174, v105, v105
	v_fmac_f32_e32 v241, v110, v110
	v_fmac_f32_e32 v247, v115, v115
	v_add_f32_dpp v168, v168, v168 quad_perm:[2,3,0,1] row_mask:0xf bank_mask:0xf bound_ctrl:1
	v_add_f32_dpp v174, v174, v174 quad_perm:[2,3,0,1] row_mask:0xf bank_mask:0xf bound_ctrl:1
	v_add_f32_dpp v241, v241, v241 quad_perm:[2,3,0,1] row_mask:0xf bank_mask:0xf bound_ctrl:1
	v_add_f32_dpp v247, v247, v247 quad_perm:[2,3,0,1] row_mask:0xf bank_mask:0xf bound_ctrl:1
	v_add_f32_dpp v168, v168, v168 row_half_mirror row_mask:0xf bank_mask:0xf bound_ctrl:1
	v_add_f32_dpp v174, v174, v174 row_half_mirror row_mask:0xf bank_mask:0xf bound_ctrl:1
	v_add_f32_dpp v241, v241, v241 row_half_mirror row_mask:0xf bank_mask:0xf bound_ctrl:1
	v_add_f32_dpp v247, v247, v247 row_half_mirror row_mask:0xf bank_mask:0xf bound_ctrl:1
	v_add_f32_dpp v168, v168, v168 row_mirror row_mask:0xf bank_mask:0xf bound_ctrl:1
	v_add_f32_dpp v174, v174, v174 row_mirror row_mask:0xf bank_mask:0xf bound_ctrl:1
	v_add_f32_dpp v241, v241, v241 row_mirror row_mask:0xf bank_mask:0xf bound_ctrl:1
	v_add_f32_dpp v247, v247, v247 row_mirror row_mask:0xf bank_mask:0xf bound_ctrl:1
	v_readlane_b32 s36, v168, 16
	v_readlane_b32 s40, v174, 16
	v_readlane_b32 s44, v241, 16
	v_readlane_b32 s48, v247, 16
	v_readlane_b32 s37, v168, 48
	v_readlane_b32 s41, v174, 48
	v_readlane_b32 s45, v241, 48
	v_readlane_b32 s49, v247, 48
	v_readlane_b32 s38, v168, 0
	v_readlane_b32 s42, v174, 0
	v_readlane_b32 s46, v241, 0
	v_readlane_b32 s50, v247, 0
	v_readlane_b32 s39, v168, 32
	v_readlane_b32 s43, v174, 32
	v_readlane_b32 s47, v241, 32
	v_readlane_b32 s51, v247, 32
	v_mov_b32_e32 v168, s36
	v_mov_b32_e32 v174, s40
	v_mov_b32_e32 v241, s44
	v_mov_b32_e32 v247, s48
	v_mov_b32_e32 v169, s37
	v_mov_b32_e32 v175, s41
	v_mov_b32_e32 v242, s45
	v_mov_b32_e32 v248, s49
	v_add_f32_e32 v168, s38, v168
	v_add_f32_e32 v174, s42, v174
	v_add_f32_e32 v241, s46, v241
	v_add_f32_e32 v247, s50, v247
	v_add_f32_e32 v169, s39, v169
	v_add_f32_e32 v175, s43, v175
	v_add_f32_e32 v242, s47, v242
	v_add_f32_e32 v248, s51, v248
	v_add_f32_e32 v168, v168, v169
	v_add_f32_e32 v174, v174, v175
	v_add_f32_e32 v241, v241, v242
	v_add_f32_e32 v247, v247, v248
	v_fmamk_f32 v168, v168, 0x3c800000, v9
	v_fmamk_f32 v174, v174, 0x3c800000, v9
	v_fmamk_f32 v241, v241, 0x3c800000, v9
	v_fmamk_f32 v247, v247, 0x3c800000, v9
	v_readfirstlane_b32 s40, v174
	v_readfirstlane_b32 s44, v241
	v_readfirstlane_b32 s48, v247
	v_writelane_b32 v168, s40, 1
	v_writelane_b32 v168, s44, 2
	v_writelane_b32 v168, s48, 3
	v_mul_f32_e32 v169, 0x4f800000, v168
	v_cmp_gt_f32_e64 s[52:53], s68, v168
	v_mov_b32_e32 v170, v168
	s_nop 1
	v_cndmask_b32_e64 v168, v170, v169, s[52:53]
	v_sqrt_f32_e32 v169, v168
	s_nop 0
	v_add_u32_e32 v170, -1, v169
	v_fma_f32 v171, -v170, v169, v168
	v_cmp_ge_f32_e64 s[60:61], 0, v171
	v_add_u32_e32 v171, 1, v169
	s_nop 1
	v_cndmask_b32_e64 v170, v169, v170, s[60:61]
	v_fma_f32 v169, -v171, v169, v168
	v_cmp_lt_f32_e64 s[60:61], 0, v169
	s_nop 1
	v_cndmask_b32_e64 v169, v170, v171, s[60:61]
	v_mul_f32_e32 v170, 0x37800000, v169
	v_cndmask_b32_e64 v169, v169, v170, s[52:53]
	v_cmp_class_f32_e64 s[60:61], v168, v8
	s_nop 1
	v_cndmask_b32_e64 v168, v169, v168, s[60:61]
	v_div_scale_f32 v169, s[60:61], v168, v168, 1.0
	v_rcp_f32_e32 v170, v169
	s_nop 0
	v_fma_f32 v171, -v169, v170, 1.0
	v_fmac_f32_e32 v170, v171, v170
	v_div_scale_f32 v171, vcc, 1.0, v168, 1.0
	v_mul_f32_e32 v172, v171, v170
	v_fma_f32 v173, -v169, v172, v171
	v_fmac_f32_e32 v172, v173, v170
	v_fma_f32 v169, -v169, v172, v171
	v_div_fmas_f32 v169, v169, v170, v172
	v_div_fixup_f32 v168, v169, v168, 1.0
	s_nop 0
	v_readlane_b32 s37, v168, 0
	v_readlane_b32 s41, v168, 1
	v_readlane_b32 s45, v168, 2
	v_readlane_b32 s49, v168, 3
	v_mul_f32_e32 v100, s37, v100
	v_mul_f32_e32 v105, s41, v105
	v_mul_f32_e32 v110, s45, v110
	v_mul_f32_e32 v115, s49, v115
	v_lshlrev_b32_e32 v103, 16, v103
	v_lshlrev_b32_e32 v108, 16, v108
	v_lshlrev_b32_e32 v113, 16, v113
	v_lshlrev_b32_e32 v118, 16, v118
	v_fma_f32 v100, v6, v100, v7
	v_fma_f32 v105, v6, v105, v7
	v_fma_f32 v110, v6, v110, v7
	v_fma_f32 v115, v6, v115, v7
	v_fmac_f32_e32 v100, s73, v101
	v_fmac_f32_e32 v105, s26, v106
	v_fmac_f32_e32 v110, s27, v111
	v_fmac_f32_e32 v115, s32, v116
	v_mul_f32_e32 v100, v100, v103
	v_mul_f32_e32 v105, v105, v108
	v_mul_f32_e32 v110, v110, v113
	v_mul_f32_e32 v115, v115, v118
	v_cvt_pk_bf16_f32 v169, v100, v100
	v_cvt_pk_bf16_f32 v175, v105, v105
	v_cvt_pk_bf16_f32 v242, v110, v110
	v_cvt_pk_bf16_f32 v248, v115, v115
	global_store_short v2, v169, s[28:29]
	s_add_u32 s28, s28, 0x1000
	s_addc_u32 s29, s29, 0
	global_store_short v2, v175, s[28:29]
	s_add_u32 s28, s28, 0x1000
	s_addc_u32 s29, s29, 0
	global_store_short v2, v242, s[28:29]
	s_add_u32 s28, s28, 0x1000
	s_addc_u32 s29, s29, 0
	global_store_short v2, v248, s[28:29]
	s_add_u32 s28, s28, 0x1000
	s_addc_u32 s29, s29, 0
	s_waitcnt vmcnt(8)
	ds_write_b128 v12, v[120:123] offset:0
	ds_write_b128 v12, v[124:127] offset:1024
	ds_write_b128 v12, v[128:131] offset:16384
	ds_write_b128 v12, v[132:135] offset:17408
	ds_write_b128 v14, v[136:139]
	v_readlane_b32 s69, v159, 0
	v_readlane_b32 s70, v159, 1
	v_readlane_b32 s71, v159, 2
	v_readlane_b32 s72, v159, 3
	v_readlane_b32 s73, v159, 4
	v_readlane_b32 s26, v159, 5
	v_readlane_b32 s27, v159, 6
	v_readlane_b32 s32, v159, 7
	global_load_dwordx4 v[120:123], v11, s[6:7]
	global_load_dwordx4 v[124:127], v11, s[6:7] offset:1024
	global_load_dwordx4 v[128:131], v11, s[8:9]
	global_load_dwordx4 v[132:135], v11, s[8:9] offset:1024
	global_load_dwordx4 v[136:139], v11, s[10:11]
	global_load_dword v159, v158, s[12:13]
	s_add_u32 s6, s6, 0x10000
	s_addc_u32 s7, s7, 0
	s_add_u32 s8, s8, 0x10000
	s_addc_u32 s9, s9, 0
	s_add_u32 s10, s10, 0x8000
	s_addc_u32 s11, s11, 0
	s_add_u32 s12, s12, 0x400
	s_addc_u32 s13, s13, 0
	s_waitcnt lgkmcnt(0)
	s_barrier
; __device__ __forceinline__ void rw_post(Frame& F) {
;     ...
;                         y[4 * hf + q] += (a[0] + a[1]) + (a[2] + a[3]); }
;                     asm volatile("s_waitcnt lgkmcnt(0)" ::: "memory"); }
;             }
; #pragma unroll
;             for (int q = 0; q < 8; ++q) { const int row = rb0 + t0 + q;
;                 const float mean = wsum(y[q]) * (1.f / 64.f); const float dv = y[q] - mean; const float var = wsum(dv * dv) * (1.f / 64.f);
	ds_read_b32 v80, v154 offset:0
	ds_read_b32 v81, v154 offset:16384
	ds_read_u16 v83, v156 offset:0
	ds_read_b32 v85, v154 offset:2048
	ds_read_b32 v86, v154 offset:18432
	ds_read_u16 v88, v156 offset:1024
	ds_read_b32 v90, v154 offset:4096
	ds_read_b32 v91, v154 offset:20480
	ds_read_u16 v93, v156 offset:2048
	ds_read_b32 v95, v154 offset:6144
	ds_read_b32 v96, v154 offset:22528
	ds_read_u16 v98, v156 offset:3072
	ds_read_b32 v100, v154 offset:8192
	ds_read_b32 v101, v154 offset:24576
	ds_read_u16 v103, v156 offset:4096
	ds_read_b32 v105, v154 offset:10240
	ds_read_b32 v106, v154 offset:26624
	ds_read_u16 v108, v156 offset:5120
	ds_read_b32 v110, v154 offset:12288
	ds_read_b32 v111, v154 offset:28672
	ds_read_u16 v113, v156 offset:6144
	ds_read_b32 v115, v154 offset:14336
	ds_read_b32 v116, v154 offset:30720
	ds_read_u16 v118, v156 offset:7168
	s_waitcnt lgkmcnt(0)
	v_add_f32_e32 v80, v80, v48
	v_add_f32_e32 v85, v85, v49
	v_add_f32_e32 v90, v90, v50
	v_add_f32_e32 v95, v95, v51
	v_add_f32_dpp v168, v80, v80 quad_perm:[1,0,3,2] row_mask:0xf bank_mask:0xf bound_ctrl:1
	v_add_f32_dpp v174, v85, v85 quad_perm:[1,0,3,2] row_mask:0xf bank_mask:0xf bound_ctrl:1
	v_add_f32_dpp v241, v90, v90 quad_perm:[1,0,3,2] row_mask:0xf bank_mask:0xf bound_ctrl:1
	v_add_f32_dpp v247, v95, v95 quad_perm:[1,0,3,2] row_mask:0xf bank_mask:0xf bound_ctrl:1
	v_add_f32_dpp v168, v168, v168 quad_perm:[2,3,0,1] row_mask:0xf bank_mask:0xf bound_ctrl:1
	v_add_f32_dpp v174, v174, v174 quad_perm:[2,3,0,1] row_mask:0xf bank_mask:0xf bound_ctrl:1
	v_add_f32_dpp v241, v241, v241 quad_perm:[2,3,0,1] row_mask:0xf bank_mask:0xf bound_ctrl:1
	v_add_f32_dpp v247, v247, v247 quad_perm:[2,3,0,1] row_mask:0xf bank_mask:0xf bound_ctrl:1
	v_add_f32_dpp v168, v168, v168 row_half_mirror row_mask:0xf bank_mask:0xf bound_ctrl:1
	v_add_f32_dpp v174, v174, v174 row_half_mirror row_mask:0xf bank_mask:0xf bound_ctrl:1
	v_add_f32_dpp v241, v241, v241 row_half_mirror row_mask:0xf bank_mask:0xf bound_ctrl:1
	v_add_f32_dpp v247, v247, v247 row_half_mirror row_mask:0xf bank_mask:0xf bound_ctrl:1
	v_add_f32_dpp v168, v168, v168 row_mirror row_mask:0xf bank_mask:0xf bound_ctrl:1
	v_add_f32_dpp v174, v174, v174 row_mirror row_mask:0xf bank_mask:0xf bound_ctrl:1
	v_add_f32_dpp v241, v241, v241 row_mirror row_mask:0xf bank_mask:0xf bound_ctrl:1
	v_add_f32_dpp v247, v247, v247 row_mirror row_mask:0xf bank_mask:0xf bound_ctrl:1
	v_readlane_b32 s36, v168, 16
	v_readlane_b32 s40, v174, 16
	v_readlane_b32 s44, v241, 16
	v_readlane_b32 s48, v247, 16
	v_readlane_b32 s37, v168, 48
	v_readlane_b32 s41, v174, 48
	v_readlane_b32 s45, v241, 48
	v_readlane_b32 s49, v247, 48
	v_readlane_b32 s38, v168, 0
	v_readlane_b32 s42, v174, 0
	v_readlane_b32 s46, v241, 0
	v_readlane_b32 s50, v247, 0
	v_readlane_b32 s39, v168, 32
	v_readlane_b32 s43, v174, 32
	v_readlane_b32 s47, v241, 32
	v_readlane_b32 s51, v247, 32
	v_mov_b32_e32 v168, s36
	v_mov_b32_e32 v174, s40
	v_mov_b32_e32 v241, s44
	v_mov_b32_e32 v247, s48
	v_mov_b32_e32 v169, s37
	v_mov_b32_e32 v175, s41
	v_mov_b32_e32 v242, s45
	v_mov_b32_e32 v248, s49
	v_add_f32_e32 v168, s38, v168
	v_add_f32_e32 v174, s42, v174
	v_add_f32_e32 v241, s46, v241
	v_add_f32_e32 v247, s50, v247
	v_add_f32_e32 v169, s39, v169
	v_add_f32_e32 v175, s43, v175
	v_add_f32_e32 v242, s47, v242
	v_add_f32_e32 v248, s51, v248
	v_add_f32_e32 v168, v168, v169
	v_add_f32_e32 v174, v174, v175
	v_add_f32_e32 v241, v241, v242
	v_add_f32_e32 v247, v247, v248
	v_fmamk_f32 v80, v168, 0xbc800000, v80
	v_fmamk_f32 v85, v174, 0xbc800000, v85
	v_fmamk_f32 v90, v241, 0xbc800000, v90
	v_fmamk_f32 v95, v247, 0xbc800000, v95
	v_mul_f32_e32 v168, v80, v80
	v_mul_f32_e32 v174, v85, v85
	v_mul_f32_e32 v241, v90, v90
	v_mul_f32_e32 v247, v95, v95
	v_mov_b32_dpp v168, v168 quad_perm:[1,0,3,2] row_mask:0xf bank_mask:0xf bound_ctrl:1
	v_mov_b32_dpp v174, v174 quad_perm:[1,0,3,2] row_mask:0xf bank_mask:0xf bound_ctrl:1
	v_mov_b32_dpp v241, v241 quad_perm:[1,0,3,2] row_mask:0xf bank_mask:0xf bound_ctrl:1
	v_mov_b32_dpp v247, v247 quad_perm:[1,0,3,2] row_mask:0xf bank_mask:0xf bound_ctrl:1
	v_fmac_f32_e32 v168, v80, v80
	v_fmac_f32_e32 v174, v85, v85
	v_fmac_f32_e32 v241, v90, v90
	v_fmac_f32_e32 v247, v95, v95
	v_add_f32_dpp v168, v168, v168 quad_perm:[2,3,0,1] row_mask:0xf bank_mask:0xf bound_ctrl:1
	v_add_f32_dpp v174, v174, v174 quad_perm:[2,3,0,1] row_mask:0xf bank_mask:0xf bound_ctrl:1
	v_add_f32_dpp v241, v241, v241 quad_perm:[2,3,0,1] row_mask:0xf bank_mask:0xf bound_ctrl:1
	v_add_f32_dpp v247, v247, v247 quad_perm:[2,3,0,1] row_mask:0xf bank_mask:0xf bound_ctrl:1
	v_add_f32_dpp v168, v168, v168 row_half_mirror row_mask:0xf bank_mask:0xf bound_ctrl:1
	v_add_f32_dpp v174, v174, v174 row_half_mirror row_mask:0xf bank_mask:0xf bound_ctrl:1
	v_add_f32_dpp v241, v241, v241 row_half_mirror row_mask:0xf bank_mask:0xf bound_ctrl:1
	v_add_f32_dpp v247, v247, v247 row_half_mirror row_mask:0xf bank_mask:0xf bound_ctrl:1
	v_add_f32_dpp v168, v168, v168 row_mirror row_mask:0xf bank_mask:0xf bound_ctrl:1
	v_add_f32_dpp v174, v174, v174 row_mirror row_mask:0xf bank_mask:0xf bound_ctrl:1
	v_add_f32_dpp v241, v241, v241 row_mirror row_mask:0xf bank_mask:0xf bound_ctrl:1
	v_add_f32_dpp v247, v247, v247 row_mirror row_mask:0xf bank_mask:0xf bound_ctrl:1
	v_readlane_b32 s36, v168, 16
	v_readlane_b32 s40, v174, 16
	v_readlane_b32 s44, v241, 16
	v_readlane_b32 s48, v247, 16
	v_readlane_b32 s37, v168, 48
	v_readlane_b32 s41, v174, 48
	v_readlane_b32 s45, v241, 48
	v_readlane_b32 s49, v247, 48
	v_readlane_b32 s38, v168, 0
	v_readlane_b32 s42, v174, 0
	v_readlane_b32 s46, v241, 0
	v_readlane_b32 s50, v247, 0
	v_readlane_b32 s39, v168, 32
; __device__ __forceinline__ float bf2f(bf16 x) { return __uint_as_float(((unsigned)x) << 16); }
; __device__ __forceinline__ unsigned f2bf(float f) { return cvt_pk_bf16(f, 0.f) & 0xffffu; }
; __device__ __forceinline__ void rw_post(Frame& F) {
;     ...
;             for (int q = 0; q < 8; ++q) { const int row = rb0 + t0 + q;
;                 const float mean = wsum(y[q]) * (1.f / 64.f); const float dv = y[q] - mean; const float var = wsum(dv * dv) * (1.f / 64.f);
;                 const float yn = dv * (1.f / sqrtf(var + 64e-5f)) * g_ + b_;
;                 OB[(size_t)row * DH + col] = (bf16)f2bf((yn + rk[q] * vv[q]) * bf2f(gg[q])); }
	v_readlane_b32 s43, v174, 32
	v_readlane_b32 s47, v241, 32
	v_readlane_b32 s51, v247, 32
	v_mov_b32_e32 v168, s36
	v_mov_b32_e32 v174, s40
	v_mov_b32_e32 v241, s44
	v_mov_b32_e32 v247, s48
	v_mov_b32_e32 v169, s37
	v_mov_b32_e32 v175, s41
	v_mov_b32_e32 v242, s45
	v_mov_b32_e32 v248, s49
	v_add_f32_e32 v168, s38, v168
	v_add_f32_e32 v174, s42, v174
	v_add_f32_e32 v241, s46, v241
	v_add_f32_e32 v247, s50, v247
	v_add_f32_e32 v169, s39, v169
	v_add_f32_e32 v175, s43, v175
	v_add_f32_e32 v242, s47, v242
	v_add_f32_e32 v248, s51, v248
	v_add_f32_e32 v168, v168, v169
	v_add_f32_e32 v174, v174, v175
	v_add_f32_e32 v241, v241, v242
	v_add_f32_e32 v247, v247, v248
	v_fmamk_f32 v168, v168, 0x3c800000, v9
	v_fmamk_f32 v174, v174, 0x3c800000, v9
	v_fmamk_f32 v241, v241, 0x3c800000, v9
	v_fmamk_f32 v247, v247, 0x3c800000, v9
	v_readfirstlane_b32 s40, v174
	v_readfirstlane_b32 s44, v241
	v_readfirstlane_b32 s48, v247
	v_writelane_b32 v168, s40, 1
	v_writelane_b32 v168, s44, 2
	v_writelane_b32 v168, s48, 3
	v_mul_f32_e32 v169, 0x4f800000, v168
	v_cmp_gt_f32_e64 s[52:53], s68, v168
	v_mov_b32_e32 v170, v168
	s_nop 1
	v_cndmask_b32_e64 v168, v170, v169, s[52:53]
	v_sqrt_f32_e32 v169, v168
	s_nop 0
	v_add_u32_e32 v170, -1, v169
	v_fma_f32 v171, -v170, v169, v168
	v_cmp_ge_f32_e64 s[60:61], 0, v171
	v_add_u32_e32 v171, 1, v169
	s_nop 1
	v_cndmask_b32_e64 v170, v169, v170, s[60:61]
	v_fma_f32 v169, -v171, v169, v168
	v_cmp_lt_f32_e64 s[60:61], 0, v169
	s_nop 1
	v_cndmask_b32_e64 v169, v170, v171, s[60:61]
	v_mul_f32_e32 v170, 0x37800000, v169
	v_cndmask_b32_e64 v169, v169, v170, s[52:53]
	v_cmp_class_f32_e64 s[60:61], v168, v8
	s_nop 1
	v_cndmask_b32_e64 v168, v169, v168, s[60:61]
	v_div_scale_f32 v169, s[60:61], v168, v168, 1.0
	v_rcp_f32_e32 v170, v169
	s_nop 0
	v_fma_f32 v171, -v169, v170, 1.0
	v_fmac_f32_e32 v170, v171, v170
	v_div_scale_f32 v171, vcc, 1.0, v168, 1.0
	v_mul_f32_e32 v172, v171, v170
	v_fma_f32 v173, -v169, v172, v171
	v_fmac_f32_e32 v172, v173, v170
	v_fma_f32 v169, -v169, v172, v171
	v_div_fmas_f32 v169, v169, v170, v172
	v_div_fixup_f32 v168, v169, v168, 1.0
	s_nop 0
	v_readlane_b32 s37, v168, 0
	v_readlane_b32 s41, v168, 1
	v_readlane_b32 s45, v168, 2
	v_readlane_b32 s49, v168, 3
	v_mul_f32_e32 v80, s37, v80
	v_mul_f32_e32 v85, s41, v85
	v_mul_f32_e32 v90, s45, v90
	v_mul_f32_e32 v95, s49, v95
	v_lshlrev_b32_e32 v83, 16, v83
	v_lshlrev_b32_e32 v88, 16, v88
	v_lshlrev_b32_e32 v93, 16, v93
	v_lshlrev_b32_e32 v98, 16, v98
	v_fma_f32 v80, v6, v80, v7
	v_fma_f32 v85, v6, v85, v7
	v_fma_f32 v90, v6, v90, v7
	v_fma_f32 v95, v6, v95, v7
	v_fmac_f32_e32 v80, s69, v81
	v_fmac_f32_e32 v85, s70, v86
	v_fmac_f32_e32 v90, s71, v91
	v_fmac_f32_e32 v95, s72, v96
	v_mul_f32_e32 v80, v80, v83
	v_mul_f32_e32 v85, v85, v88
	v_mul_f32_e32 v90, v90, v93
	v_mul_f32_e32 v95, v95, v98
	v_cvt_pk_bf16_f32 v169, v80, v80
	v_cvt_pk_bf16_f32 v175, v85, v85
	v_cvt_pk_bf16_f32 v242, v90, v90
	v_cvt_pk_bf16_f32 v248, v95, v95
	global_store_short v2, v169, s[28:29]
	s_add_u32 s28, s28, 0x1000
	s_addc_u32 s29, s29, 0
	global_store_short v2, v175, s[28:29]
	s_add_u32 s28, s28, 0x1000
	s_addc_u32 s29, s29, 0
	global_store_short v2, v242, s[28:29]
	s_add_u32 s28, s28, 0x1000
	s_addc_u32 s29, s29, 0
	global_store_short v2, v248, s[28:29]
	s_add_u32 s28, s28, 0x1000
	s_addc_u32 s29, s29, 0
	v_add_f32_e32 v100, v100, v64
	v_add_f32_e32 v105, v105, v65
	v_add_f32_e32 v110, v110, v66
	v_add_f32_e32 v115, v115, v67
	v_add_f32_dpp v168, v100, v100 quad_perm:[1,0,3,2] row_mask:0xf bank_mask:0xf bound_ctrl:1
	v_add_f32_dpp v174, v105, v105 quad_perm:[1,0,3,2] row_mask:0xf bank_mask:0xf bound_ctrl:1
	v_add_f32_dpp v241, v110, v110 quad_perm:[1,0,3,2] row_mask:0xf bank_mask:0xf bound_ctrl:1
	v_add_f32_dpp v247, v115, v115 quad_perm:[1,0,3,2] row_mask:0xf bank_mask:0xf bound_ctrl:1
	v_add_f32_dpp v168, v168, v168 quad_perm:[2,3,0,1] row_mask:0xf bank_mask:0xf bound_ctrl:1
	v_add_f32_dpp v174, v174, v174 quad_perm:[2,3,0,1] row_mask:0xf bank_mask:0xf bound_ctrl:1
	v_add_f32_dpp v241, v241, v241 quad_perm:[2,3,0,1] row_mask:0xf bank_mask:0xf bound_ctrl:1
	v_add_f32_dpp v247, v247, v247 quad_perm:[2,3,0,1] row_mask:0xf bank_mask:0xf bound_ctrl:1
	v_add_f32_dpp v168, v168, v168 row_half_mirror row_mask:0xf bank_mask:0xf bound_ctrl:1
	v_add_f32_dpp v174, v174, v174 row_half_mirror row_mask:0xf bank_mask:0xf bound_ctrl:1
	v_add_f32_dpp v241, v241, v241 row_half_mirror row_mask:0xf bank_mask:0xf bound_ctrl:1
	v_add_f32_dpp v247, v247, v247 row_half_mirror row_mask:0xf bank_mask:0xf bound_ctrl:1
	v_add_f32_dpp v168, v168, v168 row_mirror row_mask:0xf bank_mask:0xf bound_ctrl:1
	v_add_f32_dpp v174, v174, v174 row_mirror row_mask:0xf bank_mask:0xf bound_ctrl:1
	v_add_f32_dpp v241, v241, v241 row_mirror row_mask:0xf bank_mask:0xf bound_ctrl:1
	v_add_f32_dpp v247, v247, v247 row_mirror row_mask:0xf bank_mask:0xf bound_ctrl:1
	v_readlane_b32 s36, v168, 16
	v_readlane_b32 s40, v174, 16
	v_readlane_b32 s44, v241, 16
	v_readlane_b32 s48, v247, 16
	v_readlane_b32 s37, v168, 48
	v_readlane_b32 s41, v174, 48
	v_readlane_b32 s45, v241, 48
	v_readlane_b32 s49, v247, 48
	v_readlane_b32 s38, v168, 0
	v_readlane_b32 s42, v174, 0
	v_readlane_b32 s46, v241, 0
	v_readlane_b32 s50, v247, 0
	v_readlane_b32 s39, v168, 32
	v_readlane_b32 s43, v174, 32
	v_readlane_b32 s47, v241, 32
	v_readlane_b32 s51, v247, 32
	v_mov_b32_e32 v168, s36
	v_mov_b32_e32 v174, s40
	v_mov_b32_e32 v241, s44
	v_mov_b32_e32 v247, s48
	v_mov_b32_e32 v169, s37
	v_mov_b32_e32 v175, s41
	v_mov_b32_e32 v242, s45
	v_mov_b32_e32 v248, s49
	v_add_f32_e32 v168, s38, v168
	v_add_f32_e32 v174, s42, v174
	v_add_f32_e32 v241, s46, v241
; __device__ __forceinline__ float bf2f(bf16 x) { return __uint_as_float(((unsigned)x) << 16); }
; __device__ __forceinline__ unsigned f2bf(float f) { return cvt_pk_bf16(f, 0.f) & 0xffffu; }
; #define POST_LD(Y_, V_, G_, R_, C_, t) do { _Pragma("unroll") for (int q = 0; q < 8; ++q) { const size_t o_ = (size_t)((t) + q) * DH; Y_[q] = yp[o_]; V_[q] = vp[o_]; G_[q] = gp[o_]; R_[q] = rp[((t) + q) * 32]; C_[q] = cp[o_]; } } while (0)
; __device__ __forceinline__ void rw_post(Frame& F) {
;     ...
;         POST_LD(y, vv, gg, rk, cc, 0);
;         for (int t0 = 0; t0 < 64; t0 += 8) {
;             float ny[8], nv[8], nr[8], nc[8]; bf16 ng[8];
;             const int tn = t0 + 8 < 64 ? t0 + 8 : t0;
;             POST_LD(ny, nv, ng, nr, nc, tn);
;     ...
;             for (int q = 0; q < 8; ++q) { const int row = rb0 + t0 + q;
;                 const float mean = wsum(y[q]) * (1.f / 64.f); const float dv = y[q] - mean; const float var = wsum(dv * dv) * (1.f / 64.f);
;                 const float yn = dv * (1.f / sqrtf(var + 64e-5f)) * g_ + b_;
;                 OB[(size_t)row * DH + col] = (bf16)f2bf((yn + rk[q] * vv[q]) * bf2f(gg[q])); }
	v_add_f32_e32 v247, s50, v247
	v_add_f32_e32 v169, s39, v169
	v_add_f32_e32 v175, s43, v175
	v_add_f32_e32 v242, s47, v242
	v_add_f32_e32 v248, s51, v248
	v_add_f32_e32 v168, v168, v169
	v_add_f32_e32 v174, v174, v175
	v_add_f32_e32 v241, v241, v242
	v_add_f32_e32 v247, v247, v248
	v_fmamk_f32 v100, v168, 0xbc800000, v100
	v_fmamk_f32 v105, v174, 0xbc800000, v105
	v_fmamk_f32 v110, v241, 0xbc800000, v110
	v_fmamk_f32 v115, v247, 0xbc800000, v115
	v_mul_f32_e32 v168, v100, v100
	v_mul_f32_e32 v174, v105, v105
	v_mul_f32_e32 v241, v110, v110
	v_mul_f32_e32 v247, v115, v115
	v_mov_b32_dpp v168, v168 quad_perm:[1,0,3,2] row_mask:0xf bank_mask:0xf bound_ctrl:1
	v_mov_b32_dpp v174, v174 quad_perm:[1,0,3,2] row_mask:0xf bank_mask:0xf bound_ctrl:1
	v_mov_b32_dpp v241, v241 quad_perm:[1,0,3,2] row_mask:0xf bank_mask:0xf bound_ctrl:1
	v_mov_b32_dpp v247, v247 quad_perm:[1,0,3,2] row_mask:0xf bank_mask:0xf bound_ctrl:1
	v_fmac_f32_e32 v168, v100, v100
	v_fmac_f32_e32 v174, v105, v105
	v_fmac_f32_e32 v241, v110, v110
	v_fmac_f32_e32 v247, v115, v115
	v_add_f32_dpp v168, v168, v168 quad_perm:[2,3,0,1] row_mask:0xf bank_mask:0xf bound_ctrl:1
	v_add_f32_dpp v174, v174, v174 quad_perm:[2,3,0,1] row_mask:0xf bank_mask:0xf bound_ctrl:1
	v_add_f32_dpp v241, v241, v241 quad_perm:[2,3,0,1] row_mask:0xf bank_mask:0xf bound_ctrl:1
	v_add_f32_dpp v247, v247, v247 quad_perm:[2,3,0,1] row_mask:0xf bank_mask:0xf bound_ctrl:1
	v_add_f32_dpp v168, v168, v168 row_half_mirror row_mask:0xf bank_mask:0xf bound_ctrl:1
	v_add_f32_dpp v174, v174, v174 row_half_mirror row_mask:0xf bank_mask:0xf bound_ctrl:1
	v_add_f32_dpp v241, v241, v241 row_half_mirror row_mask:0xf bank_mask:0xf bound_ctrl:1
	v_add_f32_dpp v247, v247, v247 row_half_mirror row_mask:0xf bank_mask:0xf bound_ctrl:1
	v_add_f32_dpp v168, v168, v168 row_mirror row_mask:0xf bank_mask:0xf bound_ctrl:1
	v_add_f32_dpp v174, v174, v174 row_mirror row_mask:0xf bank_mask:0xf bound_ctrl:1
	v_add_f32_dpp v241, v241, v241 row_mirror row_mask:0xf bank_mask:0xf bound_ctrl:1
	v_add_f32_dpp v247, v247, v247 row_mirror row_mask:0xf bank_mask:0xf bound_ctrl:1
	v_readlane_b32 s36, v168, 16
	v_readlane_b32 s40, v174, 16
	v_readlane_b32 s44, v241, 16
	v_readlane_b32 s48, v247, 16
	v_readlane_b32 s37, v168, 48
	v_readlane_b32 s41, v174, 48
	v_readlane_b32 s45, v241, 48
	v_readlane_b32 s49, v247, 48
	v_readlane_b32 s38, v168, 0
	v_readlane_b32 s42, v174, 0
	v_readlane_b32 s46, v241, 0
	v_readlane_b32 s50, v247, 0
	v_readlane_b32 s39, v168, 32
	v_readlane_b32 s43, v174, 32
	v_readlane_b32 s47, v241, 32
	v_readlane_b32 s51, v247, 32
	v_mov_b32_e32 v168, s36
	v_mov_b32_e32 v174, s40
	v_mov_b32_e32 v241, s44
	v_mov_b32_e32 v247, s48
	v_mov_b32_e32 v169, s37
	v_mov_b32_e32 v175, s41
	v_mov_b32_e32 v242, s45
	v_mov_b32_e32 v248, s49
	v_add_f32_e32 v168, s38, v168
	v_add_f32_e32 v174, s42, v174
	v_add_f32_e32 v241, s46, v241
	v_add_f32_e32 v247, s50, v247
	v_add_f32_e32 v169, s39, v169
	v_add_f32_e32 v175, s43, v175
	v_add_f32_e32 v242, s47, v242
	v_add_f32_e32 v248, s51, v248
	v_add_f32_e32 v168, v168, v169
	v_add_f32_e32 v174, v174, v175
	v_add_f32_e32 v241, v241, v242
	v_add_f32_e32 v247, v247, v248
	v_fmamk_f32 v168, v168, 0x3c800000, v9
	v_fmamk_f32 v174, v174, 0x3c800000, v9
	v_fmamk_f32 v241, v241, 0x3c800000, v9
	v_fmamk_f32 v247, v247, 0x3c800000, v9
	v_readfirstlane_b32 s40, v174
	v_readfirstlane_b32 s44, v241
	v_readfirstlane_b32 s48, v247
	v_writelane_b32 v168, s40, 1
	v_writelane_b32 v168, s44, 2
	v_writelane_b32 v168, s48, 3
	v_mul_f32_e32 v169, 0x4f800000, v168
	v_cmp_gt_f32_e64 s[52:53], s68, v168
	v_mov_b32_e32 v170, v168
	s_nop 1
	v_cndmask_b32_e64 v168, v170, v169, s[52:53]
	v_sqrt_f32_e32 v169, v168
	s_nop 0
	v_add_u32_e32 v170, -1, v169
	v_fma_f32 v171, -v170, v169, v168
	v_cmp_ge_f32_e64 s[60:61], 0, v171
	v_add_u32_e32 v171, 1, v169
	s_nop 1
	v_cndmask_b32_e64 v170, v169, v170, s[60:61]
	v_fma_f32 v169, -v171, v169, v168
	v_cmp_lt_f32_e64 s[60:61], 0, v169
	s_nop 1
	v_cndmask_b32_e64 v169, v170, v171, s[60:61]
	v_mul_f32_e32 v170, 0x37800000, v169
	v_cndmask_b32_e64 v169, v169, v170, s[52:53]
	v_cmp_class_f32_e64 s[60:61], v168, v8
	s_nop 1
	v_cndmask_b32_e64 v168, v169, v168, s[60:61]
	v_div_scale_f32 v169, s[60:61], v168, v168, 1.0
	v_rcp_f32_e32 v170, v169
	s_nop 0
	v_fma_f32 v171, -v169, v170, 1.0
	v_fmac_f32_e32 v170, v171, v170
	v_div_scale_f32 v171, vcc, 1.0, v168, 1.0
	v_mul_f32_e32 v172, v171, v170
	v_fma_f32 v173, -v169, v172, v171
	v_fmac_f32_e32 v172, v173, v170
	v_fma_f32 v169, -v169, v172, v171
	v_div_fmas_f32 v169, v169, v170, v172
	v_div_fixup_f32 v168, v169, v168, 1.0
	s_nop 0
	v_readlane_b32 s37, v168, 0
	v_readlane_b32 s41, v168, 1
	v_readlane_b32 s45, v168, 2
	v_readlane_b32 s49, v168, 3
	v_mul_f32_e32 v100, s37, v100
	v_mul_f32_e32 v105, s41, v105
	v_mul_f32_e32 v110, s45, v110
	v_mul_f32_e32 v115, s49, v115
	v_lshlrev_b32_e32 v103, 16, v103
	v_lshlrev_b32_e32 v108, 16, v108
	v_lshlrev_b32_e32 v113, 16, v113
	v_lshlrev_b32_e32 v118, 16, v118
	v_fma_f32 v100, v6, v100, v7
	v_fma_f32 v105, v6, v105, v7
	v_fma_f32 v110, v6, v110, v7
	v_fma_f32 v115, v6, v115, v7
	v_fmac_f32_e32 v100, s73, v101
	v_fmac_f32_e32 v105, s26, v106
	v_fmac_f32_e32 v110, s27, v111
	v_fmac_f32_e32 v115, s32, v116
	v_mul_f32_e32 v100, v100, v103
	v_mul_f32_e32 v105, v105, v108
	v_mul_f32_e32 v110, v110, v113
	v_mul_f32_e32 v115, v115, v118
	v_cvt_pk_bf16_f32 v169, v100, v100
	v_cvt_pk_bf16_f32 v175, v105, v105
	v_cvt_pk_bf16_f32 v242, v110, v110
	v_cvt_pk_bf16_f32 v248, v115, v115
	global_store_short v2, v169, s[28:29]
	s_add_u32 s28, s28, 0x1000
	s_addc_u32 s29, s29, 0
	global_store_short v2, v175, s[28:29]
	s_add_u32 s28, s28, 0x1000
	s_addc_u32 s29, s29, 0
	global_store_short v2, v242, s[28:29]
	s_add_u32 s28, s28, 0x1000
	s_addc_u32 s29, s29, 0
	global_store_short v2, v248, s[28:29]
	s_add_u32 s28, s28, 0x1000
	s_addc_u32 s29, s29, 0
	s_waitcnt vmcnt(8)
	ds_write_b128 v13, v[120:123] offset:0
	ds_write_b128 v13, v[124:127] offset:1024
	ds_write_b128 v13, v[128:131] offset:16384
	ds_write_b128 v13, v[132:135] offset:17408
	ds_write_b128 v15, v[136:139]
	v_readlane_b32 s69, v159, 0
	v_readlane_b32 s70, v159, 1
	v_readlane_b32 s71, v159, 2
	v_readlane_b32 s72, v159, 3
	v_readlane_b32 s73, v159, 4
	v_readlane_b32 s26, v159, 5
	v_readlane_b32 s27, v159, 6
	v_readlane_b32 s32, v159, 7
	global_load_dwordx4 v[120:123], v11, s[6:7]
	global_load_dwordx4 v[124:127], v11, s[6:7] offset:1024
	global_load_dwordx4 v[128:131], v11, s[8:9]
	global_load_dwordx4 v[132:135], v11, s[8:9] offset:1024
	global_load_dwordx4 v[136:139], v11, s[10:11]
	global_load_dword v159, v158, s[12:13]
	s_add_u32 s6, s6, 0x10000
	s_addc_u32 s7, s7, 0
	s_add_u32 s8, s8, 0x10000
	s_addc_u32 s9, s9, 0
	s_add_u32 s10, s10, 0x8000
	s_addc_u32 s11, s11, 0
	s_add_u32 s12, s12, 0x400
	s_addc_u32 s13, s13, 0
	s_waitcnt lgkmcnt(0)
	s_barrier
; __device__ __forceinline__ void rw_post(Frame& F) {
;     ...
;                         y[4 * hf + q] += (a[0] + a[1]) + (a[2] + a[3]); }
;                     asm volatile("s_waitcnt lgkmcnt(0)" ::: "memory"); }
;             }
; #pragma unroll
;             for (int q = 0; q < 8; ++q) { const int row = rb0 + t0 + q;
;                 const float mean = wsum(y[q]) * (1.f / 64.f); const float dv = y[q] - mean; const float var = wsum(dv * dv) * (1.f / 64.f);
	ds_read_b32 v80, v155 offset:0
	ds_read_b32 v81, v155 offset:16384
	ds_read_u16 v83, v157 offset:0
	ds_read_b32 v85, v155 offset:2048
	ds_read_b32 v86, v155 offset:18432
	ds_read_u16 v88, v157 offset:1024
	ds_read_b32 v90, v155 offset:4096
	ds_read_b32 v91, v155 offset:20480
	ds_read_u16 v93, v157 offset:2048
	ds_read_b32 v95, v155 offset:6144
	ds_read_b32 v96, v155 offset:22528
	ds_read_u16 v98, v157 offset:3072
	ds_read_b32 v100, v155 offset:8192
	ds_read_b32 v101, v155 offset:24576
	ds_read_u16 v103, v157 offset:4096
	ds_read_b32 v105, v155 offset:10240
	ds_read_b32 v106, v155 offset:26624
	ds_read_u16 v108, v157 offset:5120
	ds_read_b32 v110, v155 offset:12288
	ds_read_b32 v111, v155 offset:28672
	ds_read_u16 v113, v157 offset:6144
	ds_read_b32 v115, v155 offset:14336
	ds_read_b32 v116, v155 offset:30720
	ds_read_u16 v118, v157 offset:7168
	s_waitcnt lgkmcnt(0)
	v_add_f32_e32 v80, v80, v52
	v_add_f32_e32 v85, v85, v53
	v_add_f32_e32 v90, v90, v54
	v_add_f32_e32 v95, v95, v55
	v_add_f32_dpp v168, v80, v80 quad_perm:[1,0,3,2] row_mask:0xf bank_mask:0xf bound_ctrl:1
	v_add_f32_dpp v174, v85, v85 quad_perm:[1,0,3,2] row_mask:0xf bank_mask:0xf bound_ctrl:1
	v_add_f32_dpp v241, v90, v90 quad_perm:[1,0,3,2] row_mask:0xf bank_mask:0xf bound_ctrl:1
	v_add_f32_dpp v247, v95, v95 quad_perm:[1,0,3,2] row_mask:0xf bank_mask:0xf bound_ctrl:1
	v_add_f32_dpp v168, v168, v168 quad_perm:[2,3,0,1] row_mask:0xf bank_mask:0xf bound_ctrl:1
	v_add_f32_dpp v174, v174, v174 quad_perm:[2,3,0,1] row_mask:0xf bank_mask:0xf bound_ctrl:1
	v_add_f32_dpp v241, v241, v241 quad_perm:[2,3,0,1] row_mask:0xf bank_mask:0xf bound_ctrl:1
	v_add_f32_dpp v247, v247, v247 quad_perm:[2,3,0,1] row_mask:0xf bank_mask:0xf bound_ctrl:1
	v_add_f32_dpp v168, v168, v168 row_half_mirror row_mask:0xf bank_mask:0xf bound_ctrl:1
	v_add_f32_dpp v174, v174, v174 row_half_mirror row_mask:0xf bank_mask:0xf bound_ctrl:1
	v_add_f32_dpp v241, v241, v241 row_half_mirror row_mask:0xf bank_mask:0xf bound_ctrl:1
	v_add_f32_dpp v247, v247, v247 row_half_mirror row_mask:0xf bank_mask:0xf bound_ctrl:1
	v_add_f32_dpp v168, v168, v168 row_mirror row_mask:0xf bank_mask:0xf bound_ctrl:1
	v_add_f32_dpp v174, v174, v174 row_mirror row_mask:0xf bank_mask:0xf bound_ctrl:1
	v_add_f32_dpp v241, v241, v241 row_mirror row_mask:0xf bank_mask:0xf bound_ctrl:1
	v_add_f32_dpp v247, v247, v247 row_mirror row_mask:0xf bank_mask:0xf bound_ctrl:1
	v_readlane_b32 s36, v168, 16
	v_readlane_b32 s40, v174, 16
	v_readlane_b32 s44, v241, 16
	v_readlane_b32 s48, v247, 16
	v_readlane_b32 s37, v168, 48
	v_readlane_b32 s41, v174, 48
	v_readlane_b32 s45, v241, 48
	v_readlane_b32 s49, v247, 48
	v_readlane_b32 s38, v168, 0
	v_readlane_b32 s42, v174, 0
	v_readlane_b32 s46, v241, 0
	v_readlane_b32 s50, v247, 0
	v_readlane_b32 s39, v168, 32
	v_readlane_b32 s43, v174, 32
	v_readlane_b32 s47, v241, 32
	v_readlane_b32 s51, v247, 32
	v_mov_b32_e32 v168, s36
	v_mov_b32_e32 v174, s40
	v_mov_b32_e32 v241, s44
	v_mov_b32_e32 v247, s48
	v_mov_b32_e32 v169, s37
	v_mov_b32_e32 v175, s41
	v_mov_b32_e32 v242, s45
	v_mov_b32_e32 v248, s49
	v_add_f32_e32 v168, s38, v168
	v_add_f32_e32 v174, s42, v174
	v_add_f32_e32 v241, s46, v241
	v_add_f32_e32 v247, s50, v247
	v_add_f32_e32 v169, s39, v169
	v_add_f32_e32 v175, s43, v175
	v_add_f32_e32 v242, s47, v242
	v_add_f32_e32 v248, s51, v248
	v_add_f32_e32 v168, v168, v169
	v_add_f32_e32 v174, v174, v175
	v_add_f32_e32 v241, v241, v242
	v_add_f32_e32 v247, v247, v248
	v_fmamk_f32 v80, v168, 0xbc800000, v80
	v_fmamk_f32 v85, v174, 0xbc800000, v85
	v_fmamk_f32 v90, v241, 0xbc800000, v90
	v_fmamk_f32 v95, v247, 0xbc800000, v95
	v_mul_f32_e32 v168, v80, v80
	v_mul_f32_e32 v174, v85, v85
	v_mul_f32_e32 v241, v90, v90
	v_mul_f32_e32 v247, v95, v95
	v_mov_b32_dpp v168, v168 quad_perm:[1,0,3,2] row_mask:0xf bank_mask:0xf bound_ctrl:1
	v_mov_b32_dpp v174, v174 quad_perm:[1,0,3,2] row_mask:0xf bank_mask:0xf bound_ctrl:1
	v_mov_b32_dpp v241, v241 quad_perm:[1,0,3,2] row_mask:0xf bank_mask:0xf bound_ctrl:1
	v_mov_b32_dpp v247, v247 quad_perm:[1,0,3,2] row_mask:0xf bank_mask:0xf bound_ctrl:1
	v_fmac_f32_e32 v168, v80, v80
	v_fmac_f32_e32 v174, v85, v85
	v_fmac_f32_e32 v241, v90, v90
	v_fmac_f32_e32 v247, v95, v95
	v_add_f32_dpp v168, v168, v168 quad_perm:[2,3,0,1] row_mask:0xf bank_mask:0xf bound_ctrl:1
	v_add_f32_dpp v174, v174, v174 quad_perm:[2,3,0,1] row_mask:0xf bank_mask:0xf bound_ctrl:1
	v_add_f32_dpp v241, v241, v241 quad_perm:[2,3,0,1] row_mask:0xf bank_mask:0xf bound_ctrl:1
	v_add_f32_dpp v247, v247, v247 quad_perm:[2,3,0,1] row_mask:0xf bank_mask:0xf bound_ctrl:1
	v_add_f32_dpp v168, v168, v168 row_half_mirror row_mask:0xf bank_mask:0xf bound_ctrl:1
	v_add_f32_dpp v174, v174, v174 row_half_mirror row_mask:0xf bank_mask:0xf bound_ctrl:1
	v_add_f32_dpp v241, v241, v241 row_half_mirror row_mask:0xf bank_mask:0xf bound_ctrl:1
	v_add_f32_dpp v247, v247, v247 row_half_mirror row_mask:0xf bank_mask:0xf bound_ctrl:1
	v_add_f32_dpp v168, v168, v168 row_mirror row_mask:0xf bank_mask:0xf bound_ctrl:1
	v_add_f32_dpp v174, v174, v174 row_mirror row_mask:0xf bank_mask:0xf bound_ctrl:1
	v_add_f32_dpp v241, v241, v241 row_mirror row_mask:0xf bank_mask:0xf bound_ctrl:1
	v_add_f32_dpp v247, v247, v247 row_mirror row_mask:0xf bank_mask:0xf bound_ctrl:1
	v_readlane_b32 s36, v168, 16
	v_readlane_b32 s40, v174, 16
	v_readlane_b32 s44, v241, 16
	v_readlane_b32 s48, v247, 16
	v_readlane_b32 s37, v168, 48
	v_readlane_b32 s41, v174, 48
	v_readlane_b32 s45, v241, 48
	v_readlane_b32 s49, v247, 48
	v_readlane_b32 s38, v168, 0
	v_readlane_b32 s42, v174, 0
	v_readlane_b32 s46, v241, 0
	v_readlane_b32 s50, v247, 0
	v_readlane_b32 s39, v168, 32
; __device__ __forceinline__ float bf2f(bf16 x) { return __uint_as_float(((unsigned)x) << 16); }
; __device__ __forceinline__ unsigned f2bf(float f) { return cvt_pk_bf16(f, 0.f) & 0xffffu; }
; __device__ __forceinline__ void rw_post(Frame& F) {
;     ...
;             for (int q = 0; q < 8; ++q) { const int row = rb0 + t0 + q;
;                 const float mean = wsum(y[q]) * (1.f / 64.f); const float dv = y[q] - mean; const float var = wsum(dv * dv) * (1.f / 64.f);
;                 const float yn = dv * (1.f / sqrtf(var + 64e-5f)) * g_ + b_;
;                 OB[(size_t)row * DH + col] = (bf16)f2bf((yn + rk[q] * vv[q]) * bf2f(gg[q])); }
	v_readlane_b32 s43, v174, 32
	v_readlane_b32 s47, v241, 32
	v_readlane_b32 s51, v247, 32
	v_mov_b32_e32 v168, s36
	v_mov_b32_e32 v174, s40
	v_mov_b32_e32 v241, s44
	v_mov_b32_e32 v247, s48
	v_mov_b32_e32 v169, s37
	v_mov_b32_e32 v175, s41
	v_mov_b32_e32 v242, s45
	v_mov_b32_e32 v248, s49
	v_add_f32_e32 v168, s38, v168
	v_add_f32_e32 v174, s42, v174
	v_add_f32_e32 v241, s46, v241
	v_add_f32_e32 v247, s50, v247
	v_add_f32_e32 v169, s39, v169
	v_add_f32_e32 v175, s43, v175
	v_add_f32_e32 v242, s47, v242
	v_add_f32_e32 v248, s51, v248
	v_add_f32_e32 v168, v168, v169
	v_add_f32_e32 v174, v174, v175
	v_add_f32_e32 v241, v241, v242
	v_add_f32_e32 v247, v247, v248
	v_fmamk_f32 v168, v168, 0x3c800000, v9
	v_fmamk_f32 v174, v174, 0x3c800000, v9
	v_fmamk_f32 v241, v241, 0x3c800000, v9
	v_fmamk_f32 v247, v247, 0x3c800000, v9
	v_readfirstlane_b32 s40, v174
	v_readfirstlane_b32 s44, v241
	v_readfirstlane_b32 s48, v247
	v_writelane_b32 v168, s40, 1
	v_writelane_b32 v168, s44, 2
	v_writelane_b32 v168, s48, 3
	v_mul_f32_e32 v169, 0x4f800000, v168
	v_cmp_gt_f32_e64 s[52:53], s68, v168
	v_mov_b32_e32 v170, v168
	s_nop 1
	v_cndmask_b32_e64 v168, v170, v169, s[52:53]
	v_sqrt_f32_e32 v169, v168
	s_nop 0
	v_add_u32_e32 v170, -1, v169
	v_fma_f32 v171, -v170, v169, v168
	v_cmp_ge_f32_e64 s[60:61], 0, v171
	v_add_u32_e32 v171, 1, v169
	s_nop 1
	v_cndmask_b32_e64 v170, v169, v170, s[60:61]
	v_fma_f32 v169, -v171, v169, v168
	v_cmp_lt_f32_e64 s[60:61], 0, v169
	s_nop 1
	v_cndmask_b32_e64 v169, v170, v171, s[60:61]
	v_mul_f32_e32 v170, 0x37800000, v169
	v_cndmask_b32_e64 v169, v169, v170, s[52:53]
	v_cmp_class_f32_e64 s[60:61], v168, v8
	s_nop 1
	v_cndmask_b32_e64 v168, v169, v168, s[60:61]
	v_div_scale_f32 v169, s[60:61], v168, v168, 1.0
	v_rcp_f32_e32 v170, v169
	s_nop 0
	v_fma_f32 v171, -v169, v170, 1.0
	v_fmac_f32_e32 v170, v171, v170
	v_div_scale_f32 v171, vcc, 1.0, v168, 1.0
	v_mul_f32_e32 v172, v171, v170
	v_fma_f32 v173, -v169, v172, v171
	v_fmac_f32_e32 v172, v173, v170
	v_fma_f32 v169, -v169, v172, v171
	v_div_fmas_f32 v169, v169, v170, v172
	v_div_fixup_f32 v168, v169, v168, 1.0
	s_nop 0
	v_readlane_b32 s37, v168, 0
	v_readlane_b32 s41, v168, 1
	v_readlane_b32 s45, v168, 2
	v_readlane_b32 s49, v168, 3
	v_mul_f32_e32 v80, s37, v80
	v_mul_f32_e32 v85, s41, v85
	v_mul_f32_e32 v90, s45, v90
	v_mul_f32_e32 v95, s49, v95
	v_lshlrev_b32_e32 v83, 16, v83
	v_lshlrev_b32_e32 v88, 16, v88
	v_lshlrev_b32_e32 v93, 16, v93
	v_lshlrev_b32_e32 v98, 16, v98
	v_fma_f32 v80, v6, v80, v7
	v_fma_f32 v85, v6, v85, v7
	v_fma_f32 v90, v6, v90, v7
	v_fma_f32 v95, v6, v95, v7
	v_fmac_f32_e32 v80, s69, v81
	v_fmac_f32_e32 v85, s70, v86
	v_fmac_f32_e32 v90, s71, v91
	v_fmac_f32_e32 v95, s72, v96
	v_mul_f32_e32 v80, v80, v83
	v_mul_f32_e32 v85, v85, v88
	v_mul_f32_e32 v90, v90, v93
	v_mul_f32_e32 v95, v95, v98
	v_cvt_pk_bf16_f32 v169, v80, v80
	v_cvt_pk_bf16_f32 v175, v85, v85
	v_cvt_pk_bf16_f32 v242, v90, v90
	v_cvt_pk_bf16_f32 v248, v95, v95
	global_store_short v2, v169, s[28:29]
	s_add_u32 s28, s28, 0x1000
	s_addc_u32 s29, s29, 0
	global_store_short v2, v175, s[28:29]
	s_add_u32 s28, s28, 0x1000
	s_addc_u32 s29, s29, 0
	global_store_short v2, v242, s[28:29]
	s_add_u32 s28, s28, 0x1000
	s_addc_u32 s29, s29, 0
	global_store_short v2, v248, s[28:29]
	s_add_u32 s28, s28, 0x1000
	s_addc_u32 s29, s29, 0
	v_add_f32_e32 v100, v100, v68
	v_add_f32_e32 v105, v105, v69
	v_add_f32_e32 v110, v110, v70
	v_add_f32_e32 v115, v115, v71
	v_add_f32_dpp v168, v100, v100 quad_perm:[1,0,3,2] row_mask:0xf bank_mask:0xf bound_ctrl:1
	v_add_f32_dpp v174, v105, v105 quad_perm:[1,0,3,2] row_mask:0xf bank_mask:0xf bound_ctrl:1
	v_add_f32_dpp v241, v110, v110 quad_perm:[1,0,3,2] row_mask:0xf bank_mask:0xf bound_ctrl:1
	v_add_f32_dpp v247, v115, v115 quad_perm:[1,0,3,2] row_mask:0xf bank_mask:0xf bound_ctrl:1
	v_add_f32_dpp v168, v168, v168 quad_perm:[2,3,0,1] row_mask:0xf bank_mask:0xf bound_ctrl:1
	v_add_f32_dpp v174, v174, v174 quad_perm:[2,3,0,1] row_mask:0xf bank_mask:0xf bound_ctrl:1
	v_add_f32_dpp v241, v241, v241 quad_perm:[2,3,0,1] row_mask:0xf bank_mask:0xf bound_ctrl:1
	v_add_f32_dpp v247, v247, v247 quad_perm:[2,3,0,1] row_mask:0xf bank_mask:0xf bound_ctrl:1
	v_add_f32_dpp v168, v168, v168 row_half_mirror row_mask:0xf bank_mask:0xf bound_ctrl:1
	v_add_f32_dpp v174, v174, v174 row_half_mirror row_mask:0xf bank_mask:0xf bound_ctrl:1
	v_add_f32_dpp v241, v241, v241 row_half_mirror row_mask:0xf bank_mask:0xf bound_ctrl:1
	v_add_f32_dpp v247, v247, v247 row_half_mirror row_mask:0xf bank_mask:0xf bound_ctrl:1
	v_add_f32_dpp v168, v168, v168 row_mirror row_mask:0xf bank_mask:0xf bound_ctrl:1
	v_add_f32_dpp v174, v174, v174 row_mirror row_mask:0xf bank_mask:0xf bound_ctrl:1
	v_add_f32_dpp v241, v241, v241 row_mirror row_mask:0xf bank_mask:0xf bound_ctrl:1
	v_add_f32_dpp v247, v247, v247 row_mirror row_mask:0xf bank_mask:0xf bound_ctrl:1
	v_readlane_b32 s36, v168, 16
	v_readlane_b32 s40, v174, 16
	v_readlane_b32 s44, v241, 16
	v_readlane_b32 s48, v247, 16
	v_readlane_b32 s37, v168, 48
	v_readlane_b32 s41, v174, 48
	v_readlane_b32 s45, v241, 48
	v_readlane_b32 s49, v247, 48
	v_readlane_b32 s38, v168, 0
	v_readlane_b32 s42, v174, 0
	v_readlane_b32 s46, v241, 0
	v_readlane_b32 s50, v247, 0
	v_readlane_b32 s39, v168, 32
	v_readlane_b32 s43, v174, 32
	v_readlane_b32 s47, v241, 32
	v_readlane_b32 s51, v247, 32
	v_mov_b32_e32 v168, s36
	v_mov_b32_e32 v174, s40
	v_mov_b32_e32 v241, s44
	v_mov_b32_e32 v247, s48
	v_mov_b32_e32 v169, s37
	v_mov_b32_e32 v175, s41
	v_mov_b32_e32 v242, s45
	v_mov_b32_e32 v248, s49
	v_add_f32_e32 v168, s38, v168
	v_add_f32_e32 v174, s42, v174
	v_add_f32_e32 v241, s46, v241
; __device__ __forceinline__ float bf2f(bf16 x) { return __uint_as_float(((unsigned)x) << 16); }
; __device__ __forceinline__ unsigned f2bf(float f) { return cvt_pk_bf16(f, 0.f) & 0xffffu; }
; __device__ __forceinline__ float dpp_xor1(float x) { return __builtin_bit_cast(float, __builtin_amdgcn_update_dpp(0, __builtin_bit_cast(int, x), 0xB1, 0xF, 0xF, true)); }
; __device__ __forceinline__ float dpp_xor2(float x) { return __builtin_bit_cast(float, __builtin_amdgcn_update_dpp(0, __builtin_bit_cast(int, x), 0x4E, 0xF, 0xF, true)); }
; __device__ __forceinline__ float dpp_hmir(float x) { return __builtin_bit_cast(float, __builtin_amdgcn_update_dpp(0, __builtin_bit_cast(int, x), 0x141, 0xF, 0xF, true)); }
; __device__ __forceinline__ float dpp_mir(float x)  { return __builtin_bit_cast(float, __builtin_amdgcn_update_dpp(0, __builtin_bit_cast(int, x), 0x140, 0xF, 0xF, true)); }
; __device__ __forceinline__ float red16(float x) { x += dpp_xor1(x); x += dpp_xor2(x); x += dpp_hmir(x); x += dpp_mir(x); return x; }
; __device__ __forceinline__ float wsum(float x) {
;     x = red16(x); const int xi = __builtin_bit_cast(int, x);
;     const float r0 = __builtin_bit_cast(float, __builtin_amdgcn_readlane(xi, 0)), r1 = __builtin_bit_cast(float, __builtin_amdgcn_readlane(xi, 16));
;     const float r2 = __builtin_bit_cast(float, __builtin_amdgcn_readlane(xi, 32)), r3 = __builtin_bit_cast(float, __builtin_amdgcn_readlane(xi, 48));
;     return (r0 + r1) + (r2 + r3);
; }
; __device__ __forceinline__ void rw_post(Frame& F) {
;     ...
;             for (int q = 0; q < 8; ++q) { const int row = rb0 + t0 + q;
;                 const float mean = wsum(y[q]) * (1.f / 64.f); const float dv = y[q] - mean; const float var = wsum(dv * dv) * (1.f / 64.f);
;                 const float yn = dv * (1.f / sqrtf(var + 64e-5f)) * g_ + b_;
;                 OB[(size_t)row * DH + col] = (bf16)f2bf((yn + rk[q] * vv[q]) * bf2f(gg[q])); }
	v_add_f32_e32 v247, s50, v247
	v_add_f32_e32 v169, s39, v169
	v_add_f32_e32 v175, s43, v175
	v_add_f32_e32 v242, s47, v242
	v_add_f32_e32 v248, s51, v248
	v_add_f32_e32 v168, v168, v169
	v_add_f32_e32 v174, v174, v175
	v_add_f32_e32 v241, v241, v242
	v_add_f32_e32 v247, v247, v248
	v_fmamk_f32 v100, v168, 0xbc800000, v100
	v_fmamk_f32 v105, v174, 0xbc800000, v105
	v_fmamk_f32 v110, v241, 0xbc800000, v110
	v_fmamk_f32 v115, v247, 0xbc800000, v115
	v_mul_f32_e32 v168, v100, v100
	v_mul_f32_e32 v174, v105, v105
	v_mul_f32_e32 v241, v110, v110
	v_mul_f32_e32 v247, v115, v115
	v_mov_b32_dpp v168, v168 quad_perm:[1,0,3,2] row_mask:0xf bank_mask:0xf bound_ctrl:1
	v_mov_b32_dpp v174, v174 quad_perm:[1,0,3,2] row_mask:0xf bank_mask:0xf bound_ctrl:1
	v_mov_b32_dpp v241, v241 quad_perm:[1,0,3,2] row_mask:0xf bank_mask:0xf bound_ctrl:1
	v_mov_b32_dpp v247, v247 quad_perm:[1,0,3,2] row_mask:0xf bank_mask:0xf bound_ctrl:1
	v_fmac_f32_e32 v168, v100, v100
	v_fmac_f32_e32 v174, v105, v105
	v_fmac_f32_e32 v241, v110, v110
	v_fmac_f32_e32 v247, v115, v115
	v_add_f32_dpp v168, v168, v168 quad_perm:[2,3,0,1] row_mask:0xf bank_mask:0xf bound_ctrl:1
	v_add_f32_dpp v174, v174, v174 quad_perm:[2,3,0,1] row_mask:0xf bank_mask:0xf bound_ctrl:1
	v_add_f32_dpp v241, v241, v241 quad_perm:[2,3,0,1] row_mask:0xf bank_mask:0xf bound_ctrl:1
	v_add_f32_dpp v247, v247, v247 quad_perm:[2,3,0,1] row_mask:0xf bank_mask:0xf bound_ctrl:1
	v_add_f32_dpp v168, v168, v168 row_half_mirror row_mask:0xf bank_mask:0xf bound_ctrl:1
	v_add_f32_dpp v174, v174, v174 row_half_mirror row_mask:0xf bank_mask:0xf bound_ctrl:1
	v_add_f32_dpp v241, v241, v241 row_half_mirror row_mask:0xf bank_mask:0xf bound_ctrl:1
	v_add_f32_dpp v247, v247, v247 row_half_mirror row_mask:0xf bank_mask:0xf bound_ctrl:1
	v_add_f32_dpp v168, v168, v168 row_mirror row_mask:0xf bank_mask:0xf bound_ctrl:1
	v_add_f32_dpp v174, v174, v174 row_mirror row_mask:0xf bank_mask:0xf bound_ctrl:1
	v_add_f32_dpp v241, v241, v241 row_mirror row_mask:0xf bank_mask:0xf bound_ctrl:1
	v_add_f32_dpp v247, v247, v247 row_mirror row_mask:0xf bank_mask:0xf bound_ctrl:1
	v_readlane_b32 s36, v168, 16
	v_readlane_b32 s40, v174, 16
	v_readlane_b32 s44, v241, 16
	v_readlane_b32 s48, v247, 16
	v_readlane_b32 s37, v168, 48
	v_readlane_b32 s41, v174, 48
	v_readlane_b32 s45, v241, 48
	v_readlane_b32 s49, v247, 48
	v_readlane_b32 s38, v168, 0
	v_readlane_b32 s42, v174, 0
	v_readlane_b32 s46, v241, 0
	v_readlane_b32 s50, v247, 0
	v_readlane_b32 s39, v168, 32
	v_readlane_b32 s43, v174, 32
	v_readlane_b32 s47, v241, 32
	v_readlane_b32 s51, v247, 32
	v_mov_b32_e32 v168, s36
	v_mov_b32_e32 v174, s40
	v_mov_b32_e32 v241, s44
	v_mov_b32_e32 v247, s48
	v_mov_b32_e32 v169, s37
	v_mov_b32_e32 v175, s41
	v_mov_b32_e32 v242, s45
	v_mov_b32_e32 v248, s49
	v_add_f32_e32 v168, s38, v168
	v_add_f32_e32 v174, s42, v174
	v_add_f32_e32 v241, s46, v241
	v_add_f32_e32 v247, s50, v247
	v_add_f32_e32 v169, s39, v169
	v_add_f32_e32 v175, s43, v175
	v_add_f32_e32 v242, s47, v242
	v_add_f32_e32 v248, s51, v248
	v_add_f32_e32 v168, v168, v169
	v_add_f32_e32 v174, v174, v175
	v_add_f32_e32 v241, v241, v242
	v_add_f32_e32 v247, v247, v248
	v_fmamk_f32 v168, v168, 0x3c800000, v9
	v_fmamk_f32 v174, v174, 0x3c800000, v9
	v_fmamk_f32 v241, v241, 0x3c800000, v9
	v_fmamk_f32 v247, v247, 0x3c800000, v9
	v_readfirstlane_b32 s40, v174
	v_readfirstlane_b32 s44, v241
	v_readfirstlane_b32 s48, v247
	v_writelane_b32 v168, s40, 1
	v_writelane_b32 v168, s44, 2
	v_writelane_b32 v168, s48, 3
	v_mul_f32_e32 v169, 0x4f800000, v168
	v_cmp_gt_f32_e64 s[52:53], s68, v168
	v_mov_b32_e32 v170, v168
	s_nop 1
	v_cndmask_b32_e64 v168, v170, v169, s[52:53]
	v_sqrt_f32_e32 v169, v168
	s_nop 0
	v_add_u32_e32 v170, -1, v169
	v_fma_f32 v171, -v170, v169, v168
	v_cmp_ge_f32_e64 s[60:61], 0, v171
	v_add_u32_e32 v171, 1, v169
	s_nop 1
	v_cndmask_b32_e64 v170, v169, v170, s[60:61]
	v_fma_f32 v169, -v171, v169, v168
	v_cmp_lt_f32_e64 s[60:61], 0, v169
	s_nop 1
	v_cndmask_b32_e64 v169, v170, v171, s[60:61]
	v_mul_f32_e32 v170, 0x37800000, v169
	v_cndmask_b32_e64 v169, v169, v170, s[52:53]
	v_cmp_class_f32_e64 s[60:61], v168, v8
	s_nop 1
	v_cndmask_b32_e64 v168, v169, v168, s[60:61]
	v_div_scale_f32 v169, s[60:61], v168, v168, 1.0
	v_rcp_f32_e32 v170, v169
	s_nop 0
	v_fma_f32 v171, -v169, v170, 1.0
	v_fmac_f32_e32 v170, v171, v170
	v_div_scale_f32 v171, vcc, 1.0, v168, 1.0
	v_mul_f32_e32 v172, v171, v170
	v_fma_f32 v173, -v169, v172, v171
	v_fmac_f32_e32 v172, v173, v170
	v_fma_f32 v169, -v169, v172, v171
	v_div_fmas_f32 v169, v169, v170, v172
	v_div_fixup_f32 v168, v169, v168, 1.0
	s_nop 0
	v_readlane_b32 s37, v168, 0
	v_readlane_b32 s41, v168, 1
	v_readlane_b32 s45, v168, 2
	v_readlane_b32 s49, v168, 3
	v_mul_f32_e32 v100, s37, v100
	v_mul_f32_e32 v105, s41, v105
	v_mul_f32_e32 v110, s45, v110
	v_mul_f32_e32 v115, s49, v115
	v_lshlrev_b32_e32 v103, 16, v103
	v_lshlrev_b32_e32 v108, 16, v108
	v_lshlrev_b32_e32 v113, 16, v113
	v_lshlrev_b32_e32 v118, 16, v118
	v_fma_f32 v100, v6, v100, v7
	v_fma_f32 v105, v6, v105, v7
	v_fma_f32 v110, v6, v110, v7
	v_fma_f32 v115, v6, v115, v7
	v_fmac_f32_e32 v100, s73, v101
	v_fmac_f32_e32 v105, s26, v106
	v_fmac_f32_e32 v110, s27, v111
	v_fmac_f32_e32 v115, s32, v116
	v_mul_f32_e32 v100, v100, v103
	v_mul_f32_e32 v105, v105, v108
	v_mul_f32_e32 v110, v110, v113
	v_mul_f32_e32 v115, v115, v118
	v_cvt_pk_bf16_f32 v169, v100, v100
	v_cvt_pk_bf16_f32 v175, v105, v105
	v_cvt_pk_bf16_f32 v242, v110, v110
	v_cvt_pk_bf16_f32 v248, v115, v115
	global_store_short v2, v169, s[28:29]
	s_add_u32 s28, s28, 0x1000
	s_addc_u32 s29, s29, 0
	global_store_short v2, v175, s[28:29]
	s_add_u32 s28, s28, 0x1000
	s_addc_u32 s29, s29, 0
	global_store_short v2, v242, s[28:29]
	s_add_u32 s28, s28, 0x1000
	s_addc_u32 s29, s29, 0
	global_store_short v2, v248, s[28:29]
	s_add_u32 s28, s28, 0x1000
	s_addc_u32 s29, s29, 0
	s_waitcnt vmcnt(8)
	ds_write_b128 v12, v[120:123] offset:0
	ds_write_b128 v12, v[124:127] offset:1024
	ds_write_b128 v12, v[128:131] offset:16384
	ds_write_b128 v12, v[132:135] offset:17408
	ds_write_b128 v14, v[136:139]
	v_readlane_b32 s69, v159, 0
	v_readlane_b32 s70, v159, 1
	v_readlane_b32 s71, v159, 2
	v_readlane_b32 s72, v159, 3
	v_readlane_b32 s73, v159, 4
	v_readlane_b32 s26, v159, 5
	v_readlane_b32 s27, v159, 6
	v_readlane_b32 s32, v159, 7
	global_load_dwordx4 v[120:123], v11, s[6:7]
	global_load_dwordx4 v[124:127], v11, s[6:7] offset:1024
	global_load_dwordx4 v[128:131], v11, s[8:9]
	global_load_dwordx4 v[132:135], v11, s[8:9] offset:1024
	global_load_dwordx4 v[136:139], v11, s[10:11]
	global_load_dword v159, v158, s[12:13]
	s_add_u32 s6, s6, 0x10000
	s_addc_u32 s7, s7, 0
	s_add_u32 s8, s8, 0x10000
	s_addc_u32 s9, s9, 0
	s_add_u32 s10, s10, 0x8000
	s_addc_u32 s11, s11, 0
	s_add_u32 s12, s12, 0x400
	s_addc_u32 s13, s13, 0
	s_waitcnt lgkmcnt(0)
	s_barrier
; #define LAS __attribute__((address_space(3)))
; __device__ __forceinline__ float bf2f(bf16 x) { return __uint_as_float(((unsigned)x) << 16); }
; __device__ __forceinline__ unsigned f2bf(float f) { return cvt_pk_bf16(f, 0.f) & 0xffffu; }
; __device__ __forceinline__ float dpp_xor1(float x) { return __builtin_bit_cast(float, __builtin_amdgcn_update_dpp(0, __builtin_bit_cast(int, x), 0xB1, 0xF, 0xF, true)); }
; __device__ __forceinline__ float dpp_xor2(float x) { return __builtin_bit_cast(float, __builtin_amdgcn_update_dpp(0, __builtin_bit_cast(int, x), 0x4E, 0xF, 0xF, true)); }
; __device__ __forceinline__ float dpp_hmir(float x) { return __builtin_bit_cast(float, __builtin_amdgcn_update_dpp(0, __builtin_bit_cast(int, x), 0x141, 0xF, 0xF, true)); }
; __device__ __forceinline__ float red16(float x) { x += dpp_xor1(x); x += dpp_xor2(x); x += dpp_hmir(x); x += dpp_mir(x); return x; }
; __device__ __forceinline__ float wsum(float x) {
;     x = red16(x); const int xi = __builtin_bit_cast(int, x);
;     const float r0 = __builtin_bit_cast(float, __builtin_amdgcn_readlane(xi, 0)), r1 = __builtin_bit_cast(float, __builtin_amdgcn_readlane(xi, 16));
;     const float r2 = __builtin_bit_cast(float, __builtin_amdgcn_readlane(xi, 32)), r3 = __builtin_bit_cast(float, __builtin_amdgcn_readlane(xi, 48));
;     return (r0 + r1) + (r2 + r3);
; }
; __device__ __forceinline__ void rw_post(Frame& F) {
;     ...
;                     for (int q = 0; q < 4; ++q) { f32x4 a = (f32x4){0.f, 0.f, 0.f, 0.f};
; #pragma unroll
;                         for (int i = 0; i < 16; ++i) a = __builtin_elementwise_fma(Sr[i], *(const LAS f32x4*)(cs + q * 64 + 4 * i), a);
;                         y[4 * hf + q] += (a[0] + a[1]) + (a[2] + a[3]); }
;                     asm volatile("s_waitcnt lgkmcnt(0)" ::: "memory"); }
;             }
; #pragma unroll
;             for (int q = 0; q < 8; ++q) { const int row = rb0 + t0 + q;
;                 const float mean = wsum(y[q]) * (1.f / 64.f); const float dv = y[q] - mean; const float var = wsum(dv * dv) * (1.f / 64.f);
;                 const float yn = dv * (1.f / sqrtf(var + 64e-5f)) * g_ + b_;
;                 OB[(size_t)row * DH + col] = (bf16)f2bf((yn + rk[q] * vv[q]) * bf2f(gg[q])); }
	ds_read_b32 v80, v154 offset:0
	ds_read_b32 v81, v154 offset:16384
	ds_read_u16 v83, v156 offset:0
	ds_read_b32 v85, v154 offset:2048
	ds_read_b32 v86, v154 offset:18432
	ds_read_u16 v88, v156 offset:1024
	ds_read_b32 v90, v154 offset:4096
	ds_read_b32 v91, v154 offset:20480
	ds_read_u16 v93, v156 offset:2048
	ds_read_b32 v95, v154 offset:6144
	ds_read_b32 v96, v154 offset:22528
	ds_read_u16 v98, v156 offset:3072
	ds_read_b32 v100, v154 offset:8192
	ds_read_b32 v101, v154 offset:24576
	ds_read_u16 v103, v156 offset:4096
	ds_read_b32 v105, v154 offset:10240
	ds_read_b32 v106, v154 offset:26624
	ds_read_u16 v108, v156 offset:5120
	ds_read_b32 v110, v154 offset:12288
	ds_read_b32 v111, v154 offset:28672
	ds_read_u16 v113, v156 offset:6144
	ds_read_b32 v115, v154 offset:14336
	ds_read_b32 v116, v154 offset:30720
	ds_read_u16 v118, v156 offset:7168
	s_waitcnt lgkmcnt(0)
	v_add_f32_e32 v80, v80, v56
	v_add_f32_e32 v85, v85, v57
	v_add_f32_e32 v90, v90, v58
	v_add_f32_e32 v95, v95, v59
	v_add_f32_dpp v168, v80, v80 quad_perm:[1,0,3,2] row_mask:0xf bank_mask:0xf bound_ctrl:1
	v_add_f32_dpp v174, v85, v85 quad_perm:[1,0,3,2] row_mask:0xf bank_mask:0xf bound_ctrl:1
	v_add_f32_dpp v241, v90, v90 quad_perm:[1,0,3,2] row_mask:0xf bank_mask:0xf bound_ctrl:1
	v_add_f32_dpp v247, v95, v95 quad_perm:[1,0,3,2] row_mask:0xf bank_mask:0xf bound_ctrl:1
	v_add_f32_dpp v168, v168, v168 quad_perm:[2,3,0,1] row_mask:0xf bank_mask:0xf bound_ctrl:1
	v_add_f32_dpp v174, v174, v174 quad_perm:[2,3,0,1] row_mask:0xf bank_mask:0xf bound_ctrl:1
	v_add_f32_dpp v241, v241, v241 quad_perm:[2,3,0,1] row_mask:0xf bank_mask:0xf bound_ctrl:1
	v_add_f32_dpp v247, v247, v247 quad_perm:[2,3,0,1] row_mask:0xf bank_mask:0xf bound_ctrl:1
	v_add_f32_dpp v168, v168, v168 row_half_mirror row_mask:0xf bank_mask:0xf bound_ctrl:1
	v_add_f32_dpp v174, v174, v174 row_half_mirror row_mask:0xf bank_mask:0xf bound_ctrl:1
	v_add_f32_dpp v241, v241, v241 row_half_mirror row_mask:0xf bank_mask:0xf bound_ctrl:1
	v_add_f32_dpp v247, v247, v247 row_half_mirror row_mask:0xf bank_mask:0xf bound_ctrl:1
	v_add_f32_dpp v168, v168, v168 row_mirror row_mask:0xf bank_mask:0xf bound_ctrl:1
	v_add_f32_dpp v174, v174, v174 row_mirror row_mask:0xf bank_mask:0xf bound_ctrl:1
	v_add_f32_dpp v241, v241, v241 row_mirror row_mask:0xf bank_mask:0xf bound_ctrl:1
	v_add_f32_dpp v247, v247, v247 row_mirror row_mask:0xf bank_mask:0xf bound_ctrl:1
	v_readlane_b32 s36, v168, 16
	v_readlane_b32 s40, v174, 16
	v_readlane_b32 s44, v241, 16
	v_readlane_b32 s48, v247, 16
	v_readlane_b32 s37, v168, 48
	v_readlane_b32 s41, v174, 48
	v_readlane_b32 s45, v241, 48
	v_readlane_b32 s49, v247, 48
	v_readlane_b32 s38, v168, 0
	v_readlane_b32 s42, v174, 0
	v_readlane_b32 s46, v241, 0
	v_readlane_b32 s50, v247, 0
	v_readlane_b32 s39, v168, 32
	v_readlane_b32 s43, v174, 32
	v_readlane_b32 s47, v241, 32
	v_readlane_b32 s51, v247, 32
	v_mov_b32_e32 v168, s36
	v_mov_b32_e32 v174, s40
	v_mov_b32_e32 v241, s44
	v_mov_b32_e32 v247, s48
	v_mov_b32_e32 v169, s37
	v_mov_b32_e32 v175, s41
	v_mov_b32_e32 v242, s45
	v_mov_b32_e32 v248, s49
	v_add_f32_e32 v168, s38, v168
	v_add_f32_e32 v174, s42, v174
	v_add_f32_e32 v241, s46, v241
	v_add_f32_e32 v247, s50, v247
	v_add_f32_e32 v169, s39, v169
	v_add_f32_e32 v175, s43, v175
	v_add_f32_e32 v242, s47, v242
	v_add_f32_e32 v248, s51, v248
	v_add_f32_e32 v168, v168, v169
	v_add_f32_e32 v174, v174, v175
	v_add_f32_e32 v241, v241, v242
	v_add_f32_e32 v247, v247, v248
	v_fmamk_f32 v80, v168, 0xbc800000, v80
	v_fmamk_f32 v85, v174, 0xbc800000, v85
	v_fmamk_f32 v90, v241, 0xbc800000, v90
	v_fmamk_f32 v95, v247, 0xbc800000, v95
	v_mul_f32_e32 v168, v80, v80
	v_mul_f32_e32 v174, v85, v85
	v_mul_f32_e32 v241, v90, v90
	v_mul_f32_e32 v247, v95, v95
	v_mov_b32_dpp v168, v168 quad_perm:[1,0,3,2] row_mask:0xf bank_mask:0xf bound_ctrl:1
	v_mov_b32_dpp v174, v174 quad_perm:[1,0,3,2] row_mask:0xf bank_mask:0xf bound_ctrl:1
	v_mov_b32_dpp v241, v241 quad_perm:[1,0,3,2] row_mask:0xf bank_mask:0xf bound_ctrl:1
	v_mov_b32_dpp v247, v247 quad_perm:[1,0,3,2] row_mask:0xf bank_mask:0xf bound_ctrl:1
	v_fmac_f32_e32 v168, v80, v80
	v_fmac_f32_e32 v174, v85, v85
	v_fmac_f32_e32 v241, v90, v90
	v_fmac_f32_e32 v247, v95, v95
	v_add_f32_dpp v168, v168, v168 quad_perm:[2,3,0,1] row_mask:0xf bank_mask:0xf bound_ctrl:1
	v_add_f32_dpp v174, v174, v174 quad_perm:[2,3,0,1] row_mask:0xf bank_mask:0xf bound_ctrl:1
	v_add_f32_dpp v241, v241, v241 quad_perm:[2,3,0,1] row_mask:0xf bank_mask:0xf bound_ctrl:1
	v_add_f32_dpp v247, v247, v247 quad_perm:[2,3,0,1] row_mask:0xf bank_mask:0xf bound_ctrl:1
	v_add_f32_dpp v168, v168, v168 row_half_mirror row_mask:0xf bank_mask:0xf bound_ctrl:1
	v_add_f32_dpp v174, v174, v174 row_half_mirror row_mask:0xf bank_mask:0xf bound_ctrl:1
	v_add_f32_dpp v241, v241, v241 row_half_mirror row_mask:0xf bank_mask:0xf bound_ctrl:1
	v_add_f32_dpp v247, v247, v247 row_half_mirror row_mask:0xf bank_mask:0xf bound_ctrl:1
	v_add_f32_dpp v168, v168, v168 row_mirror row_mask:0xf bank_mask:0xf bound_ctrl:1
	v_add_f32_dpp v174, v174, v174 row_mirror row_mask:0xf bank_mask:0xf bound_ctrl:1
	v_add_f32_dpp v241, v241, v241 row_mirror row_mask:0xf bank_mask:0xf bound_ctrl:1
	v_add_f32_dpp v247, v247, v247 row_mirror row_mask:0xf bank_mask:0xf bound_ctrl:1
	v_readlane_b32 s36, v168, 16
	v_readlane_b32 s40, v174, 16
	v_readlane_b32 s44, v241, 16
	v_readlane_b32 s48, v247, 16
	v_readlane_b32 s37, v168, 48
	v_readlane_b32 s41, v174, 48
	v_readlane_b32 s45, v241, 48
	v_readlane_b32 s49, v247, 48
	v_readlane_b32 s38, v168, 0
	v_readlane_b32 s42, v174, 0
	v_readlane_b32 s46, v241, 0
	v_readlane_b32 s50, v247, 0
	v_readlane_b32 s39, v168, 32
; __device__ __forceinline__ float bf2f(bf16 x) { return __uint_as_float(((unsigned)x) << 16); }
; __device__ __forceinline__ unsigned f2bf(float f) { return cvt_pk_bf16(f, 0.f) & 0xffffu; }
; __device__ __forceinline__ float dpp_xor1(float x) { return __builtin_bit_cast(float, __builtin_amdgcn_update_dpp(0, __builtin_bit_cast(int, x), 0xB1, 0xF, 0xF, true)); }
; __device__ __forceinline__ float dpp_xor2(float x) { return __builtin_bit_cast(float, __builtin_amdgcn_update_dpp(0, __builtin_bit_cast(int, x), 0x4E, 0xF, 0xF, true)); }
; __device__ __forceinline__ float dpp_hmir(float x) { return __builtin_bit_cast(float, __builtin_amdgcn_update_dpp(0, __builtin_bit_cast(int, x), 0x141, 0xF, 0xF, true)); }
; __device__ __forceinline__ float dpp_mir(float x)  { return __builtin_bit_cast(float, __builtin_amdgcn_update_dpp(0, __builtin_bit_cast(int, x), 0x140, 0xF, 0xF, true)); }
; __device__ __forceinline__ float red16(float x) { x += dpp_xor1(x); x += dpp_xor2(x); x += dpp_hmir(x); x += dpp_mir(x); return x; }
; __device__ __forceinline__ float wsum(float x) {
;     x = red16(x); const int xi = __builtin_bit_cast(int, x);
;     const float r0 = __builtin_bit_cast(float, __builtin_amdgcn_readlane(xi, 0)), r1 = __builtin_bit_cast(float, __builtin_amdgcn_readlane(xi, 16));
;     const float r2 = __builtin_bit_cast(float, __builtin_amdgcn_readlane(xi, 32)), r3 = __builtin_bit_cast(float, __builtin_amdgcn_readlane(xi, 48));
;     return (r0 + r1) + (r2 + r3);
; }
; __device__ __forceinline__ void rw_post(Frame& F) {
;     ...
;             for (int q = 0; q < 8; ++q) { const int row = rb0 + t0 + q;
;                 const float mean = wsum(y[q]) * (1.f / 64.f); const float dv = y[q] - mean; const float var = wsum(dv * dv) * (1.f / 64.f);
;                 const float yn = dv * (1.f / sqrtf(var + 64e-5f)) * g_ + b_;
;                 OB[(size_t)row * DH + col] = (bf16)f2bf((yn + rk[q] * vv[q]) * bf2f(gg[q])); }
	v_readlane_b32 s43, v174, 32
	v_readlane_b32 s47, v241, 32
	v_readlane_b32 s51, v247, 32
	v_mov_b32_e32 v168, s36
	v_mov_b32_e32 v174, s40
	v_mov_b32_e32 v241, s44
	v_mov_b32_e32 v247, s48
	v_mov_b32_e32 v169, s37
	v_mov_b32_e32 v175, s41
	v_mov_b32_e32 v242, s45
	v_mov_b32_e32 v248, s49
	v_add_f32_e32 v168, s38, v168
	v_add_f32_e32 v174, s42, v174
	v_add_f32_e32 v241, s46, v241
	v_add_f32_e32 v247, s50, v247
	v_add_f32_e32 v169, s39, v169
	v_add_f32_e32 v175, s43, v175
	v_add_f32_e32 v242, s47, v242
	v_add_f32_e32 v248, s51, v248
	v_add_f32_e32 v168, v168, v169
	v_add_f32_e32 v174, v174, v175
	v_add_f32_e32 v241, v241, v242
	v_add_f32_e32 v247, v247, v248
	v_fmamk_f32 v168, v168, 0x3c800000, v9
	v_fmamk_f32 v174, v174, 0x3c800000, v9
	v_fmamk_f32 v241, v241, 0x3c800000, v9
	v_fmamk_f32 v247, v247, 0x3c800000, v9
	v_readfirstlane_b32 s40, v174
	v_readfirstlane_b32 s44, v241
	v_readfirstlane_b32 s48, v247
	v_writelane_b32 v168, s40, 1
	v_writelane_b32 v168, s44, 2
	v_writelane_b32 v168, s48, 3
	v_mul_f32_e32 v169, 0x4f800000, v168
	v_cmp_gt_f32_e64 s[52:53], s68, v168
	v_mov_b32_e32 v170, v168
	s_nop 1
	v_cndmask_b32_e64 v168, v170, v169, s[52:53]
	v_sqrt_f32_e32 v169, v168
	s_nop 0
	v_add_u32_e32 v170, -1, v169
	v_fma_f32 v171, -v170, v169, v168
	v_cmp_ge_f32_e64 s[60:61], 0, v171
	v_add_u32_e32 v171, 1, v169
	s_nop 1
	v_cndmask_b32_e64 v170, v169, v170, s[60:61]
	v_fma_f32 v169, -v171, v169, v168
	v_cmp_lt_f32_e64 s[60:61], 0, v169
	s_nop 1
	v_cndmask_b32_e64 v169, v170, v171, s[60:61]
	v_mul_f32_e32 v170, 0x37800000, v169
	v_cndmask_b32_e64 v169, v169, v170, s[52:53]
	v_cmp_class_f32_e64 s[60:61], v168, v8
	s_nop 1
	v_cndmask_b32_e64 v168, v169, v168, s[60:61]
	v_div_scale_f32 v169, s[60:61], v168, v168, 1.0
	v_rcp_f32_e32 v170, v169
	s_nop 0
	v_fma_f32 v171, -v169, v170, 1.0
	v_fmac_f32_e32 v170, v171, v170
	v_div_scale_f32 v171, vcc, 1.0, v168, 1.0
	v_mul_f32_e32 v172, v171, v170
	v_fma_f32 v173, -v169, v172, v171
	v_fmac_f32_e32 v172, v173, v170
	v_fma_f32 v169, -v169, v172, v171
	v_div_fmas_f32 v169, v169, v170, v172
	v_div_fixup_f32 v168, v169, v168, 1.0
	s_nop 0
	v_readlane_b32 s37, v168, 0
	v_readlane_b32 s41, v168, 1
	v_readlane_b32 s45, v168, 2
	v_readlane_b32 s49, v168, 3
	v_mul_f32_e32 v80, s37, v80
	v_mul_f32_e32 v85, s41, v85
	v_mul_f32_e32 v90, s45, v90
	v_mul_f32_e32 v95, s49, v95
	v_lshlrev_b32_e32 v83, 16, v83
	v_lshlrev_b32_e32 v88, 16, v88
	v_lshlrev_b32_e32 v93, 16, v93
	v_lshlrev_b32_e32 v98, 16, v98
	v_fma_f32 v80, v6, v80, v7
	v_fma_f32 v85, v6, v85, v7
	v_fma_f32 v90, v6, v90, v7
	v_fma_f32 v95, v6, v95, v7
	v_fmac_f32_e32 v80, s69, v81
	v_fmac_f32_e32 v85, s70, v86
	v_fmac_f32_e32 v90, s71, v91
	v_fmac_f32_e32 v95, s72, v96
	v_mul_f32_e32 v80, v80, v83
	v_mul_f32_e32 v85, v85, v88
	v_mul_f32_e32 v90, v90, v93
	v_mul_f32_e32 v95, v95, v98
	v_cvt_pk_bf16_f32 v169, v80, v80
	v_cvt_pk_bf16_f32 v175, v85, v85
	v_cvt_pk_bf16_f32 v242, v90, v90
	v_cvt_pk_bf16_f32 v248, v95, v95
	global_store_short v2, v169, s[28:29]
	s_add_u32 s28, s28, 0x1000
	s_addc_u32 s29, s29, 0
	global_store_short v2, v175, s[28:29]
	s_add_u32 s28, s28, 0x1000
	s_addc_u32 s29, s29, 0
	global_store_short v2, v242, s[28:29]
	s_add_u32 s28, s28, 0x1000
	s_addc_u32 s29, s29, 0
	global_store_short v2, v248, s[28:29]
	s_add_u32 s28, s28, 0x1000
	s_addc_u32 s29, s29, 0
	v_add_f32_e32 v100, v100, v72
	v_add_f32_e32 v105, v105, v73
	v_add_f32_e32 v110, v110, v74
	v_add_f32_e32 v115, v115, v75
	v_add_f32_dpp v168, v100, v100 quad_perm:[1,0,3,2] row_mask:0xf bank_mask:0xf bound_ctrl:1
	v_add_f32_dpp v174, v105, v105 quad_perm:[1,0,3,2] row_mask:0xf bank_mask:0xf bound_ctrl:1
	v_add_f32_dpp v241, v110, v110 quad_perm:[1,0,3,2] row_mask:0xf bank_mask:0xf bound_ctrl:1
	v_add_f32_dpp v247, v115, v115 quad_perm:[1,0,3,2] row_mask:0xf bank_mask:0xf bound_ctrl:1
	v_add_f32_dpp v168, v168, v168 quad_perm:[2,3,0,1] row_mask:0xf bank_mask:0xf bound_ctrl:1
	v_add_f32_dpp v174, v174, v174 quad_perm:[2,3,0,1] row_mask:0xf bank_mask:0xf bound_ctrl:1
	v_add_f32_dpp v241, v241, v241 quad_perm:[2,3,0,1] row_mask:0xf bank_mask:0xf bound_ctrl:1
	v_add_f32_dpp v247, v247, v247 quad_perm:[2,3,0,1] row_mask:0xf bank_mask:0xf bound_ctrl:1
	v_add_f32_dpp v168, v168, v168 row_half_mirror row_mask:0xf bank_mask:0xf bound_ctrl:1
	v_add_f32_dpp v174, v174, v174 row_half_mirror row_mask:0xf bank_mask:0xf bound_ctrl:1
	v_add_f32_dpp v241, v241, v241 row_half_mirror row_mask:0xf bank_mask:0xf bound_ctrl:1
	v_add_f32_dpp v247, v247, v247 row_half_mirror row_mask:0xf bank_mask:0xf bound_ctrl:1
	v_add_f32_dpp v168, v168, v168 row_mirror row_mask:0xf bank_mask:0xf bound_ctrl:1
	v_add_f32_dpp v174, v174, v174 row_mirror row_mask:0xf bank_mask:0xf bound_ctrl:1
	v_add_f32_dpp v241, v241, v241 row_mirror row_mask:0xf bank_mask:0xf bound_ctrl:1
	v_add_f32_dpp v247, v247, v247 row_mirror row_mask:0xf bank_mask:0xf bound_ctrl:1
	v_readlane_b32 s36, v168, 16
	v_readlane_b32 s40, v174, 16
	v_readlane_b32 s44, v241, 16
	v_readlane_b32 s48, v247, 16
	v_readlane_b32 s37, v168, 48
	v_readlane_b32 s41, v174, 48
	v_readlane_b32 s45, v241, 48
	v_readlane_b32 s49, v247, 48
	v_readlane_b32 s38, v168, 0
	v_readlane_b32 s42, v174, 0
	v_readlane_b32 s46, v241, 0
	v_readlane_b32 s50, v247, 0
	v_readlane_b32 s39, v168, 32
	v_readlane_b32 s43, v174, 32
	v_readlane_b32 s47, v241, 32
	v_readlane_b32 s51, v247, 32
	v_mov_b32_e32 v168, s36
	v_mov_b32_e32 v174, s40
	v_mov_b32_e32 v241, s44
	v_mov_b32_e32 v247, s48
	v_mov_b32_e32 v169, s37
	v_mov_b32_e32 v175, s41
	v_mov_b32_e32 v242, s45
	v_mov_b32_e32 v248, s49
	v_add_f32_e32 v168, s38, v168
	v_add_f32_e32 v174, s42, v174
	v_add_f32_e32 v241, s46, v241
; __device__ __forceinline__ float bf2f(bf16 x) { return __uint_as_float(((unsigned)x) << 16); }
; __device__ __forceinline__ unsigned f2bf(float f) { return cvt_pk_bf16(f, 0.f) & 0xffffu; }
; __device__ __forceinline__ float dpp_xor1(float x) { return __builtin_bit_cast(float, __builtin_amdgcn_update_dpp(0, __builtin_bit_cast(int, x), 0xB1, 0xF, 0xF, true)); }
; __device__ __forceinline__ float dpp_xor2(float x) { return __builtin_bit_cast(float, __builtin_amdgcn_update_dpp(0, __builtin_bit_cast(int, x), 0x4E, 0xF, 0xF, true)); }
; __device__ __forceinline__ float dpp_hmir(float x) { return __builtin_bit_cast(float, __builtin_amdgcn_update_dpp(0, __builtin_bit_cast(int, x), 0x141, 0xF, 0xF, true)); }
; __device__ __forceinline__ float dpp_mir(float x)  { return __builtin_bit_cast(float, __builtin_amdgcn_update_dpp(0, __builtin_bit_cast(int, x), 0x140, 0xF, 0xF, true)); }
; __device__ __forceinline__ float red16(float x) { x += dpp_xor1(x); x += dpp_xor2(x); x += dpp_hmir(x); x += dpp_mir(x); return x; }
; __device__ __forceinline__ float wsum(float x) {
;     x = red16(x); const int xi = __builtin_bit_cast(int, x);
;     const float r0 = __builtin_bit_cast(float, __builtin_amdgcn_readlane(xi, 0)), r1 = __builtin_bit_cast(float, __builtin_amdgcn_readlane(xi, 16));
;     const float r2 = __builtin_bit_cast(float, __builtin_amdgcn_readlane(xi, 32)), r3 = __builtin_bit_cast(float, __builtin_amdgcn_readlane(xi, 48));
;     return (r0 + r1) + (r2 + r3);
; }
; __device__ __forceinline__ void rw_post(Frame& F) {
;     ...
;             for (int q = 0; q < 8; ++q) { const int row = rb0 + t0 + q;
;                 const float mean = wsum(y[q]) * (1.f / 64.f); const float dv = y[q] - mean; const float var = wsum(dv * dv) * (1.f / 64.f);
;                 const float yn = dv * (1.f / sqrtf(var + 64e-5f)) * g_ + b_;
;                 OB[(size_t)row * DH + col] = (bf16)f2bf((yn + rk[q] * vv[q]) * bf2f(gg[q])); }
	v_add_f32_e32 v247, s50, v247
	v_add_f32_e32 v169, s39, v169
	v_add_f32_e32 v175, s43, v175
	v_add_f32_e32 v242, s47, v242
	v_add_f32_e32 v248, s51, v248
	v_add_f32_e32 v168, v168, v169
	v_add_f32_e32 v174, v174, v175
	v_add_f32_e32 v241, v241, v242
	v_add_f32_e32 v247, v247, v248
	v_fmamk_f32 v100, v168, 0xbc800000, v100
	v_fmamk_f32 v105, v174, 0xbc800000, v105
	v_fmamk_f32 v110, v241, 0xbc800000, v110
	v_fmamk_f32 v115, v247, 0xbc800000, v115
	v_mul_f32_e32 v168, v100, v100
	v_mul_f32_e32 v174, v105, v105
	v_mul_f32_e32 v241, v110, v110
	v_mul_f32_e32 v247, v115, v115
	v_mov_b32_dpp v168, v168 quad_perm:[1,0,3,2] row_mask:0xf bank_mask:0xf bound_ctrl:1
	v_mov_b32_dpp v174, v174 quad_perm:[1,0,3,2] row_mask:0xf bank_mask:0xf bound_ctrl:1
	v_mov_b32_dpp v241, v241 quad_perm:[1,0,3,2] row_mask:0xf bank_mask:0xf bound_ctrl:1
	v_mov_b32_dpp v247, v247 quad_perm:[1,0,3,2] row_mask:0xf bank_mask:0xf bound_ctrl:1
	v_fmac_f32_e32 v168, v100, v100
	v_fmac_f32_e32 v174, v105, v105
	v_fmac_f32_e32 v241, v110, v110
	v_fmac_f32_e32 v247, v115, v115
	v_add_f32_dpp v168, v168, v168 quad_perm:[2,3,0,1] row_mask:0xf bank_mask:0xf bound_ctrl:1
	v_add_f32_dpp v174, v174, v174 quad_perm:[2,3,0,1] row_mask:0xf bank_mask:0xf bound_ctrl:1
	v_add_f32_dpp v241, v241, v241 quad_perm:[2,3,0,1] row_mask:0xf bank_mask:0xf bound_ctrl:1
	v_add_f32_dpp v247, v247, v247 quad_perm:[2,3,0,1] row_mask:0xf bank_mask:0xf bound_ctrl:1
	v_add_f32_dpp v168, v168, v168 row_half_mirror row_mask:0xf bank_mask:0xf bound_ctrl:1
	v_add_f32_dpp v174, v174, v174 row_half_mirror row_mask:0xf bank_mask:0xf bound_ctrl:1
	v_add_f32_dpp v241, v241, v241 row_half_mirror row_mask:0xf bank_mask:0xf bound_ctrl:1
	v_add_f32_dpp v247, v247, v247 row_half_mirror row_mask:0xf bank_mask:0xf bound_ctrl:1
	v_add_f32_dpp v168, v168, v168 row_mirror row_mask:0xf bank_mask:0xf bound_ctrl:1
	v_add_f32_dpp v174, v174, v174 row_mirror row_mask:0xf bank_mask:0xf bound_ctrl:1
	v_add_f32_dpp v241, v241, v241 row_mirror row_mask:0xf bank_mask:0xf bound_ctrl:1
	v_add_f32_dpp v247, v247, v247 row_mirror row_mask:0xf bank_mask:0xf bound_ctrl:1
	v_readlane_b32 s36, v168, 16
	v_readlane_b32 s40, v174, 16
	v_readlane_b32 s44, v241, 16
	v_readlane_b32 s48, v247, 16
	v_readlane_b32 s37, v168, 48
	v_readlane_b32 s41, v174, 48
	v_readlane_b32 s45, v241, 48
	v_readlane_b32 s49, v247, 48
	v_readlane_b32 s38, v168, 0
	v_readlane_b32 s42, v174, 0
	v_readlane_b32 s46, v241, 0
	v_readlane_b32 s50, v247, 0
	v_readlane_b32 s39, v168, 32
	v_readlane_b32 s43, v174, 32
	v_readlane_b32 s47, v241, 32
	v_readlane_b32 s51, v247, 32
	v_mov_b32_e32 v168, s36
	v_mov_b32_e32 v174, s40
	v_mov_b32_e32 v241, s44
	v_mov_b32_e32 v247, s48
	v_mov_b32_e32 v169, s37
	v_mov_b32_e32 v175, s41
	v_mov_b32_e32 v242, s45
	v_mov_b32_e32 v248, s49
	v_add_f32_e32 v168, s38, v168
	v_add_f32_e32 v174, s42, v174
	v_add_f32_e32 v241, s46, v241
	v_add_f32_e32 v247, s50, v247
	v_add_f32_e32 v169, s39, v169
	v_add_f32_e32 v175, s43, v175
	v_add_f32_e32 v242, s47, v242
	v_add_f32_e32 v248, s51, v248
	v_add_f32_e32 v168, v168, v169
	v_add_f32_e32 v174, v174, v175
	v_add_f32_e32 v241, v241, v242
	v_add_f32_e32 v247, v247, v248
	v_fmamk_f32 v168, v168, 0x3c800000, v9
	v_fmamk_f32 v174, v174, 0x3c800000, v9
	v_fmamk_f32 v241, v241, 0x3c800000, v9
	v_fmamk_f32 v247, v247, 0x3c800000, v9
	v_readfirstlane_b32 s40, v174
	v_readfirstlane_b32 s44, v241
	v_readfirstlane_b32 s48, v247
	v_writelane_b32 v168, s40, 1
	v_writelane_b32 v168, s44, 2
	v_writelane_b32 v168, s48, 3
	v_mul_f32_e32 v169, 0x4f800000, v168
	v_cmp_gt_f32_e64 s[52:53], s68, v168
	v_mov_b32_e32 v170, v168
	s_nop 1
	v_cndmask_b32_e64 v168, v170, v169, s[52:53]
	v_sqrt_f32_e32 v169, v168
	s_nop 0
	v_add_u32_e32 v170, -1, v169
	v_fma_f32 v171, -v170, v169, v168
	v_cmp_ge_f32_e64 s[60:61], 0, v171
	v_add_u32_e32 v171, 1, v169
	s_nop 1
	v_cndmask_b32_e64 v170, v169, v170, s[60:61]
	v_fma_f32 v169, -v171, v169, v168
	v_cmp_lt_f32_e64 s[60:61], 0, v169
	s_nop 1
	v_cndmask_b32_e64 v169, v170, v171, s[60:61]
	v_mul_f32_e32 v170, 0x37800000, v169
	v_cndmask_b32_e64 v169, v169, v170, s[52:53]
	v_cmp_class_f32_e64 s[60:61], v168, v8
	s_nop 1
	v_cndmask_b32_e64 v168, v169, v168, s[60:61]
	v_div_scale_f32 v169, s[60:61], v168, v168, 1.0
	v_rcp_f32_e32 v170, v169
	s_nop 0
	v_fma_f32 v171, -v169, v170, 1.0
	v_fmac_f32_e32 v170, v171, v170
	v_div_scale_f32 v171, vcc, 1.0, v168, 1.0
	v_mul_f32_e32 v172, v171, v170
	v_fma_f32 v173, -v169, v172, v171
	v_fmac_f32_e32 v172, v173, v170
	v_fma_f32 v169, -v169, v172, v171
	v_div_fmas_f32 v169, v169, v170, v172
	v_div_fixup_f32 v168, v169, v168, 1.0
	s_nop 0
	v_readlane_b32 s37, v168, 0
	v_readlane_b32 s41, v168, 1
	v_readlane_b32 s45, v168, 2
	v_readlane_b32 s49, v168, 3
	v_mul_f32_e32 v100, s37, v100
	v_mul_f32_e32 v105, s41, v105
	v_mul_f32_e32 v110, s45, v110
	v_mul_f32_e32 v115, s49, v115
	v_lshlrev_b32_e32 v103, 16, v103
	v_lshlrev_b32_e32 v108, 16, v108
	v_lshlrev_b32_e32 v113, 16, v113
	v_lshlrev_b32_e32 v118, 16, v118
	v_fma_f32 v100, v6, v100, v7
	v_fma_f32 v105, v6, v105, v7
	v_fma_f32 v110, v6, v110, v7
	v_fma_f32 v115, v6, v115, v7
	v_fmac_f32_e32 v100, s73, v101
	v_fmac_f32_e32 v105, s26, v106
	v_fmac_f32_e32 v110, s27, v111
	v_fmac_f32_e32 v115, s32, v116
	v_mul_f32_e32 v100, v100, v103
	v_mul_f32_e32 v105, v105, v108
	v_mul_f32_e32 v110, v110, v113
	v_mul_f32_e32 v115, v115, v118
	v_cvt_pk_bf16_f32 v169, v100, v100
	v_cvt_pk_bf16_f32 v175, v105, v105
	v_cvt_pk_bf16_f32 v242, v110, v110
	v_cvt_pk_bf16_f32 v248, v115, v115
	global_store_short v2, v169, s[28:29]
	s_add_u32 s28, s28, 0x1000
	s_addc_u32 s29, s29, 0
	global_store_short v2, v175, s[28:29]
	s_add_u32 s28, s28, 0x1000
	s_addc_u32 s29, s29, 0
	global_store_short v2, v242, s[28:29]
	s_add_u32 s28, s28, 0x1000
	s_addc_u32 s29, s29, 0
	global_store_short v2, v248, s[28:29]
	s_add_u32 s28, s28, 0x1000
	s_addc_u32 s29, s29, 0
	s_waitcnt vmcnt(8)
	ds_write_b128 v13, v[120:123] offset:0
	ds_write_b128 v13, v[124:127] offset:1024
	ds_write_b128 v13, v[128:131] offset:16384
	ds_write_b128 v13, v[132:135] offset:17408
	ds_write_b128 v15, v[136:139]
	v_readlane_b32 s69, v159, 0
	v_readlane_b32 s70, v159, 1
	v_readlane_b32 s71, v159, 2
	v_readlane_b32 s72, v159, 3
	v_readlane_b32 s73, v159, 4
	v_readlane_b32 s26, v159, 5
	v_readlane_b32 s27, v159, 6
	v_readlane_b32 s32, v159, 7
	s_waitcnt lgkmcnt(0)
	s_barrier
; #define LAS __attribute__((address_space(3)))
; __device__ __forceinline__ float bf2f(bf16 x) { return __uint_as_float(((unsigned)x) << 16); }
; __device__ __forceinline__ unsigned f2bf(float f) { return cvt_pk_bf16(f, 0.f) & 0xffffu; }
; __device__ __forceinline__ float dpp_xor1(float x) { return __builtin_bit_cast(float, __builtin_amdgcn_update_dpp(0, __builtin_bit_cast(int, x), 0xB1, 0xF, 0xF, true)); }
; __device__ __forceinline__ float dpp_xor2(float x) { return __builtin_bit_cast(float, __builtin_amdgcn_update_dpp(0, __builtin_bit_cast(int, x), 0x4E, 0xF, 0xF, true)); }
; __device__ __forceinline__ float dpp_hmir(float x) { return __builtin_bit_cast(float, __builtin_amdgcn_update_dpp(0, __builtin_bit_cast(int, x), 0x141, 0xF, 0xF, true)); }
; __device__ __forceinline__ float red16(float x) { x += dpp_xor1(x); x += dpp_xor2(x); x += dpp_hmir(x); x += dpp_mir(x); return x; }
; __device__ __forceinline__ float wsum(float x) {
;     x = red16(x); const int xi = __builtin_bit_cast(int, x);
;     const float r0 = __builtin_bit_cast(float, __builtin_amdgcn_readlane(xi, 0)), r1 = __builtin_bit_cast(float, __builtin_amdgcn_readlane(xi, 16));
;     const float r2 = __builtin_bit_cast(float, __builtin_amdgcn_readlane(xi, 32)), r3 = __builtin_bit_cast(float, __builtin_amdgcn_readlane(xi, 48));
;     return (r0 + r1) + (r2 + r3);
; }
; __device__ __forceinline__ void rw_post(Frame& F) {
;     ...
;                     for (int q = 0; q < 4; ++q) { f32x4 a = (f32x4){0.f, 0.f, 0.f, 0.f};
; #pragma unroll
;                         for (int i = 0; i < 16; ++i) a = __builtin_elementwise_fma(Sr[i], *(const LAS f32x4*)(cs + q * 64 + 4 * i), a);
;                         y[4 * hf + q] += (a[0] + a[1]) + (a[2] + a[3]); }
;                     asm volatile("s_waitcnt lgkmcnt(0)" ::: "memory"); }
;             }
; #pragma unroll
;             for (int q = 0; q < 8; ++q) { const int row = rb0 + t0 + q;
;                 const float mean = wsum(y[q]) * (1.f / 64.f); const float dv = y[q] - mean; const float var = wsum(dv * dv) * (1.f / 64.f);
;                 const float yn = dv * (1.f / sqrtf(var + 64e-5f)) * g_ + b_;
;                 OB[(size_t)row * DH + col] = (bf16)f2bf((yn + rk[q] * vv[q]) * bf2f(gg[q])); }
	ds_read_b32 v80, v155 offset:0
	ds_read_b32 v81, v155 offset:16384
	ds_read_u16 v83, v157 offset:0
	ds_read_b32 v85, v155 offset:2048
	ds_read_b32 v86, v155 offset:18432
	ds_read_u16 v88, v157 offset:1024
	ds_read_b32 v90, v155 offset:4096
	ds_read_b32 v91, v155 offset:20480
	ds_read_u16 v93, v157 offset:2048
	ds_read_b32 v95, v155 offset:6144
	ds_read_b32 v96, v155 offset:22528
	ds_read_u16 v98, v157 offset:3072
	ds_read_b32 v100, v155 offset:8192
	ds_read_b32 v101, v155 offset:24576
	ds_read_u16 v103, v157 offset:4096
	ds_read_b32 v105, v155 offset:10240
	ds_read_b32 v106, v155 offset:26624
	ds_read_u16 v108, v157 offset:5120
	ds_read_b32 v110, v155 offset:12288
	ds_read_b32 v111, v155 offset:28672
	ds_read_u16 v113, v157 offset:6144
	ds_read_b32 v115, v155 offset:14336
	ds_read_b32 v116, v155 offset:30720
	ds_read_u16 v118, v157 offset:7168
	s_waitcnt lgkmcnt(0)
	v_add_f32_e32 v80, v80, v60
	v_add_f32_e32 v85, v85, v61
	v_add_f32_e32 v90, v90, v62
	v_add_f32_e32 v95, v95, v63
	v_add_f32_dpp v168, v80, v80 quad_perm:[1,0,3,2] row_mask:0xf bank_mask:0xf bound_ctrl:1
	v_add_f32_dpp v174, v85, v85 quad_perm:[1,0,3,2] row_mask:0xf bank_mask:0xf bound_ctrl:1
	v_add_f32_dpp v241, v90, v90 quad_perm:[1,0,3,2] row_mask:0xf bank_mask:0xf bound_ctrl:1
	v_add_f32_dpp v247, v95, v95 quad_perm:[1,0,3,2] row_mask:0xf bank_mask:0xf bound_ctrl:1
	v_add_f32_dpp v168, v168, v168 quad_perm:[2,3,0,1] row_mask:0xf bank_mask:0xf bound_ctrl:1
	v_add_f32_dpp v174, v174, v174 quad_perm:[2,3,0,1] row_mask:0xf bank_mask:0xf bound_ctrl:1
	v_add_f32_dpp v241, v241, v241 quad_perm:[2,3,0,1] row_mask:0xf bank_mask:0xf bound_ctrl:1
	v_add_f32_dpp v247, v247, v247 quad_perm:[2,3,0,1] row_mask:0xf bank_mask:0xf bound_ctrl:1
	v_add_f32_dpp v168, v168, v168 row_half_mirror row_mask:0xf bank_mask:0xf bound_ctrl:1
	v_add_f32_dpp v174, v174, v174 row_half_mirror row_mask:0xf bank_mask:0xf bound_ctrl:1
	v_add_f32_dpp v241, v241, v241 row_half_mirror row_mask:0xf bank_mask:0xf bound_ctrl:1
	v_add_f32_dpp v247, v247, v247 row_half_mirror row_mask:0xf bank_mask:0xf bound_ctrl:1
	v_add_f32_dpp v168, v168, v168 row_mirror row_mask:0xf bank_mask:0xf bound_ctrl:1
	v_add_f32_dpp v174, v174, v174 row_mirror row_mask:0xf bank_mask:0xf bound_ctrl:1
	v_add_f32_dpp v241, v241, v241 row_mirror row_mask:0xf bank_mask:0xf bound_ctrl:1
	v_add_f32_dpp v247, v247, v247 row_mirror row_mask:0xf bank_mask:0xf bound_ctrl:1
	v_readlane_b32 s36, v168, 16
	v_readlane_b32 s40, v174, 16
	v_readlane_b32 s44, v241, 16
	v_readlane_b32 s48, v247, 16
	v_readlane_b32 s37, v168, 48
	v_readlane_b32 s41, v174, 48
	v_readlane_b32 s45, v241, 48
	v_readlane_b32 s49, v247, 48
	v_readlane_b32 s38, v168, 0
	v_readlane_b32 s42, v174, 0
	v_readlane_b32 s46, v241, 0
	v_readlane_b32 s50, v247, 0
	v_readlane_b32 s39, v168, 32
	v_readlane_b32 s43, v174, 32
	v_readlane_b32 s47, v241, 32
	v_readlane_b32 s51, v247, 32
	v_mov_b32_e32 v168, s36
	v_mov_b32_e32 v174, s40
	v_mov_b32_e32 v241, s44
	v_mov_b32_e32 v247, s48
	v_mov_b32_e32 v169, s37
	v_mov_b32_e32 v175, s41
	v_mov_b32_e32 v242, s45
	v_mov_b32_e32 v248, s49
	v_add_f32_e32 v168, s38, v168
	v_add_f32_e32 v174, s42, v174
	v_add_f32_e32 v241, s46, v241
	v_add_f32_e32 v247, s50, v247
	v_add_f32_e32 v169, s39, v169
	v_add_f32_e32 v175, s43, v175
	v_add_f32_e32 v242, s47, v242
	v_add_f32_e32 v248, s51, v248
	v_add_f32_e32 v168, v168, v169
	v_add_f32_e32 v174, v174, v175
	v_add_f32_e32 v241, v241, v242
	v_add_f32_e32 v247, v247, v248
	v_fmamk_f32 v80, v168, 0xbc800000, v80
	v_fmamk_f32 v85, v174, 0xbc800000, v85
	v_fmamk_f32 v90, v241, 0xbc800000, v90
	v_fmamk_f32 v95, v247, 0xbc800000, v95
	v_mul_f32_e32 v168, v80, v80
	v_mul_f32_e32 v174, v85, v85
	v_mul_f32_e32 v241, v90, v90
	v_mul_f32_e32 v247, v95, v95
	v_mov_b32_dpp v168, v168 quad_perm:[1,0,3,2] row_mask:0xf bank_mask:0xf bound_ctrl:1
	v_mov_b32_dpp v174, v174 quad_perm:[1,0,3,2] row_mask:0xf bank_mask:0xf bound_ctrl:1
	v_mov_b32_dpp v241, v241 quad_perm:[1,0,3,2] row_mask:0xf bank_mask:0xf bound_ctrl:1
	v_mov_b32_dpp v247, v247 quad_perm:[1,0,3,2] row_mask:0xf bank_mask:0xf bound_ctrl:1
	v_fmac_f32_e32 v168, v80, v80
	v_fmac_f32_e32 v174, v85, v85
	v_fmac_f32_e32 v241, v90, v90
	v_fmac_f32_e32 v247, v95, v95
	v_add_f32_dpp v168, v168, v168 quad_perm:[2,3,0,1] row_mask:0xf bank_mask:0xf bound_ctrl:1
	v_add_f32_dpp v174, v174, v174 quad_perm:[2,3,0,1] row_mask:0xf bank_mask:0xf bound_ctrl:1
	v_add_f32_dpp v241, v241, v241 quad_perm:[2,3,0,1] row_mask:0xf bank_mask:0xf bound_ctrl:1
	v_add_f32_dpp v247, v247, v247 quad_perm:[2,3,0,1] row_mask:0xf bank_mask:0xf bound_ctrl:1
	v_add_f32_dpp v168, v168, v168 row_half_mirror row_mask:0xf bank_mask:0xf bound_ctrl:1
	v_add_f32_dpp v174, v174, v174 row_half_mirror row_mask:0xf bank_mask:0xf bound_ctrl:1
	v_add_f32_dpp v241, v241, v241 row_half_mirror row_mask:0xf bank_mask:0xf bound_ctrl:1
	v_add_f32_dpp v247, v247, v247 row_half_mirror row_mask:0xf bank_mask:0xf bound_ctrl:1
	v_add_f32_dpp v168, v168, v168 row_mirror row_mask:0xf bank_mask:0xf bound_ctrl:1
	v_add_f32_dpp v174, v174, v174 row_mirror row_mask:0xf bank_mask:0xf bound_ctrl:1
	v_add_f32_dpp v241, v241, v241 row_mirror row_mask:0xf bank_mask:0xf bound_ctrl:1
	v_add_f32_dpp v247, v247, v247 row_mirror row_mask:0xf bank_mask:0xf bound_ctrl:1
	v_readlane_b32 s36, v168, 16
	v_readlane_b32 s40, v174, 16
	v_readlane_b32 s44, v241, 16
	v_readlane_b32 s48, v247, 16
	v_readlane_b32 s37, v168, 48
	v_readlane_b32 s41, v174, 48
	v_readlane_b32 s45, v241, 48
	v_readlane_b32 s49, v247, 48
	v_readlane_b32 s38, v168, 0
	v_readlane_b32 s42, v174, 0
	v_readlane_b32 s46, v241, 0
	v_readlane_b32 s50, v247, 0
	v_readlane_b32 s39, v168, 32
; __device__ __forceinline__ float bf2f(bf16 x) { return __uint_as_float(((unsigned)x) << 16); }
; __device__ __forceinline__ unsigned f2bf(float f) { return cvt_pk_bf16(f, 0.f) & 0xffffu; }
; __device__ __forceinline__ float dpp_xor1(float x) { return __builtin_bit_cast(float, __builtin_amdgcn_update_dpp(0, __builtin_bit_cast(int, x), 0xB1, 0xF, 0xF, true)); }
; __device__ __forceinline__ float dpp_xor2(float x) { return __builtin_bit_cast(float, __builtin_amdgcn_update_dpp(0, __builtin_bit_cast(int, x), 0x4E, 0xF, 0xF, true)); }
; __device__ __forceinline__ float dpp_hmir(float x) { return __builtin_bit_cast(float, __builtin_amdgcn_update_dpp(0, __builtin_bit_cast(int, x), 0x141, 0xF, 0xF, true)); }
; __device__ __forceinline__ float dpp_mir(float x)  { return __builtin_bit_cast(float, __builtin_amdgcn_update_dpp(0, __builtin_bit_cast(int, x), 0x140, 0xF, 0xF, true)); }
; __device__ __forceinline__ float red16(float x) { x += dpp_xor1(x); x += dpp_xor2(x); x += dpp_hmir(x); x += dpp_mir(x); return x; }
; __device__ __forceinline__ float wsum(float x) {
;     x = red16(x); const int xi = __builtin_bit_cast(int, x);
;     const float r0 = __builtin_bit_cast(float, __builtin_amdgcn_readlane(xi, 0)), r1 = __builtin_bit_cast(float, __builtin_amdgcn_readlane(xi, 16));
;     const float r2 = __builtin_bit_cast(float, __builtin_amdgcn_readlane(xi, 32)), r3 = __builtin_bit_cast(float, __builtin_amdgcn_readlane(xi, 48));
;     return (r0 + r1) + (r2 + r3);
; }
; __device__ __forceinline__ void rw_post(Frame& F) {
;     ...
;             for (int q = 0; q < 8; ++q) { const int row = rb0 + t0 + q;
;                 const float mean = wsum(y[q]) * (1.f / 64.f); const float dv = y[q] - mean; const float var = wsum(dv * dv) * (1.f / 64.f);
;                 const float yn = dv * (1.f / sqrtf(var + 64e-5f)) * g_ + b_;
;                 OB[(size_t)row * DH + col] = (bf16)f2bf((yn + rk[q] * vv[q]) * bf2f(gg[q])); }
	v_readlane_b32 s43, v174, 32
	v_readlane_b32 s47, v241, 32
	v_readlane_b32 s51, v247, 32
	v_mov_b32_e32 v168, s36
	v_mov_b32_e32 v174, s40
	v_mov_b32_e32 v241, s44
	v_mov_b32_e32 v247, s48
	v_mov_b32_e32 v169, s37
	v_mov_b32_e32 v175, s41
	v_mov_b32_e32 v242, s45
	v_mov_b32_e32 v248, s49
	v_add_f32_e32 v168, s38, v168
	v_add_f32_e32 v174, s42, v174
	v_add_f32_e32 v241, s46, v241
	v_add_f32_e32 v247, s50, v247
	v_add_f32_e32 v169, s39, v169
	v_add_f32_e32 v175, s43, v175
	v_add_f32_e32 v242, s47, v242
	v_add_f32_e32 v248, s51, v248
	v_add_f32_e32 v168, v168, v169
	v_add_f32_e32 v174, v174, v175
	v_add_f32_e32 v241, v241, v242
	v_add_f32_e32 v247, v247, v248
	v_fmamk_f32 v168, v168, 0x3c800000, v9
	v_fmamk_f32 v174, v174, 0x3c800000, v9
	v_fmamk_f32 v241, v241, 0x3c800000, v9
	v_fmamk_f32 v247, v247, 0x3c800000, v9
	v_readfirstlane_b32 s40, v174
	v_readfirstlane_b32 s44, v241
	v_readfirstlane_b32 s48, v247
	v_writelane_b32 v168, s40, 1
	v_writelane_b32 v168, s44, 2
	v_writelane_b32 v168, s48, 3
	v_mul_f32_e32 v169, 0x4f800000, v168
	v_cmp_gt_f32_e64 s[52:53], s68, v168
	v_mov_b32_e32 v170, v168
	s_nop 1
	v_cndmask_b32_e64 v168, v170, v169, s[52:53]
	v_sqrt_f32_e32 v169, v168
	s_nop 0
	v_add_u32_e32 v170, -1, v169
	v_fma_f32 v171, -v170, v169, v168
	v_cmp_ge_f32_e64 s[60:61], 0, v171
	v_add_u32_e32 v171, 1, v169
	s_nop 1
	v_cndmask_b32_e64 v170, v169, v170, s[60:61]
	v_fma_f32 v169, -v171, v169, v168
	v_cmp_lt_f32_e64 s[60:61], 0, v169
	s_nop 1
	v_cndmask_b32_e64 v169, v170, v171, s[60:61]
	v_mul_f32_e32 v170, 0x37800000, v169
	v_cndmask_b32_e64 v169, v169, v170, s[52:53]
	v_cmp_class_f32_e64 s[60:61], v168, v8
	s_nop 1
	v_cndmask_b32_e64 v168, v169, v168, s[60:61]
	v_div_scale_f32 v169, s[60:61], v168, v168, 1.0
	v_rcp_f32_e32 v170, v169
	s_nop 0
	v_fma_f32 v171, -v169, v170, 1.0
	v_fmac_f32_e32 v170, v171, v170
	v_div_scale_f32 v171, vcc, 1.0, v168, 1.0
	v_mul_f32_e32 v172, v171, v170
	v_fma_f32 v173, -v169, v172, v171
	v_fmac_f32_e32 v172, v173, v170
	v_fma_f32 v169, -v169, v172, v171
	v_div_fmas_f32 v169, v169, v170, v172
	v_div_fixup_f32 v168, v169, v168, 1.0
	s_nop 0
	v_readlane_b32 s37, v168, 0
	v_readlane_b32 s41, v168, 1
	v_readlane_b32 s45, v168, 2
	v_readlane_b32 s49, v168, 3
	v_mul_f32_e32 v80, s37, v80
	v_mul_f32_e32 v85, s41, v85
	v_mul_f32_e32 v90, s45, v90
	v_mul_f32_e32 v95, s49, v95
	v_lshlrev_b32_e32 v83, 16, v83
	v_lshlrev_b32_e32 v88, 16, v88
	v_lshlrev_b32_e32 v93, 16, v93
	v_lshlrev_b32_e32 v98, 16, v98
	v_fma_f32 v80, v6, v80, v7
	v_fma_f32 v85, v6, v85, v7
	v_fma_f32 v90, v6, v90, v7
	v_fma_f32 v95, v6, v95, v7
	v_fmac_f32_e32 v80, s69, v81
	v_fmac_f32_e32 v85, s70, v86
	v_fmac_f32_e32 v90, s71, v91
	v_fmac_f32_e32 v95, s72, v96
	v_mul_f32_e32 v80, v80, v83
	v_mul_f32_e32 v85, v85, v88
	v_mul_f32_e32 v90, v90, v93
	v_mul_f32_e32 v95, v95, v98
	v_cvt_pk_bf16_f32 v169, v80, v80
	v_cvt_pk_bf16_f32 v175, v85, v85
	v_cvt_pk_bf16_f32 v242, v90, v90
	v_cvt_pk_bf16_f32 v248, v95, v95
	global_store_short v2, v169, s[28:29]
	s_add_u32 s28, s28, 0x1000
	s_addc_u32 s29, s29, 0
	global_store_short v2, v175, s[28:29]
	s_add_u32 s28, s28, 0x1000
	s_addc_u32 s29, s29, 0
	global_store_short v2, v242, s[28:29]
	s_add_u32 s28, s28, 0x1000
	s_addc_u32 s29, s29, 0
	global_store_short v2, v248, s[28:29]
	s_add_u32 s28, s28, 0x1000
	s_addc_u32 s29, s29, 0
	v_add_f32_e32 v100, v100, v76
	v_add_f32_e32 v105, v105, v77
	v_add_f32_e32 v110, v110, v78
	v_add_f32_e32 v115, v115, v79
	v_add_f32_dpp v168, v100, v100 quad_perm:[1,0,3,2] row_mask:0xf bank_mask:0xf bound_ctrl:1
	v_add_f32_dpp v174, v105, v105 quad_perm:[1,0,3,2] row_mask:0xf bank_mask:0xf bound_ctrl:1
	v_add_f32_dpp v241, v110, v110 quad_perm:[1,0,3,2] row_mask:0xf bank_mask:0xf bound_ctrl:1
	v_add_f32_dpp v247, v115, v115 quad_perm:[1,0,3,2] row_mask:0xf bank_mask:0xf bound_ctrl:1
	v_add_f32_dpp v168, v168, v168 quad_perm:[2,3,0,1] row_mask:0xf bank_mask:0xf bound_ctrl:1
	v_add_f32_dpp v174, v174, v174 quad_perm:[2,3,0,1] row_mask:0xf bank_mask:0xf bound_ctrl:1
	v_add_f32_dpp v241, v241, v241 quad_perm:[2,3,0,1] row_mask:0xf bank_mask:0xf bound_ctrl:1
	v_add_f32_dpp v247, v247, v247 quad_perm:[2,3,0,1] row_mask:0xf bank_mask:0xf bound_ctrl:1
	v_add_f32_dpp v168, v168, v168 row_half_mirror row_mask:0xf bank_mask:0xf bound_ctrl:1
	v_add_f32_dpp v174, v174, v174 row_half_mirror row_mask:0xf bank_mask:0xf bound_ctrl:1
	v_add_f32_dpp v241, v241, v241 row_half_mirror row_mask:0xf bank_mask:0xf bound_ctrl:1
	v_add_f32_dpp v247, v247, v247 row_half_mirror row_mask:0xf bank_mask:0xf bound_ctrl:1
	v_add_f32_dpp v168, v168, v168 row_mirror row_mask:0xf bank_mask:0xf bound_ctrl:1
	v_add_f32_dpp v174, v174, v174 row_mirror row_mask:0xf bank_mask:0xf bound_ctrl:1
	v_add_f32_dpp v241, v241, v241 row_mirror row_mask:0xf bank_mask:0xf bound_ctrl:1
	v_add_f32_dpp v247, v247, v247 row_mirror row_mask:0xf bank_mask:0xf bound_ctrl:1
	v_readlane_b32 s36, v168, 16
	v_readlane_b32 s40, v174, 16
	v_readlane_b32 s44, v241, 16
	v_readlane_b32 s48, v247, 16
	v_readlane_b32 s37, v168, 48
	v_readlane_b32 s41, v174, 48
	v_readlane_b32 s45, v241, 48
	v_readlane_b32 s49, v247, 48
	v_readlane_b32 s38, v168, 0
	v_readlane_b32 s42, v174, 0
	v_readlane_b32 s46, v241, 0
	v_readlane_b32 s50, v247, 0
	v_readlane_b32 s39, v168, 32
	v_readlane_b32 s43, v174, 32
	v_readlane_b32 s47, v241, 32
	v_readlane_b32 s51, v247, 32
	v_mov_b32_e32 v168, s36
	v_mov_b32_e32 v174, s40
	v_mov_b32_e32 v241, s44
	v_mov_b32_e32 v247, s48
	v_mov_b32_e32 v169, s37
	v_mov_b32_e32 v175, s41
	v_mov_b32_e32 v242, s45
	v_mov_b32_e32 v248, s49
	v_add_f32_e32 v168, s38, v168
	v_add_f32_e32 v174, s42, v174
	v_add_f32_e32 v241, s46, v241
; __device__ __forceinline__ float bf2f(bf16 x) { return __uint_as_float(((unsigned)x) << 16); }
; __device__ __forceinline__ unsigned f2bf(float f) { return cvt_pk_bf16(f, 0.f) & 0xffffu; }
; __device__ __forceinline__ float dpp_xor1(float x) { return __builtin_bit_cast(float, __builtin_amdgcn_update_dpp(0, __builtin_bit_cast(int, x), 0xB1, 0xF, 0xF, true)); }
; __device__ __forceinline__ float dpp_xor2(float x) { return __builtin_bit_cast(float, __builtin_amdgcn_update_dpp(0, __builtin_bit_cast(int, x), 0x4E, 0xF, 0xF, true)); }
; __device__ __forceinline__ float dpp_hmir(float x) { return __builtin_bit_cast(float, __builtin_amdgcn_update_dpp(0, __builtin_bit_cast(int, x), 0x141, 0xF, 0xF, true)); }
; __device__ __forceinline__ float dpp_mir(float x)  { return __builtin_bit_cast(float, __builtin_amdgcn_update_dpp(0, __builtin_bit_cast(int, x), 0x140, 0xF, 0xF, true)); }
; __device__ __forceinline__ float red16(float x) { x += dpp_xor1(x); x += dpp_xor2(x); x += dpp_hmir(x); x += dpp_mir(x); return x; }
; __device__ __forceinline__ float wsum(float x) {
;     x = red16(x); const int xi = __builtin_bit_cast(int, x);
;     const float r0 = __builtin_bit_cast(float, __builtin_amdgcn_readlane(xi, 0)), r1 = __builtin_bit_cast(float, __builtin_amdgcn_readlane(xi, 16));
;     const float r2 = __builtin_bit_cast(float, __builtin_amdgcn_readlane(xi, 32)), r3 = __builtin_bit_cast(float, __builtin_amdgcn_readlane(xi, 48));
;     return (r0 + r1) + (r2 + r3);
; }
; __device__ __forceinline__ void rw_post(Frame& F) {
;     ...
;             for (int q = 0; q < 8; ++q) { const int row = rb0 + t0 + q;
;                 const float mean = wsum(y[q]) * (1.f / 64.f); const float dv = y[q] - mean; const float var = wsum(dv * dv) * (1.f / 64.f);
;                 const float yn = dv * (1.f / sqrtf(var + 64e-5f)) * g_ + b_;
;                 OB[(size_t)row * DH + col] = (bf16)f2bf((yn + rk[q] * vv[q]) * bf2f(gg[q])); }
	v_add_f32_e32 v247, s50, v247
	v_add_f32_e32 v169, s39, v169
	v_add_f32_e32 v175, s43, v175
	v_add_f32_e32 v242, s47, v242
	v_add_f32_e32 v248, s51, v248
	v_add_f32_e32 v168, v168, v169
	v_add_f32_e32 v174, v174, v175
	v_add_f32_e32 v241, v241, v242
	v_add_f32_e32 v247, v247, v248
	v_fmamk_f32 v100, v168, 0xbc800000, v100
	v_fmamk_f32 v105, v174, 0xbc800000, v105
	v_fmamk_f32 v110, v241, 0xbc800000, v110
	v_fmamk_f32 v115, v247, 0xbc800000, v115
	v_mul_f32_e32 v168, v100, v100
	v_mul_f32_e32 v174, v105, v105
	v_mul_f32_e32 v241, v110, v110
	v_mul_f32_e32 v247, v115, v115
	v_mov_b32_dpp v168, v168 quad_perm:[1,0,3,2] row_mask:0xf bank_mask:0xf bound_ctrl:1
	v_mov_b32_dpp v174, v174 quad_perm:[1,0,3,2] row_mask:0xf bank_mask:0xf bound_ctrl:1
	v_mov_b32_dpp v241, v241 quad_perm:[1,0,3,2] row_mask:0xf bank_mask:0xf bound_ctrl:1
	v_mov_b32_dpp v247, v247 quad_perm:[1,0,3,2] row_mask:0xf bank_mask:0xf bound_ctrl:1
	v_fmac_f32_e32 v168, v100, v100
	v_fmac_f32_e32 v174, v105, v105
	v_fmac_f32_e32 v241, v110, v110
	v_fmac_f32_e32 v247, v115, v115
	v_add_f32_dpp v168, v168, v168 quad_perm:[2,3,0,1] row_mask:0xf bank_mask:0xf bound_ctrl:1
	v_add_f32_dpp v174, v174, v174 quad_perm:[2,3,0,1] row_mask:0xf bank_mask:0xf bound_ctrl:1
	v_add_f32_dpp v241, v241, v241 quad_perm:[2,3,0,1] row_mask:0xf bank_mask:0xf bound_ctrl:1
	v_add_f32_dpp v247, v247, v247 quad_perm:[2,3,0,1] row_mask:0xf bank_mask:0xf bound_ctrl:1
	v_add_f32_dpp v168, v168, v168 row_half_mirror row_mask:0xf bank_mask:0xf bound_ctrl:1
	v_add_f32_dpp v174, v174, v174 row_half_mirror row_mask:0xf bank_mask:0xf bound_ctrl:1
	v_add_f32_dpp v241, v241, v241 row_half_mirror row_mask:0xf bank_mask:0xf bound_ctrl:1
	v_add_f32_dpp v247, v247, v247 row_half_mirror row_mask:0xf bank_mask:0xf bound_ctrl:1
	v_add_f32_dpp v168, v168, v168 row_mirror row_mask:0xf bank_mask:0xf bound_ctrl:1
	v_add_f32_dpp v174, v174, v174 row_mirror row_mask:0xf bank_mask:0xf bound_ctrl:1
	v_add_f32_dpp v241, v241, v241 row_mirror row_mask:0xf bank_mask:0xf bound_ctrl:1
	v_add_f32_dpp v247, v247, v247 row_mirror row_mask:0xf bank_mask:0xf bound_ctrl:1
	v_readlane_b32 s36, v168, 16
	v_readlane_b32 s40, v174, 16
	v_readlane_b32 s44, v241, 16
	v_readlane_b32 s48, v247, 16
	v_readlane_b32 s37, v168, 48
	v_readlane_b32 s41, v174, 48
	v_readlane_b32 s45, v241, 48
	v_readlane_b32 s49, v247, 48
	v_readlane_b32 s38, v168, 0
	v_readlane_b32 s42, v174, 0
	v_readlane_b32 s46, v241, 0
	v_readlane_b32 s50, v247, 0
	v_readlane_b32 s39, v168, 32
	v_readlane_b32 s43, v174, 32
	v_readlane_b32 s47, v241, 32
	v_readlane_b32 s51, v247, 32
	v_mov_b32_e32 v168, s36
	v_mov_b32_e32 v174, s40
	v_mov_b32_e32 v241, s44
	v_mov_b32_e32 v247, s48
	v_mov_b32_e32 v169, s37
	v_mov_b32_e32 v175, s41
	v_mov_b32_e32 v242, s45
	v_mov_b32_e32 v248, s49
	v_add_f32_e32 v168, s38, v168
	v_add_f32_e32 v174, s42, v174
	v_add_f32_e32 v241, s46, v241
	v_add_f32_e32 v247, s50, v247
	v_add_f32_e32 v169, s39, v169
	v_add_f32_e32 v175, s43, v175
	v_add_f32_e32 v242, s47, v242
	v_add_f32_e32 v248, s51, v248
	v_add_f32_e32 v168, v168, v169
	v_add_f32_e32 v174, v174, v175
	v_add_f32_e32 v241, v241, v242
	v_add_f32_e32 v247, v247, v248
	v_fmamk_f32 v168, v168, 0x3c800000, v9
	v_fmamk_f32 v174, v174, 0x3c800000, v9
	v_fmamk_f32 v241, v241, 0x3c800000, v9
	v_fmamk_f32 v247, v247, 0x3c800000, v9
	v_readfirstlane_b32 s40, v174
	v_readfirstlane_b32 s44, v241
	v_readfirstlane_b32 s48, v247
	v_writelane_b32 v168, s40, 1
	v_writelane_b32 v168, s44, 2
	v_writelane_b32 v168, s48, 3
	v_mul_f32_e32 v169, 0x4f800000, v168
	v_cmp_gt_f32_e64 s[52:53], s68, v168
	v_mov_b32_e32 v170, v168
	s_nop 1
	v_cndmask_b32_e64 v168, v170, v169, s[52:53]
	v_sqrt_f32_e32 v169, v168
	s_nop 0
	v_add_u32_e32 v170, -1, v169
	v_fma_f32 v171, -v170, v169, v168
	v_cmp_ge_f32_e64 s[60:61], 0, v171
	v_add_u32_e32 v171, 1, v169
	s_nop 1
	v_cndmask_b32_e64 v170, v169, v170, s[60:61]
	v_fma_f32 v169, -v171, v169, v168
	v_cmp_lt_f32_e64 s[60:61], 0, v169
	s_nop 1
	v_cndmask_b32_e64 v169, v170, v171, s[60:61]
	v_mul_f32_e32 v170, 0x37800000, v169
	v_cndmask_b32_e64 v169, v169, v170, s[52:53]
	v_cmp_class_f32_e64 s[60:61], v168, v8
	s_nop 1
	v_cndmask_b32_e64 v168, v169, v168, s[60:61]
	v_div_scale_f32 v169, s[60:61], v168, v168, 1.0
	v_rcp_f32_e32 v170, v169
	s_nop 0
	v_fma_f32 v171, -v169, v170, 1.0
	v_fmac_f32_e32 v170, v171, v170
	v_div_scale_f32 v171, vcc, 1.0, v168, 1.0
	v_mul_f32_e32 v172, v171, v170
	v_fma_f32 v173, -v169, v172, v171
	v_fmac_f32_e32 v172, v173, v170
	v_fma_f32 v169, -v169, v172, v171
	v_div_fmas_f32 v169, v169, v170, v172
	v_div_fixup_f32 v168, v169, v168, 1.0
	s_nop 0
	v_readlane_b32 s37, v168, 0
	v_readlane_b32 s41, v168, 1
	v_readlane_b32 s45, v168, 2
	v_readlane_b32 s49, v168, 3
	v_mul_f32_e32 v100, s37, v100
	v_mul_f32_e32 v105, s41, v105
	v_mul_f32_e32 v110, s45, v110
	v_mul_f32_e32 v115, s49, v115
	v_lshlrev_b32_e32 v103, 16, v103
	v_lshlrev_b32_e32 v108, 16, v108
	v_lshlrev_b32_e32 v113, 16, v113
	v_lshlrev_b32_e32 v118, 16, v118
	v_fma_f32 v100, v6, v100, v7
	v_fma_f32 v105, v6, v105, v7
	v_fma_f32 v110, v6, v110, v7
	v_fma_f32 v115, v6, v115, v7
	v_fmac_f32_e32 v100, s73, v101
	v_fmac_f32_e32 v105, s26, v106
	v_fmac_f32_e32 v110, s27, v111
	v_fmac_f32_e32 v115, s32, v116
	v_mul_f32_e32 v100, v100, v103
	v_mul_f32_e32 v105, v105, v108
	v_mul_f32_e32 v110, v110, v113
	v_mul_f32_e32 v115, v115, v118
	v_cvt_pk_bf16_f32 v169, v100, v100
	v_cvt_pk_bf16_f32 v175, v105, v105
	v_cvt_pk_bf16_f32 v242, v110, v110
	v_cvt_pk_bf16_f32 v248, v115, v115
	global_store_short v2, v169, s[28:29]
	s_add_u32 s28, s28, 0x1000
	s_addc_u32 s29, s29, 0
	global_store_short v2, v175, s[28:29]
	s_add_u32 s28, s28, 0x1000
	s_addc_u32 s29, s29, 0
	global_store_short v2, v242, s[28:29]
	s_add_u32 s28, s28, 0x1000
	s_addc_u32 s29, s29, 0
	global_store_short v2, v248, s[28:29]
	s_add_u32 s28, s28, 0x1000
	s_addc_u32 s29, s29, 0
	s_add_i32 s20, s20, s92
	s_cmpk_lt_i32 s20, 0x2040
	s_cbranch_scc1 .Lpo_unit
